# lock-free LDS completion counters (ds_add / poll) let waves 4-7 run the RWKV epilogue and stream GDN outputs behind the MFMA waves without s_barrier in the recurrence loops
# speedup vs baseline: 1.3225x; 1.0133x over previous
.LBB0_533:
	s_cmpk_gt_i32 s71, 0x7f
	s_mov_b64 s[0:1], -1
	s_cbranch_scc0 .LBB0_560
	s_add_i32 s3, s71, 0xffffff80
	v_mov_b32_e32 v1, v180
	s_lshl_b32 s0, s3, 8
	s_bfe_u32 s6, s71, 0x20001
	s_and_b32 s16, s0, 0x7800
	s_waitcnt vmcnt(2)
	v_ashrrev_i32_e32 v18, 3, v1
	s_lshl_b32 s72, s6, 2
	s_lshl_b32 s0, s6, 8
	v_add_u32_e32 v21, s16, v18
	v_mov_b64_e32 v[18:19], s[22:23]
	s_mov_b32 s1, s73
	s_add_u32 s8, s22, s0
	v_mad_i64_i32 v[18:19], s[4:5], v21, s83, v[18:19]
	s_addc_u32 s9, s23, 0
	v_lshl_add_u64 v[18:19], v[18:19], 0, s[0:1]
	s_lshl_b32 s0, s3, 6
	s_and_b32 s3, s0, 64
	v_mov_b32_e32 v2, s72
	v_lshlrev_b32_e32 v20, 4, v1
	s_lshl_b32 s0, s3, 1
	global_load_dword v24, v2, s[64:65]
	global_load_dword v124, v2, s[66:67]
	v_and_b32_e32 v25, 63, v1
	v_and_b32_e32 v2, 0xf0, v20
	v_lshl_add_u64 v[18:19], v[18:19], 0, s[0:1]
	v_and_b32_e32 v20, 0x70, v20
	v_mov_b32_e32 v21, v94
	v_mov_b32_e32 v3, v94
	v_add_u32_e32 v12, 0x200, v1
	v_lshl_add_u64 v[18:19], v[18:19], 0, v[20:21]
	v_or_b32_e32 v20, s16, v25
	v_lshl_add_u64 v[10:11], s[8:9], 0, v[2:3]
	v_ashrrev_i32_e32 v2, 4, v1
	v_ashrrev_i32_e32 v12, 4, v12
	v_mul_u32_u24_e32 v20, 0x88, v20
	v_add_u32_e32 v2, s16, v2
	v_add_u32_e32 v12, s16, v12
	v_lshlrev_b32_e32 v20, 2, v20
	v_mad_i64_i32 v[6:7], s[4:5], v2, s83, v[10:11]
	v_mad_i64_i32 v[14:15], s[4:5], v12, s83, v[10:11]
	v_lshl_add_u64 v[20:21], s[26:27], 0, v[20:21]
	global_load_dwordx4 v[2:5], v[6:7], off
	s_nop 0
	global_load_dwordx4 v[6:9], v[6:7], off offset:1024
	s_nop 0
	global_load_dwordx4 v[10:13], v[14:15], off
	s_nop 0
	global_load_dwordx4 v[14:17], v[14:15], off offset:1024
	v_lshl_add_u64 v[22:23], v[20:21], 0, s[72:73]
	global_load_dwordx4 v[18:21], v[18:19], off offset:2048
	s_nop 0
	global_load_dword v126, v[22:23], off offset:512
	global_load_dword v127, v[22:23], off offset:528
	s_lshl_b32 s1, s6, 9
	v_lshlrev_b32_e32 v22, 3, v1
	s_add_u32 s1, s75, s1
	v_and_b32_e32 v22, 0xfffffe00, v22
	v_lshlrev_b32_e32 v23, 2, v25
	s_addc_u32 s4, s79, 0
	s_lshl_b32 s3, s3, 2
	v_add3_u32 v22, s82, v22, v23
	s_add_u32 s10, s1, s3
	ds_write2st64_b32 v22, v94, v94 offset1:1
	s_addc_u32 s11, s4, 0
	s_add_u32 s12, s8, s0
	s_addc_u32 s13, s9, 0
	v_mov_b32_e32 v95, v94
	s_add_u32 s14, s26, s72
	s_mov_b32 s17, 0
	v_mov_b64_e32 v[96:97], v[94:95]
	v_mov_b64_e32 v[98:99], v[94:95]
	v_mov_b64_e32 v[100:101], v[94:95]
	s_addc_u32 s15, s27, 0
	v_mov_b64_e32 v[102:103], v[94:95]
	v_mov_b64_e32 v[104:105], v[94:95]
	v_mov_b64_e32 v[106:107], v[94:95]
	v_mov_b64_e32 v[108:109], v[94:95]
	v_mov_b64_e32 v[110:111], v[94:95]
	s_waitcnt vmcnt(8)
	v_mul_f32_e32 v22, 0x3fb8aa3b, v24
	v_exp_f32_e32 v125, v22
	v_mov_b32_e32 v184, 0
	v_mov_b32_e32 v185, 0
	v_mov_b32_e32 v186, 0
	v_mov_b32_e32 v187, 0
	v_mov_b32_e32 v188, 0
	v_mov_b32_e32 v189, 0
	v_mov_b32_e32 v190, 0
	v_mov_b32_e32 v191, 0
	v_mov_b32_e32 v192, 0
	v_mov_b32_e32 v193, 0
	v_mov_b32_e32 v194, 0
	v_mov_b32_e32 v195, 0
	v_mov_b32_e32 v196, 0
	v_mov_b32_e32 v197, 0
	v_mov_b32_e32 v198, 0
	v_mov_b32_e32 v199, 0
	v_mov_b32_e32 v200, 0
	v_mov_b32_e32 v201, 0
	v_mov_b32_e32 v202, 0
	v_mov_b32_e32 v203, 0
	v_mov_b32_e32 v204, 0
	v_mov_b32_e32 v205, 0
	v_mov_b32_e32 v206, 0
	v_mov_b32_e32 v207, 0
	v_mov_b32_e32 v208, 0
	v_mov_b32_e32 v209, 0
	v_mov_b32_e32 v210, 0
	v_mov_b32_e32 v211, 0
	v_mov_b32_e32 v212, 0
	v_mov_b32_e32 v213, 0
	v_mov_b32_e32 v214, 0
	v_mov_b32_e32 v215, 0
	v_mov_b32_e32 v238, 1.0
	v_mov_b32_e32 v182, 0x15800
	ds_write_b32 v182, v184 offset:0
	ds_write_b32 v182, v184 offset:4
	ds_write_b32 v182, v184 offset:8
	ds_write_b32 v182, v184 offset:12
	ds_write_b32 v182, v184 offset:16
	ds_write_b32 v182, v184 offset:20
	ds_write_b32 v182, v184 offset:24
	ds_write_b32 v182, v184 offset:28
	s_branch .LBB0_537

.LBB0_549:
	v_readfirstlane_b32 s0, v180
	s_nop 1
	s_cmpk_ge_u32 s0, 0x100
	s_cbranch_scc1 .Lgdn_out
	v_and_b32_e32 v166, 15, v180
	v_bfe_u32 v167, v180, 4, 2
	v_lshrrev_b32_e32 v168, 6, v180
	v_and_b32_e32 v177, 3, v166
	v_bfe_u32 v178, v166, 3, 1
	v_lshl_add_u32 v177, v178, 2, v177
	v_mul_u32_u24_e32 v177, 0x210, v177
	v_bfe_u32 v87, v166, 2, 1
	v_lshlrev_b32_e32 v87, 8, v87
	v_and_b32_e32 v178, 3, v166
	v_lshl_add_u32 v87, v178, 5, v87
	v_lshl_add_u32 v87, v167, 2, v87
	v_add_u32_e32 v87, 0x14880, v87
	v_and_b32_e32 v178, 4, v166
	v_sub_u32_e32 v178, 4, v178
	v_mul_u32_u24_e32 v178, 0x2100, v178
	v_lshl_add_u32 v169, v167, 4, v177
	v_add_u32_e32 v169, v169, v178
	v_mul_u32_u24_e32 v177, 0x210, v167
	v_lshl_add_u32 v170, v166, 2, v177
	v_add_u32_e32 v170, 0x8400, v170
	v_add_u32_e32 v237, 0x840, v170
	v_add_u32_e32 v95, 0x1080, v170
	v_lshlrev_b32_e32 v177, 6, v168
	v_lshl_add_u32 v177, v166, 2, v177
	v_add_u32_e32 v171, 0x10800, v177
	v_lshl_add_u32 v172, v167, 8, v177
	v_add_u32_e32 v172, 0x1d800, v172
	v_mov_b32_e32 v173, 0x14800
	v_lshlrev_b32_e32 v174, 5, v167
	v_add_u32_e32 v174, 0x14900, v174
	v_mov_b32_e32 v175, 0x21900
	v_lshl_add_u32 v176, v167, 2, v175
	v_cmp_eq_u32_e32 vcc, 1, v167
	v_cmp_eq_u32_e64 s[4:5], 2, v167
	v_cmp_eq_u32_e64 s[6:7], 3, v167
	s_mov_b32 s40, 1
	s_mov_b32 s41, 0
	v_mov_b32_e32 v91, 0x15800
	v_mov_b32_e32 v92, 1
	ds_read_b128 v[22:25], v169 offset:0
	ds_read_b128 v[26:29], v169 offset:64
	ds_read_b128 v[30:33], v169 offset:128
	ds_read_b128 v[34:37], v169 offset:192
	ds_read_b128 v[38:41], v169 offset:256
	ds_read_b128 v[42:45], v169 offset:320
	ds_read_b128 v[46:49], v169 offset:384
	ds_read_b128 v[50:53], v169 offset:448
	ds_read2_b32 v[54:55], v170 offset0:0 offset1:16
	ds_read2_b32 v[56:57], v170 offset0:32 offset1:48
	ds_read2_b32 v[58:59], v170 offset0:64 offset1:80
	ds_read2_b32 v[60:61], v170 offset0:96 offset1:112
	ds_read2st64_b32 v[70:71], v171 offset0:0 offset1:1
	ds_read2st64_b32 v[72:73], v171 offset0:2 offset1:3
	ds_read_b128 v[132:135], v175 offset:0
	ds_read_b128 v[136:139], v175 offset:256
	ds_read_b32 v151, v176 offset:256
	ds_read_b32 v152, v176 offset:512
	ds_read_b32 v150, v173 offset:32
	ds_read_b64 v[148:149], v173 offset:64
	ds_read_b128 v[140:143], v173 offset:96
	ds_read_b128 v[144:147], v174 offset:0
	s_mov_b32 s1, 0
	s_waitcnt lgkmcnt(0)
	s_waitcnt lgkmcnt(1)
	v_mfma_f32_16x16x4_f32 v[96:99], v22, v184, 0
	v_mfma_f32_16x16x4_f32 v[100:103], v23, v185, 0
	v_mfma_f32_16x16x4_f32 v[96:99], v24, v186, v[96:99]
	v_mfma_f32_16x16x4_f32 v[100:103], v25, v187, v[100:103]
	v_mul_f32_e32 v129, v132, v70
	v_mul_f32_e32 v130, v133, v71
	v_mul_f32_e32 v131, v134, v72
	v_mul_f32_e32 v153, v135, v73
	v_mfma_f32_16x16x4_f32 v[96:99], v26, v188, v[96:99]
	v_mfma_f32_16x16x4_f32 v[100:103], v27, v189, v[100:103]
	v_mfma_f32_16x16x4_f32 v[96:99], v28, v190, v[96:99]
	v_mfma_f32_16x16x4_f32 v[100:103], v29, v191, v[100:103]
	v_mul_f32_e64 v114, -v132, v136
	v_mul_f32_e64 v115, -v133, v137
	v_mul_f32_e64 v116, -v134, v138
	v_mul_f32_e64 v117, -v135, v139
	v_mfma_f32_16x16x4_f32 v[96:99], v30, v192, v[96:99]
	v_mfma_f32_16x16x4_f32 v[100:103], v31, v193, v[100:103]
	v_mfma_f32_16x16x4_f32 v[96:99], v32, v194, v[96:99]
	v_mfma_f32_16x16x4_f32 v[100:103], v33, v195, v[100:103]
	v_mul_f32_e32 v240, v238, v139
	v_rcp_f32_e32 v89, v240
	v_readfirstlane_b32 s0, v240
	ds_read_b32 v86, v87 offset:0
	v_mfma_f32_16x16x4_f32 v[96:99], v34, v196, v[96:99]
	v_mfma_f32_16x16x4_f32 v[100:103], v35, v197, v[100:103]
	v_mfma_f32_16x16x4_f32 v[96:99], v36, v198, v[96:99]
	v_mfma_f32_16x16x4_f32 v[100:103], v37, v199, v[100:103]
	ds_read2_b32 v[62:63], v237 offset0:0 offset1:16
	ds_read2_b32 v[64:65], v237 offset0:32 offset1:48
	ds_read2_b32 v[66:67], v237 offset0:64 offset1:80
	ds_read2_b32 v[68:69], v237 offset0:96 offset1:112
	v_mfma_f32_16x16x4_f32 v[96:99], v38, v200, v[96:99]
	v_mfma_f32_16x16x4_f32 v[100:103], v39, v201, v[100:103]
	v_mfma_f32_16x16x4_f32 v[96:99], v40, v202, v[96:99]
	v_mfma_f32_16x16x4_f32 v[100:103], v41, v203, v[100:103]
	ds_read2st64_b32 v[74:75], v171 offset0:4 offset1:5
	ds_read2st64_b32 v[76:77], v171 offset0:6 offset1:7
	ds_read_b128 v[216:219], v175 offset:16
	ds_read_b128 v[220:223], v175 offset:272
	v_mfma_f32_16x16x4_f32 v[96:99], v42, v204, v[96:99]
	v_mfma_f32_16x16x4_f32 v[100:103], v43, v205, v[100:103]
	v_mfma_f32_16x16x4_f32 v[96:99], v44, v206, v[96:99]
	v_mfma_f32_16x16x4_f32 v[100:103], v45, v207, v[100:103]
	ds_read_b32 v235, v176 offset:272
	ds_read_b32 v236, v176 offset:528
	ds_read_b32 v234, v173 offset:176
	ds_read_b64 v[232:233], v173 offset:208
	v_mfma_f32_16x16x4_f32 v[96:99], v46, v208, v[96:99]
	v_mfma_f32_16x16x4_f32 v[100:103], v47, v209, v[100:103]
	v_mfma_f32_16x16x4_f32 v[96:99], v48, v210, v[96:99]
	v_mfma_f32_16x16x4_f32 v[100:103], v49, v211, v[100:103]
	ds_read_b128 v[224:227], v173 offset:240
	ds_read_b128 v[228:231], v174 offset:144
	v_mfma_f32_16x16x4_f32 v[96:99], v50, v212, v[96:99]
	v_mfma_f32_16x16x4_f32 v[100:103], v51, v213, v[100:103]
	v_mfma_f32_16x16x4_f32 v[96:99], v52, v214, v[96:99]
	v_mfma_f32_16x16x4_f32 v[100:103], v53, v215, v[100:103]
	s_nop 7
	s_nop 1
	v_pk_mul_f32 v[100:101], v[100:101], v[238:239] op_sel_hi:[1,0]
	v_pk_mul_f32 v[102:103], v[102:103], v[238:239] op_sel_hi:[1,0]
	v_pk_fma_f32 v[78:79], v[96:97], v[238:239], v[100:101] op_sel_hi:[1,0,1]
	v_pk_fma_f32 v[80:81], v[98:99], v[238:239], v[102:103] op_sel_hi:[1,0,1]
	v_pk_fma_f32 v[96:97], v[96:97], v[238:239], v[100:101] op_sel_hi:[1,0,1]
	v_pk_fma_f32 v[98:99], v[98:99], v[238:239], v[102:103] op_sel_hi:[1,0,1]
	s_nop 0
	v_permlane32_swap_b32_e32 v96, v78
	v_permlane32_swap_b32_e32 v97, v79
	v_permlane32_swap_b32_e32 v98, v80
	v_permlane32_swap_b32_e32 v99, v81
	v_mov_b32_e32 v82, v96
	v_mov_b32_e32 v83, v97
	v_mov_b32_e32 v84, v98
	v_mov_b32_e32 v85, v99
	s_nop 0
	v_permlane16_swap_b32_e32 v96, v82
	v_permlane16_swap_b32_e32 v97, v83
	v_permlane16_swap_b32_e32 v98, v84
	v_permlane16_swap_b32_e32 v99, v85
	v_fma_f32 v108, v114, v96, v129
	v_fma_f32 v109, v115, v97, v130
	v_fma_f32 v110, v116, v98, v131
	v_fma_f32 v111, v117, v99, v153
	v_fma_f32 v109, -v150, v108, v109
	v_fma_f32 v110, -v148, v108, v110
	v_fma_f32 v111, -v140, v108, v111
	v_fma_f32 v110, -v149, v109, v110
	v_fma_f32 v111, -v141, v109, v111
	v_fma_f32 v111, -v142, v110, v111
	v_cndmask_b32_e32 v182, v108, v109, vcc
	v_cndmask_b32_e64 v182, v182, v110, s[4:5]
	v_cndmask_b32_e64 v182, v182, v111, s[6:7]
	v_mul_f32_e32 v182, v152, v182
	s_cmp_lt_u32 s0, 0x2b800000
	s_cbranch_scc0 .Lgdn_nomat_0_0
	v_pk_mul_f32 v[184:185], v[184:185], v[240:241] op_sel_hi:[1,0]
	v_pk_mul_f32 v[186:187], v[186:187], v[240:241] op_sel_hi:[1,0]
	v_pk_mul_f32 v[188:189], v[188:189], v[240:241] op_sel_hi:[1,0]
	v_pk_mul_f32 v[190:191], v[190:191], v[240:241] op_sel_hi:[1,0]
	v_pk_mul_f32 v[192:193], v[192:193], v[240:241] op_sel_hi:[1,0]
	v_pk_mul_f32 v[194:195], v[194:195], v[240:241] op_sel_hi:[1,0]
	v_pk_mul_f32 v[196:197], v[196:197], v[240:241] op_sel_hi:[1,0]
	v_pk_mul_f32 v[198:199], v[198:199], v[240:241] op_sel_hi:[1,0]
	v_pk_mul_f32 v[200:201], v[200:201], v[240:241] op_sel_hi:[1,0]
	v_pk_mul_f32 v[202:203], v[202:203], v[240:241] op_sel_hi:[1,0]
	v_pk_mul_f32 v[204:205], v[204:205], v[240:241] op_sel_hi:[1,0]
	v_pk_mul_f32 v[206:207], v[206:207], v[240:241] op_sel_hi:[1,0]
	v_pk_mul_f32 v[208:209], v[208:209], v[240:241] op_sel_hi:[1,0]
	v_pk_mul_f32 v[210:211], v[210:211], v[240:241] op_sel_hi:[1,0]
	v_pk_mul_f32 v[212:213], v[212:213], v[240:241] op_sel_hi:[1,0]
	v_pk_mul_f32 v[214:215], v[214:215], v[240:241] op_sel_hi:[1,0]
	v_mov_b32_e32 v240, 1.0
	v_mov_b32_e32 v89, 1.0

.Lgdn_nomat_0_1:
	v_mov_b32_e32 v238, v240
	v_mul_f32_e32 v90, v182, v89
	s_nop 1
	v_mfma_f32_16x16x4_f32 v[184:187], v62, v90, v[184:187]
	v_mfma_f32_16x16x4_f32 v[188:191], v63, v90, v[188:191]
	v_mfma_f32_16x16x4_f32 v[192:195], v64, v90, v[192:195]
	v_mfma_f32_16x16x4_f32 v[196:199], v65, v90, v[196:199]
	v_mfma_f32_16x16x4_f32 v[200:203], v66, v90, v[200:203]
	v_mfma_f32_16x16x4_f32 v[204:207], v67, v90, v[204:207]
	v_mfma_f32_16x16x4_f32 v[208:211], v68, v90, v[208:211]
	v_mfma_f32_16x16x4_f32 v[212:215], v69, v90, v[212:215]
	v_cndmask_b32_e32 v183, v82, v83, vcc
	v_cndmask_b32_e64 v183, v183, v84, s[4:5]
	v_cndmask_b32_e64 v183, v183, v85, s[6:7]
	v_mul_f32_e32 v179, v235, v183
	v_fmac_f32_e32 v179, v228, v108
	v_fmac_f32_e32 v179, v229, v109
	v_fmac_f32_e32 v179, v230, v110
	v_fmac_f32_e32 v179, v231, v111
	ds_write_b32 v172, v179 offset:1024
	s_mov_b64 exec, s[40:41]
	ds_add_u32 v91, v92 offset:0
	s_mov_b64 exec, -1
	v_add_u32_e32 v170, 0x1080, v170
	v_add_u32_e32 v237, 0x1080, v237
	v_add_u32_e32 v95, 0x1080, v95
	s_waitcnt lgkmcnt(2)
	v_mfma_f32_16x16x4_f32 v[96:99], v22, v184, 0
	v_mfma_f32_16x16x4_f32 v[100:103], v23, v185, 0
	v_mfma_f32_16x16x4_f32 v[96:99], v24, v186, v[96:99]
	v_mfma_f32_16x16x4_f32 v[100:103], v25, v187, v[100:103]
	v_mul_f32_e32 v129, v132, v70
	v_mul_f32_e32 v130, v133, v71
	v_mul_f32_e32 v131, v134, v72
	v_mul_f32_e32 v153, v135, v73
	v_mfma_f32_16x16x4_f32 v[96:99], v26, v188, v[96:99]
	v_mfma_f32_16x16x4_f32 v[100:103], v27, v189, v[100:103]
	v_mfma_f32_16x16x4_f32 v[96:99], v28, v190, v[96:99]
	v_mfma_f32_16x16x4_f32 v[100:103], v29, v191, v[100:103]
	v_mul_f32_e64 v114, -v132, v136
	v_mul_f32_e64 v115, -v133, v137
	v_mul_f32_e64 v116, -v134, v138
	v_mul_f32_e64 v117, -v135, v139
	v_mfma_f32_16x16x4_f32 v[96:99], v30, v192, v[96:99]
	v_mfma_f32_16x16x4_f32 v[100:103], v31, v193, v[100:103]
	v_mfma_f32_16x16x4_f32 v[96:99], v32, v194, v[96:99]
	v_mfma_f32_16x16x4_f32 v[100:103], v33, v195, v[100:103]
	v_mul_f32_e32 v240, v238, v139
	v_rcp_f32_e32 v89, v240
	v_readfirstlane_b32 s0, v240
	ds_read_b32 v86, v87 offset:512
	v_mfma_f32_16x16x4_f32 v[96:99], v34, v196, v[96:99]
	v_mfma_f32_16x16x4_f32 v[100:103], v35, v197, v[100:103]
	v_mfma_f32_16x16x4_f32 v[96:99], v36, v198, v[96:99]
	v_mfma_f32_16x16x4_f32 v[100:103], v37, v199, v[100:103]
	ds_read2_b32 v[62:63], v237 offset0:0 offset1:16
	ds_read2_b32 v[64:65], v237 offset0:32 offset1:48
	ds_read2_b32 v[66:67], v237 offset0:64 offset1:80
	ds_read2_b32 v[68:69], v237 offset0:96 offset1:112
	v_mfma_f32_16x16x4_f32 v[96:99], v38, v200, v[96:99]
	v_mfma_f32_16x16x4_f32 v[100:103], v39, v201, v[100:103]
	v_mfma_f32_16x16x4_f32 v[96:99], v40, v202, v[96:99]
	v_mfma_f32_16x16x4_f32 v[100:103], v41, v203, v[100:103]
	ds_read2st64_b32 v[74:75], v171 offset0:12 offset1:13
	ds_read2st64_b32 v[76:77], v171 offset0:14 offset1:15
	ds_read_b128 v[216:219], v175 offset:48
	ds_read_b128 v[220:223], v175 offset:304
	v_mfma_f32_16x16x4_f32 v[96:99], v42, v204, v[96:99]
	v_mfma_f32_16x16x4_f32 v[100:103], v43, v205, v[100:103]
	v_mfma_f32_16x16x4_f32 v[96:99], v44, v206, v[96:99]
	v_mfma_f32_16x16x4_f32 v[100:103], v45, v207, v[100:103]
	ds_read_b32 v235, v176 offset:304
	ds_read_b32 v236, v176 offset:560
	ds_read_b32 v234, v173 offset:688
	ds_read_b64 v[232:233], v173 offset:720
	v_mfma_f32_16x16x4_f32 v[96:99], v46, v208, v[96:99]
	v_mfma_f32_16x16x4_f32 v[100:103], v47, v209, v[100:103]
	v_mfma_f32_16x16x4_f32 v[96:99], v48, v210, v[96:99]
	v_mfma_f32_16x16x4_f32 v[100:103], v49, v211, v[100:103]
	ds_read_b128 v[224:227], v173 offset:752
	ds_read_b128 v[228:231], v174 offset:656
	v_mfma_f32_16x16x4_f32 v[96:99], v50, v212, v[96:99]
	v_mfma_f32_16x16x4_f32 v[100:103], v51, v213, v[100:103]
	v_mfma_f32_16x16x4_f32 v[96:99], v52, v214, v[96:99]
	v_mfma_f32_16x16x4_f32 v[100:103], v53, v215, v[100:103]
	s_nop 7
	s_nop 1
	v_pk_mul_f32 v[100:101], v[100:101], v[238:239] op_sel_hi:[1,0]
	v_pk_mul_f32 v[102:103], v[102:103], v[238:239] op_sel_hi:[1,0]
	v_pk_fma_f32 v[78:79], v[96:97], v[238:239], v[100:101] op_sel_hi:[1,0,1]
	v_pk_fma_f32 v[80:81], v[98:99], v[238:239], v[102:103] op_sel_hi:[1,0,1]
	v_pk_fma_f32 v[96:97], v[96:97], v[238:239], v[100:101] op_sel_hi:[1,0,1]
	v_pk_fma_f32 v[98:99], v[98:99], v[238:239], v[102:103] op_sel_hi:[1,0,1]
	s_nop 0
	v_permlane32_swap_b32_e32 v96, v78
	v_permlane32_swap_b32_e32 v97, v79
	v_permlane32_swap_b32_e32 v98, v80
	v_permlane32_swap_b32_e32 v99, v81
	v_mov_b32_e32 v82, v96
	v_mov_b32_e32 v83, v97
	v_mov_b32_e32 v84, v98
	v_mov_b32_e32 v85, v99
	s_nop 0
	v_permlane16_swap_b32_e32 v96, v82
	v_permlane16_swap_b32_e32 v97, v83
	v_permlane16_swap_b32_e32 v98, v84
	v_permlane16_swap_b32_e32 v99, v85
	v_fma_f32 v108, v114, v96, v129
	v_fma_f32 v109, v115, v97, v130
	v_fma_f32 v110, v116, v98, v131
	v_fma_f32 v111, v117, v99, v153
	v_fma_f32 v109, -v150, v108, v109
	v_fma_f32 v110, -v148, v108, v110
	v_fma_f32 v111, -v140, v108, v111
	v_fma_f32 v110, -v149, v109, v110
	v_fma_f32 v111, -v141, v109, v111
	v_fma_f32 v111, -v142, v110, v111
	v_cndmask_b32_e32 v182, v108, v109, vcc
	v_cndmask_b32_e64 v182, v182, v110, s[4:5]
	v_cndmask_b32_e64 v182, v182, v111, s[6:7]
	v_mul_f32_e32 v182, v152, v182
	s_cmp_lt_u32 s0, 0x2b800000
	s_cbranch_scc0 .Lgdn_nomat_1_0
	v_pk_mul_f32 v[184:185], v[184:185], v[240:241] op_sel_hi:[1,0]
	v_pk_mul_f32 v[186:187], v[186:187], v[240:241] op_sel_hi:[1,0]
	v_pk_mul_f32 v[188:189], v[188:189], v[240:241] op_sel_hi:[1,0]
	v_pk_mul_f32 v[190:191], v[190:191], v[240:241] op_sel_hi:[1,0]
	v_pk_mul_f32 v[192:193], v[192:193], v[240:241] op_sel_hi:[1,0]
	v_pk_mul_f32 v[194:195], v[194:195], v[240:241] op_sel_hi:[1,0]
	v_pk_mul_f32 v[196:197], v[196:197], v[240:241] op_sel_hi:[1,0]
	v_pk_mul_f32 v[198:199], v[198:199], v[240:241] op_sel_hi:[1,0]
	v_pk_mul_f32 v[200:201], v[200:201], v[240:241] op_sel_hi:[1,0]
	v_pk_mul_f32 v[202:203], v[202:203], v[240:241] op_sel_hi:[1,0]
	v_pk_mul_f32 v[204:205], v[204:205], v[240:241] op_sel_hi:[1,0]
	v_pk_mul_f32 v[206:207], v[206:207], v[240:241] op_sel_hi:[1,0]
	v_pk_mul_f32 v[208:209], v[208:209], v[240:241] op_sel_hi:[1,0]
	v_pk_mul_f32 v[210:211], v[210:211], v[240:241] op_sel_hi:[1,0]
	v_pk_mul_f32 v[212:213], v[212:213], v[240:241] op_sel_hi:[1,0]
	v_pk_mul_f32 v[214:215], v[214:215], v[240:241] op_sel_hi:[1,0]
	v_mov_b32_e32 v240, 1.0
	v_mov_b32_e32 v89, 1.0

.Lgdn_nomat_1_1:
	v_mov_b32_e32 v238, v240
	v_mul_f32_e32 v90, v182, v89
	s_nop 1
	v_mfma_f32_16x16x4_f32 v[184:187], v62, v90, v[184:187]
	v_mfma_f32_16x16x4_f32 v[188:191], v63, v90, v[188:191]
	v_mfma_f32_16x16x4_f32 v[192:195], v64, v90, v[192:195]
	v_mfma_f32_16x16x4_f32 v[196:199], v65, v90, v[196:199]
	v_mfma_f32_16x16x4_f32 v[200:203], v66, v90, v[200:203]
	v_mfma_f32_16x16x4_f32 v[204:207], v67, v90, v[204:207]
	v_mfma_f32_16x16x4_f32 v[208:211], v68, v90, v[208:211]
	v_mfma_f32_16x16x4_f32 v[212:215], v69, v90, v[212:215]
	v_cndmask_b32_e32 v183, v82, v83, vcc
	v_cndmask_b32_e64 v183, v183, v84, s[4:5]
	v_cndmask_b32_e64 v183, v183, v85, s[6:7]
	v_mul_f32_e32 v179, v235, v183
	v_fmac_f32_e32 v179, v228, v108
	v_fmac_f32_e32 v179, v229, v109
	v_fmac_f32_e32 v179, v230, v110
	v_fmac_f32_e32 v179, v231, v111
	ds_write_b32 v172, v179 offset:3072
	s_mov_b64 exec, s[40:41]
	ds_add_u32 v91, v92 offset:4
	s_mov_b64 exec, -1
	v_add_u32_e32 v170, 0x1080, v170
	v_add_u32_e32 v237, 0x1080, v237
	v_add_u32_e32 v95, 0x1080, v95
	s_waitcnt lgkmcnt(2)
	v_mfma_f32_16x16x4_f32 v[96:99], v22, v184, 0
	v_mfma_f32_16x16x4_f32 v[100:103], v23, v185, 0
	v_mfma_f32_16x16x4_f32 v[96:99], v24, v186, v[96:99]
	v_mfma_f32_16x16x4_f32 v[100:103], v25, v187, v[100:103]
	v_mul_f32_e32 v129, v132, v70
	v_mul_f32_e32 v130, v133, v71
	v_mul_f32_e32 v131, v134, v72
	v_mul_f32_e32 v153, v135, v73
	v_mfma_f32_16x16x4_f32 v[96:99], v26, v188, v[96:99]
	v_mfma_f32_16x16x4_f32 v[100:103], v27, v189, v[100:103]
	v_mfma_f32_16x16x4_f32 v[96:99], v28, v190, v[96:99]
	v_mfma_f32_16x16x4_f32 v[100:103], v29, v191, v[100:103]
	v_mul_f32_e64 v114, -v132, v136
	v_mul_f32_e64 v115, -v133, v137
	v_mul_f32_e64 v116, -v134, v138
	v_mul_f32_e64 v117, -v135, v139
	v_mfma_f32_16x16x4_f32 v[96:99], v30, v192, v[96:99]
	v_mfma_f32_16x16x4_f32 v[100:103], v31, v193, v[100:103]
	v_mfma_f32_16x16x4_f32 v[96:99], v32, v194, v[96:99]
	v_mfma_f32_16x16x4_f32 v[100:103], v33, v195, v[100:103]
	v_mul_f32_e32 v240, v238, v139
	v_rcp_f32_e32 v89, v240
	v_readfirstlane_b32 s0, v240
	ds_read_b32 v86, v87 offset:1024
	v_mfma_f32_16x16x4_f32 v[96:99], v34, v196, v[96:99]
	v_mfma_f32_16x16x4_f32 v[100:103], v35, v197, v[100:103]
	v_mfma_f32_16x16x4_f32 v[96:99], v36, v198, v[96:99]
	v_mfma_f32_16x16x4_f32 v[100:103], v37, v199, v[100:103]
	ds_read2_b32 v[62:63], v237 offset0:0 offset1:16
	ds_read2_b32 v[64:65], v237 offset0:32 offset1:48
	ds_read2_b32 v[66:67], v237 offset0:64 offset1:80
	ds_read2_b32 v[68:69], v237 offset0:96 offset1:112
	v_mfma_f32_16x16x4_f32 v[96:99], v38, v200, v[96:99]
	v_mfma_f32_16x16x4_f32 v[100:103], v39, v201, v[100:103]
	v_mfma_f32_16x16x4_f32 v[96:99], v40, v202, v[96:99]
	v_mfma_f32_16x16x4_f32 v[100:103], v41, v203, v[100:103]
	ds_read2st64_b32 v[74:75], v171 offset0:20 offset1:21
	ds_read2st64_b32 v[76:77], v171 offset0:22 offset1:23
	ds_read_b128 v[216:219], v175 offset:80
	ds_read_b128 v[220:223], v175 offset:336
	v_mfma_f32_16x16x4_f32 v[96:99], v42, v204, v[96:99]
	v_mfma_f32_16x16x4_f32 v[100:103], v43, v205, v[100:103]
	v_mfma_f32_16x16x4_f32 v[96:99], v44, v206, v[96:99]
	v_mfma_f32_16x16x4_f32 v[100:103], v45, v207, v[100:103]
	ds_read_b32 v235, v176 offset:336
	ds_read_b32 v236, v176 offset:592
	ds_read_b32 v234, v173 offset:1200
	ds_read_b64 v[232:233], v173 offset:1232
	v_mfma_f32_16x16x4_f32 v[96:99], v46, v208, v[96:99]
	v_mfma_f32_16x16x4_f32 v[100:103], v47, v209, v[100:103]
	v_mfma_f32_16x16x4_f32 v[96:99], v48, v210, v[96:99]
	v_mfma_f32_16x16x4_f32 v[100:103], v49, v211, v[100:103]
	ds_read_b128 v[224:227], v173 offset:1264
	ds_read_b128 v[228:231], v174 offset:1168
	v_mfma_f32_16x16x4_f32 v[96:99], v50, v212, v[96:99]
	v_mfma_f32_16x16x4_f32 v[100:103], v51, v213, v[100:103]
	v_mfma_f32_16x16x4_f32 v[96:99], v52, v214, v[96:99]
	v_mfma_f32_16x16x4_f32 v[100:103], v53, v215, v[100:103]
	s_nop 7
	s_nop 1
	v_pk_mul_f32 v[100:101], v[100:101], v[238:239] op_sel_hi:[1,0]
	v_pk_mul_f32 v[102:103], v[102:103], v[238:239] op_sel_hi:[1,0]
	v_pk_fma_f32 v[78:79], v[96:97], v[238:239], v[100:101] op_sel_hi:[1,0,1]
	v_pk_fma_f32 v[80:81], v[98:99], v[238:239], v[102:103] op_sel_hi:[1,0,1]
	v_pk_fma_f32 v[96:97], v[96:97], v[238:239], v[100:101] op_sel_hi:[1,0,1]
	v_pk_fma_f32 v[98:99], v[98:99], v[238:239], v[102:103] op_sel_hi:[1,0,1]
	s_nop 0
	v_permlane32_swap_b32_e32 v96, v78
	v_permlane32_swap_b32_e32 v97, v79
	v_permlane32_swap_b32_e32 v98, v80
	v_permlane32_swap_b32_e32 v99, v81
	v_mov_b32_e32 v82, v96
	v_mov_b32_e32 v83, v97
	v_mov_b32_e32 v84, v98
	v_mov_b32_e32 v85, v99
	s_nop 0
	v_permlane16_swap_b32_e32 v96, v82
	v_permlane16_swap_b32_e32 v97, v83
	v_permlane16_swap_b32_e32 v98, v84
	v_permlane16_swap_b32_e32 v99, v85
	v_fma_f32 v108, v114, v96, v129
	v_fma_f32 v109, v115, v97, v130
	v_fma_f32 v110, v116, v98, v131
	v_fma_f32 v111, v117, v99, v153
	v_fma_f32 v109, -v150, v108, v109
	v_fma_f32 v110, -v148, v108, v110
	v_fma_f32 v111, -v140, v108, v111
	v_fma_f32 v110, -v149, v109, v110
	v_fma_f32 v111, -v141, v109, v111
	v_fma_f32 v111, -v142, v110, v111
	v_cndmask_b32_e32 v182, v108, v109, vcc
	v_cndmask_b32_e64 v182, v182, v110, s[4:5]
	v_cndmask_b32_e64 v182, v182, v111, s[6:7]
	v_mul_f32_e32 v182, v152, v182
	s_cmp_lt_u32 s0, 0x2b800000
	s_cbranch_scc0 .Lgdn_nomat_2_0
	v_pk_mul_f32 v[184:185], v[184:185], v[240:241] op_sel_hi:[1,0]
	v_pk_mul_f32 v[186:187], v[186:187], v[240:241] op_sel_hi:[1,0]
	v_pk_mul_f32 v[188:189], v[188:189], v[240:241] op_sel_hi:[1,0]
	v_pk_mul_f32 v[190:191], v[190:191], v[240:241] op_sel_hi:[1,0]
	v_pk_mul_f32 v[192:193], v[192:193], v[240:241] op_sel_hi:[1,0]
	v_pk_mul_f32 v[194:195], v[194:195], v[240:241] op_sel_hi:[1,0]
	v_pk_mul_f32 v[196:197], v[196:197], v[240:241] op_sel_hi:[1,0]
	v_pk_mul_f32 v[198:199], v[198:199], v[240:241] op_sel_hi:[1,0]
	v_pk_mul_f32 v[200:201], v[200:201], v[240:241] op_sel_hi:[1,0]
	v_pk_mul_f32 v[202:203], v[202:203], v[240:241] op_sel_hi:[1,0]
	v_pk_mul_f32 v[204:205], v[204:205], v[240:241] op_sel_hi:[1,0]
	v_pk_mul_f32 v[206:207], v[206:207], v[240:241] op_sel_hi:[1,0]
	v_pk_mul_f32 v[208:209], v[208:209], v[240:241] op_sel_hi:[1,0]
	v_pk_mul_f32 v[210:211], v[210:211], v[240:241] op_sel_hi:[1,0]
	v_pk_mul_f32 v[212:213], v[212:213], v[240:241] op_sel_hi:[1,0]
	v_pk_mul_f32 v[214:215], v[214:215], v[240:241] op_sel_hi:[1,0]
	v_mov_b32_e32 v240, 1.0
	v_mov_b32_e32 v89, 1.0

.Lgdn_nomat_2_1:
	v_mov_b32_e32 v238, v240
	v_mul_f32_e32 v90, v182, v89
	s_nop 1
	v_mfma_f32_16x16x4_f32 v[184:187], v62, v90, v[184:187]
	v_mfma_f32_16x16x4_f32 v[188:191], v63, v90, v[188:191]
	v_mfma_f32_16x16x4_f32 v[192:195], v64, v90, v[192:195]
	v_mfma_f32_16x16x4_f32 v[196:199], v65, v90, v[196:199]
	v_mfma_f32_16x16x4_f32 v[200:203], v66, v90, v[200:203]
	v_mfma_f32_16x16x4_f32 v[204:207], v67, v90, v[204:207]
	v_mfma_f32_16x16x4_f32 v[208:211], v68, v90, v[208:211]
	v_mfma_f32_16x16x4_f32 v[212:215], v69, v90, v[212:215]
	v_cndmask_b32_e32 v183, v82, v83, vcc
	v_cndmask_b32_e64 v183, v183, v84, s[4:5]
	v_cndmask_b32_e64 v183, v183, v85, s[6:7]
	v_mul_f32_e32 v179, v235, v183
	v_fmac_f32_e32 v179, v228, v108
	v_fmac_f32_e32 v179, v229, v109
	v_fmac_f32_e32 v179, v230, v110
	v_fmac_f32_e32 v179, v231, v111
	ds_write_b32 v172, v179 offset:5120
	s_mov_b64 exec, s[40:41]
	ds_add_u32 v91, v92 offset:8
	s_mov_b64 exec, -1
	v_add_u32_e32 v170, 0x1080, v170
	v_add_u32_e32 v237, 0x1080, v237
	v_add_u32_e32 v95, 0x1080, v95
	s_waitcnt lgkmcnt(2)
	v_mfma_f32_16x16x4_f32 v[96:99], v22, v184, 0
	v_mfma_f32_16x16x4_f32 v[100:103], v23, v185, 0
	v_mfma_f32_16x16x4_f32 v[96:99], v24, v186, v[96:99]
	v_mfma_f32_16x16x4_f32 v[100:103], v25, v187, v[100:103]
	v_mul_f32_e32 v129, v132, v70
	v_mul_f32_e32 v130, v133, v71
	v_mul_f32_e32 v131, v134, v72
	v_mul_f32_e32 v153, v135, v73
	v_mfma_f32_16x16x4_f32 v[96:99], v26, v188, v[96:99]
	v_mfma_f32_16x16x4_f32 v[100:103], v27, v189, v[100:103]
	v_mfma_f32_16x16x4_f32 v[96:99], v28, v190, v[96:99]
	v_mfma_f32_16x16x4_f32 v[100:103], v29, v191, v[100:103]
	v_mul_f32_e64 v114, -v132, v136
	v_mul_f32_e64 v115, -v133, v137
	v_mul_f32_e64 v116, -v134, v138
	v_mul_f32_e64 v117, -v135, v139
	v_mfma_f32_16x16x4_f32 v[96:99], v30, v192, v[96:99]
	v_mfma_f32_16x16x4_f32 v[100:103], v31, v193, v[100:103]
	v_mfma_f32_16x16x4_f32 v[96:99], v32, v194, v[96:99]
	v_mfma_f32_16x16x4_f32 v[100:103], v33, v195, v[100:103]
	v_mul_f32_e32 v240, v238, v139
	v_rcp_f32_e32 v89, v240
	v_readfirstlane_b32 s0, v240
	ds_read_b32 v86, v87 offset:1536
	v_mfma_f32_16x16x4_f32 v[96:99], v34, v196, v[96:99]
	v_mfma_f32_16x16x4_f32 v[100:103], v35, v197, v[100:103]
	v_mfma_f32_16x16x4_f32 v[96:99], v36, v198, v[96:99]
	v_mfma_f32_16x16x4_f32 v[100:103], v37, v199, v[100:103]
	ds_read2_b32 v[62:63], v237 offset0:0 offset1:16
	ds_read2_b32 v[64:65], v237 offset0:32 offset1:48
	ds_read2_b32 v[66:67], v237 offset0:64 offset1:80
	ds_read2_b32 v[68:69], v237 offset0:96 offset1:112
	v_mfma_f32_16x16x4_f32 v[96:99], v38, v200, v[96:99]
	v_mfma_f32_16x16x4_f32 v[100:103], v39, v201, v[100:103]
	v_mfma_f32_16x16x4_f32 v[96:99], v40, v202, v[96:99]
	v_mfma_f32_16x16x4_f32 v[100:103], v41, v203, v[100:103]
	ds_read2st64_b32 v[74:75], v171 offset0:28 offset1:29
	ds_read2st64_b32 v[76:77], v171 offset0:30 offset1:31
	ds_read_b128 v[216:219], v175 offset:112
	ds_read_b128 v[220:223], v175 offset:368
	v_mfma_f32_16x16x4_f32 v[96:99], v42, v204, v[96:99]
	v_mfma_f32_16x16x4_f32 v[100:103], v43, v205, v[100:103]
	v_mfma_f32_16x16x4_f32 v[96:99], v44, v206, v[96:99]
	v_mfma_f32_16x16x4_f32 v[100:103], v45, v207, v[100:103]
	ds_read_b32 v235, v176 offset:368
	ds_read_b32 v236, v176 offset:624
	ds_read_b32 v234, v173 offset:1712
	ds_read_b64 v[232:233], v173 offset:1744
	v_mfma_f32_16x16x4_f32 v[96:99], v46, v208, v[96:99]
	v_mfma_f32_16x16x4_f32 v[100:103], v47, v209, v[100:103]
	v_mfma_f32_16x16x4_f32 v[96:99], v48, v210, v[96:99]
	v_mfma_f32_16x16x4_f32 v[100:103], v49, v211, v[100:103]
	ds_read_b128 v[224:227], v173 offset:1776
	ds_read_b128 v[228:231], v174 offset:1680
	v_mfma_f32_16x16x4_f32 v[96:99], v50, v212, v[96:99]
	v_mfma_f32_16x16x4_f32 v[100:103], v51, v213, v[100:103]
	v_mfma_f32_16x16x4_f32 v[96:99], v52, v214, v[96:99]
	v_mfma_f32_16x16x4_f32 v[100:103], v53, v215, v[100:103]
	s_nop 7
	s_nop 1
	v_pk_mul_f32 v[100:101], v[100:101], v[238:239] op_sel_hi:[1,0]
	v_pk_mul_f32 v[102:103], v[102:103], v[238:239] op_sel_hi:[1,0]
	v_pk_fma_f32 v[78:79], v[96:97], v[238:239], v[100:101] op_sel_hi:[1,0,1]
	v_pk_fma_f32 v[80:81], v[98:99], v[238:239], v[102:103] op_sel_hi:[1,0,1]
	v_pk_fma_f32 v[96:97], v[96:97], v[238:239], v[100:101] op_sel_hi:[1,0,1]
	v_pk_fma_f32 v[98:99], v[98:99], v[238:239], v[102:103] op_sel_hi:[1,0,1]
	s_nop 0
	v_permlane32_swap_b32_e32 v96, v78
	v_permlane32_swap_b32_e32 v97, v79
	v_permlane32_swap_b32_e32 v98, v80
	v_permlane32_swap_b32_e32 v99, v81
	v_mov_b32_e32 v82, v96
	v_mov_b32_e32 v83, v97
	v_mov_b32_e32 v84, v98
	v_mov_b32_e32 v85, v99
	s_nop 0
	v_permlane16_swap_b32_e32 v96, v82
	v_permlane16_swap_b32_e32 v97, v83
	v_permlane16_swap_b32_e32 v98, v84
	v_permlane16_swap_b32_e32 v99, v85
	v_fma_f32 v108, v114, v96, v129
	v_fma_f32 v109, v115, v97, v130
	v_fma_f32 v110, v116, v98, v131
	v_fma_f32 v111, v117, v99, v153
	v_fma_f32 v109, -v150, v108, v109
	v_fma_f32 v110, -v148, v108, v110
	v_fma_f32 v111, -v140, v108, v111
	v_fma_f32 v110, -v149, v109, v110
	v_fma_f32 v111, -v141, v109, v111
	v_fma_f32 v111, -v142, v110, v111
	v_cndmask_b32_e32 v182, v108, v109, vcc
	v_cndmask_b32_e64 v182, v182, v110, s[4:5]
	v_cndmask_b32_e64 v182, v182, v111, s[6:7]
	v_mul_f32_e32 v182, v152, v182
	s_cmp_lt_u32 s0, 0x2b800000
	s_cbranch_scc0 .Lgdn_nomat_3_0
	v_pk_mul_f32 v[184:185], v[184:185], v[240:241] op_sel_hi:[1,0]
	v_pk_mul_f32 v[186:187], v[186:187], v[240:241] op_sel_hi:[1,0]
	v_pk_mul_f32 v[188:189], v[188:189], v[240:241] op_sel_hi:[1,0]
	v_pk_mul_f32 v[190:191], v[190:191], v[240:241] op_sel_hi:[1,0]
	v_pk_mul_f32 v[192:193], v[192:193], v[240:241] op_sel_hi:[1,0]
	v_pk_mul_f32 v[194:195], v[194:195], v[240:241] op_sel_hi:[1,0]
	v_pk_mul_f32 v[196:197], v[196:197], v[240:241] op_sel_hi:[1,0]
	v_pk_mul_f32 v[198:199], v[198:199], v[240:241] op_sel_hi:[1,0]
	v_pk_mul_f32 v[200:201], v[200:201], v[240:241] op_sel_hi:[1,0]
	v_pk_mul_f32 v[202:203], v[202:203], v[240:241] op_sel_hi:[1,0]
	v_pk_mul_f32 v[204:205], v[204:205], v[240:241] op_sel_hi:[1,0]
	v_pk_mul_f32 v[206:207], v[206:207], v[240:241] op_sel_hi:[1,0]
	v_pk_mul_f32 v[208:209], v[208:209], v[240:241] op_sel_hi:[1,0]
	v_pk_mul_f32 v[210:211], v[210:211], v[240:241] op_sel_hi:[1,0]
	v_pk_mul_f32 v[212:213], v[212:213], v[240:241] op_sel_hi:[1,0]
	v_pk_mul_f32 v[214:215], v[214:215], v[240:241] op_sel_hi:[1,0]
	v_mov_b32_e32 v240, 1.0
	v_mov_b32_e32 v89, 1.0

.Lgdn_nomat_3_1:
	v_mov_b32_e32 v238, v240
	v_mul_f32_e32 v90, v182, v89
	s_nop 1
	v_mfma_f32_16x16x4_f32 v[184:187], v62, v90, v[184:187]
	v_mfma_f32_16x16x4_f32 v[188:191], v63, v90, v[188:191]
	v_mfma_f32_16x16x4_f32 v[192:195], v64, v90, v[192:195]
	v_mfma_f32_16x16x4_f32 v[196:199], v65, v90, v[196:199]
	v_mfma_f32_16x16x4_f32 v[200:203], v66, v90, v[200:203]
	v_mfma_f32_16x16x4_f32 v[204:207], v67, v90, v[204:207]
	v_mfma_f32_16x16x4_f32 v[208:211], v68, v90, v[208:211]
	v_mfma_f32_16x16x4_f32 v[212:215], v69, v90, v[212:215]
	v_cndmask_b32_e32 v183, v82, v83, vcc
	v_cndmask_b32_e64 v183, v183, v84, s[4:5]
	v_cndmask_b32_e64 v183, v183, v85, s[6:7]
	v_mul_f32_e32 v179, v235, v183
	v_fmac_f32_e32 v179, v228, v108
	v_fmac_f32_e32 v179, v229, v109
	v_fmac_f32_e32 v179, v230, v110
	v_fmac_f32_e32 v179, v231, v111
	ds_write_b32 v172, v179 offset:7168
	s_mov_b64 exec, s[40:41]
	ds_add_u32 v91, v92 offset:12
	s_mov_b64 exec, -1
	v_add_u32_e32 v170, 0x1080, v170
	v_add_u32_e32 v237, 0x1080, v237
	v_add_u32_e32 v95, 0x1080, v95
	s_waitcnt lgkmcnt(2)
	v_mfma_f32_16x16x4_f32 v[96:99], v22, v184, 0
	v_mfma_f32_16x16x4_f32 v[100:103], v23, v185, 0
	v_mfma_f32_16x16x4_f32 v[96:99], v24, v186, v[96:99]
	v_mfma_f32_16x16x4_f32 v[100:103], v25, v187, v[100:103]
	v_mul_f32_e32 v129, v132, v70
	v_mul_f32_e32 v130, v133, v71
	v_mul_f32_e32 v131, v134, v72
	v_mul_f32_e32 v153, v135, v73
	v_mfma_f32_16x16x4_f32 v[96:99], v26, v188, v[96:99]
	v_mfma_f32_16x16x4_f32 v[100:103], v27, v189, v[100:103]
	v_mfma_f32_16x16x4_f32 v[96:99], v28, v190, v[96:99]
	v_mfma_f32_16x16x4_f32 v[100:103], v29, v191, v[100:103]
	v_mul_f32_e64 v114, -v132, v136
	v_mul_f32_e64 v115, -v133, v137
	v_mul_f32_e64 v116, -v134, v138
	v_mul_f32_e64 v117, -v135, v139
	v_mfma_f32_16x16x4_f32 v[96:99], v30, v192, v[96:99]
	v_mfma_f32_16x16x4_f32 v[100:103], v31, v193, v[100:103]
	v_mfma_f32_16x16x4_f32 v[96:99], v32, v194, v[96:99]
	v_mfma_f32_16x16x4_f32 v[100:103], v33, v195, v[100:103]
	v_mul_f32_e32 v240, v238, v139
	v_rcp_f32_e32 v89, v240
	v_readfirstlane_b32 s0, v240
	ds_read_b32 v86, v87 offset:2048
	v_mfma_f32_16x16x4_f32 v[96:99], v34, v196, v[96:99]
	v_mfma_f32_16x16x4_f32 v[100:103], v35, v197, v[100:103]
	v_mfma_f32_16x16x4_f32 v[96:99], v36, v198, v[96:99]
	v_mfma_f32_16x16x4_f32 v[100:103], v37, v199, v[100:103]
	ds_read2_b32 v[62:63], v237 offset0:0 offset1:16
	ds_read2_b32 v[64:65], v237 offset0:32 offset1:48
	ds_read2_b32 v[66:67], v237 offset0:64 offset1:80
	ds_read2_b32 v[68:69], v237 offset0:96 offset1:112
	v_mfma_f32_16x16x4_f32 v[96:99], v38, v200, v[96:99]
	v_mfma_f32_16x16x4_f32 v[100:103], v39, v201, v[100:103]
	v_mfma_f32_16x16x4_f32 v[96:99], v40, v202, v[96:99]
	v_mfma_f32_16x16x4_f32 v[100:103], v41, v203, v[100:103]
	ds_read2st64_b32 v[74:75], v171 offset0:36 offset1:37
	ds_read2st64_b32 v[76:77], v171 offset0:38 offset1:39
	ds_read_b128 v[216:219], v175 offset:144
	ds_read_b128 v[220:223], v175 offset:400
	v_mfma_f32_16x16x4_f32 v[96:99], v42, v204, v[96:99]
	v_mfma_f32_16x16x4_f32 v[100:103], v43, v205, v[100:103]
	v_mfma_f32_16x16x4_f32 v[96:99], v44, v206, v[96:99]
	v_mfma_f32_16x16x4_f32 v[100:103], v45, v207, v[100:103]
	ds_read_b32 v235, v176 offset:400
	ds_read_b32 v236, v176 offset:656
	ds_read_b32 v234, v173 offset:2224
	ds_read_b64 v[232:233], v173 offset:2256
	v_mfma_f32_16x16x4_f32 v[96:99], v46, v208, v[96:99]
	v_mfma_f32_16x16x4_f32 v[100:103], v47, v209, v[100:103]
	v_mfma_f32_16x16x4_f32 v[96:99], v48, v210, v[96:99]
	v_mfma_f32_16x16x4_f32 v[100:103], v49, v211, v[100:103]
	ds_read_b128 v[224:227], v173 offset:2288
	ds_read_b128 v[228:231], v174 offset:2192
	v_mfma_f32_16x16x4_f32 v[96:99], v50, v212, v[96:99]
	v_mfma_f32_16x16x4_f32 v[100:103], v51, v213, v[100:103]
	v_mfma_f32_16x16x4_f32 v[96:99], v52, v214, v[96:99]
	v_mfma_f32_16x16x4_f32 v[100:103], v53, v215, v[100:103]
	s_nop 7
	s_nop 1
	v_pk_mul_f32 v[100:101], v[100:101], v[238:239] op_sel_hi:[1,0]
	v_pk_mul_f32 v[102:103], v[102:103], v[238:239] op_sel_hi:[1,0]
	v_pk_fma_f32 v[78:79], v[96:97], v[238:239], v[100:101] op_sel_hi:[1,0,1]
	v_pk_fma_f32 v[80:81], v[98:99], v[238:239], v[102:103] op_sel_hi:[1,0,1]
	v_pk_fma_f32 v[96:97], v[96:97], v[238:239], v[100:101] op_sel_hi:[1,0,1]
	v_pk_fma_f32 v[98:99], v[98:99], v[238:239], v[102:103] op_sel_hi:[1,0,1]
	s_nop 0
	v_permlane32_swap_b32_e32 v96, v78
	v_permlane32_swap_b32_e32 v97, v79
	v_permlane32_swap_b32_e32 v98, v80
	v_permlane32_swap_b32_e32 v99, v81
	v_mov_b32_e32 v82, v96
	v_mov_b32_e32 v83, v97
	v_mov_b32_e32 v84, v98
	v_mov_b32_e32 v85, v99
	s_nop 0
	v_permlane16_swap_b32_e32 v96, v82
	v_permlane16_swap_b32_e32 v97, v83
	v_permlane16_swap_b32_e32 v98, v84
	v_permlane16_swap_b32_e32 v99, v85
	v_fma_f32 v108, v114, v96, v129
	v_fma_f32 v109, v115, v97, v130
	v_fma_f32 v110, v116, v98, v131
	v_fma_f32 v111, v117, v99, v153
	v_fma_f32 v109, -v150, v108, v109
	v_fma_f32 v110, -v148, v108, v110
	v_fma_f32 v111, -v140, v108, v111
	v_fma_f32 v110, -v149, v109, v110
	v_fma_f32 v111, -v141, v109, v111
	v_fma_f32 v111, -v142, v110, v111
	v_cndmask_b32_e32 v182, v108, v109, vcc
	v_cndmask_b32_e64 v182, v182, v110, s[4:5]
	v_cndmask_b32_e64 v182, v182, v111, s[6:7]
	v_mul_f32_e32 v182, v152, v182
	s_cmp_lt_u32 s0, 0x2b800000
	s_cbranch_scc0 .Lgdn_nomat_4_0
	v_pk_mul_f32 v[184:185], v[184:185], v[240:241] op_sel_hi:[1,0]
	v_pk_mul_f32 v[186:187], v[186:187], v[240:241] op_sel_hi:[1,0]
	v_pk_mul_f32 v[188:189], v[188:189], v[240:241] op_sel_hi:[1,0]
	v_pk_mul_f32 v[190:191], v[190:191], v[240:241] op_sel_hi:[1,0]
	v_pk_mul_f32 v[192:193], v[192:193], v[240:241] op_sel_hi:[1,0]
	v_pk_mul_f32 v[194:195], v[194:195], v[240:241] op_sel_hi:[1,0]
	v_pk_mul_f32 v[196:197], v[196:197], v[240:241] op_sel_hi:[1,0]
	v_pk_mul_f32 v[198:199], v[198:199], v[240:241] op_sel_hi:[1,0]
	v_pk_mul_f32 v[200:201], v[200:201], v[240:241] op_sel_hi:[1,0]
	v_pk_mul_f32 v[202:203], v[202:203], v[240:241] op_sel_hi:[1,0]
	v_pk_mul_f32 v[204:205], v[204:205], v[240:241] op_sel_hi:[1,0]
	v_pk_mul_f32 v[206:207], v[206:207], v[240:241] op_sel_hi:[1,0]
	v_pk_mul_f32 v[208:209], v[208:209], v[240:241] op_sel_hi:[1,0]
	v_pk_mul_f32 v[210:211], v[210:211], v[240:241] op_sel_hi:[1,0]
	v_pk_mul_f32 v[212:213], v[212:213], v[240:241] op_sel_hi:[1,0]
	v_pk_mul_f32 v[214:215], v[214:215], v[240:241] op_sel_hi:[1,0]
	v_mov_b32_e32 v240, 1.0
	v_mov_b32_e32 v89, 1.0

.Lgdn_nomat_4_1:
	v_mov_b32_e32 v238, v240
	v_mul_f32_e32 v90, v182, v89
	s_nop 1
	v_mfma_f32_16x16x4_f32 v[184:187], v62, v90, v[184:187]
	v_mfma_f32_16x16x4_f32 v[188:191], v63, v90, v[188:191]
	v_mfma_f32_16x16x4_f32 v[192:195], v64, v90, v[192:195]
	v_mfma_f32_16x16x4_f32 v[196:199], v65, v90, v[196:199]
	v_mfma_f32_16x16x4_f32 v[200:203], v66, v90, v[200:203]
	v_mfma_f32_16x16x4_f32 v[204:207], v67, v90, v[204:207]
	v_mfma_f32_16x16x4_f32 v[208:211], v68, v90, v[208:211]
	v_mfma_f32_16x16x4_f32 v[212:215], v69, v90, v[212:215]
	v_cndmask_b32_e32 v183, v82, v83, vcc
	v_cndmask_b32_e64 v183, v183, v84, s[4:5]
	v_cndmask_b32_e64 v183, v183, v85, s[6:7]
	v_mul_f32_e32 v179, v235, v183
	v_fmac_f32_e32 v179, v228, v108
	v_fmac_f32_e32 v179, v229, v109
	v_fmac_f32_e32 v179, v230, v110
	v_fmac_f32_e32 v179, v231, v111
	ds_write_b32 v172, v179 offset:9216
	s_mov_b64 exec, s[40:41]
	ds_add_u32 v91, v92 offset:16
	s_mov_b64 exec, -1
	v_add_u32_e32 v170, 0x1080, v170
	v_add_u32_e32 v237, 0x1080, v237
	v_add_u32_e32 v95, 0x1080, v95
	s_waitcnt lgkmcnt(2)
	v_mfma_f32_16x16x4_f32 v[96:99], v22, v184, 0
	v_mfma_f32_16x16x4_f32 v[100:103], v23, v185, 0
	v_mfma_f32_16x16x4_f32 v[96:99], v24, v186, v[96:99]
	v_mfma_f32_16x16x4_f32 v[100:103], v25, v187, v[100:103]
	v_mul_f32_e32 v129, v132, v70
	v_mul_f32_e32 v130, v133, v71
	v_mul_f32_e32 v131, v134, v72
	v_mul_f32_e32 v153, v135, v73
	v_mfma_f32_16x16x4_f32 v[96:99], v26, v188, v[96:99]
	v_mfma_f32_16x16x4_f32 v[100:103], v27, v189, v[100:103]
	v_mfma_f32_16x16x4_f32 v[96:99], v28, v190, v[96:99]
	v_mfma_f32_16x16x4_f32 v[100:103], v29, v191, v[100:103]
	v_mul_f32_e64 v114, -v132, v136
	v_mul_f32_e64 v115, -v133, v137
	v_mul_f32_e64 v116, -v134, v138
	v_mul_f32_e64 v117, -v135, v139
	v_mfma_f32_16x16x4_f32 v[96:99], v30, v192, v[96:99]
	v_mfma_f32_16x16x4_f32 v[100:103], v31, v193, v[100:103]
	v_mfma_f32_16x16x4_f32 v[96:99], v32, v194, v[96:99]
	v_mfma_f32_16x16x4_f32 v[100:103], v33, v195, v[100:103]
	v_mul_f32_e32 v240, v238, v139
	v_rcp_f32_e32 v89, v240
	v_readfirstlane_b32 s0, v240
	ds_read_b32 v86, v87 offset:2560
	v_mfma_f32_16x16x4_f32 v[96:99], v34, v196, v[96:99]
	v_mfma_f32_16x16x4_f32 v[100:103], v35, v197, v[100:103]
	v_mfma_f32_16x16x4_f32 v[96:99], v36, v198, v[96:99]
	v_mfma_f32_16x16x4_f32 v[100:103], v37, v199, v[100:103]
	ds_read2_b32 v[62:63], v237 offset0:0 offset1:16
	ds_read2_b32 v[64:65], v237 offset0:32 offset1:48
	ds_read2_b32 v[66:67], v237 offset0:64 offset1:80
	ds_read2_b32 v[68:69], v237 offset0:96 offset1:112
	v_mfma_f32_16x16x4_f32 v[96:99], v38, v200, v[96:99]
	v_mfma_f32_16x16x4_f32 v[100:103], v39, v201, v[100:103]
	v_mfma_f32_16x16x4_f32 v[96:99], v40, v202, v[96:99]
	v_mfma_f32_16x16x4_f32 v[100:103], v41, v203, v[100:103]
	ds_read2st64_b32 v[74:75], v171 offset0:44 offset1:45
	ds_read2st64_b32 v[76:77], v171 offset0:46 offset1:47
	ds_read_b128 v[216:219], v175 offset:176
	ds_read_b128 v[220:223], v175 offset:432
	v_mfma_f32_16x16x4_f32 v[96:99], v42, v204, v[96:99]
	v_mfma_f32_16x16x4_f32 v[100:103], v43, v205, v[100:103]
	v_mfma_f32_16x16x4_f32 v[96:99], v44, v206, v[96:99]
	v_mfma_f32_16x16x4_f32 v[100:103], v45, v207, v[100:103]
	ds_read_b32 v235, v176 offset:432
	ds_read_b32 v236, v176 offset:688
	ds_read_b32 v234, v173 offset:2736
	ds_read_b64 v[232:233], v173 offset:2768
	v_mfma_f32_16x16x4_f32 v[96:99], v46, v208, v[96:99]
	v_mfma_f32_16x16x4_f32 v[100:103], v47, v209, v[100:103]
	v_mfma_f32_16x16x4_f32 v[96:99], v48, v210, v[96:99]
	v_mfma_f32_16x16x4_f32 v[100:103], v49, v211, v[100:103]
	ds_read_b128 v[224:227], v173 offset:2800
	ds_read_b128 v[228:231], v174 offset:2704
	v_mfma_f32_16x16x4_f32 v[96:99], v50, v212, v[96:99]
	v_mfma_f32_16x16x4_f32 v[100:103], v51, v213, v[100:103]
	v_mfma_f32_16x16x4_f32 v[96:99], v52, v214, v[96:99]
	v_mfma_f32_16x16x4_f32 v[100:103], v53, v215, v[100:103]
	s_nop 7
	s_nop 1
	v_pk_mul_f32 v[100:101], v[100:101], v[238:239] op_sel_hi:[1,0]
	v_pk_mul_f32 v[102:103], v[102:103], v[238:239] op_sel_hi:[1,0]
	v_pk_fma_f32 v[78:79], v[96:97], v[238:239], v[100:101] op_sel_hi:[1,0,1]
	v_pk_fma_f32 v[80:81], v[98:99], v[238:239], v[102:103] op_sel_hi:[1,0,1]
	v_pk_fma_f32 v[96:97], v[96:97], v[238:239], v[100:101] op_sel_hi:[1,0,1]
	v_pk_fma_f32 v[98:99], v[98:99], v[238:239], v[102:103] op_sel_hi:[1,0,1]
	s_nop 0
	v_permlane32_swap_b32_e32 v96, v78
	v_permlane32_swap_b32_e32 v97, v79
	v_permlane32_swap_b32_e32 v98, v80
	v_permlane32_swap_b32_e32 v99, v81
	v_mov_b32_e32 v82, v96
	v_mov_b32_e32 v83, v97
	v_mov_b32_e32 v84, v98
	v_mov_b32_e32 v85, v99
	s_nop 0
	v_permlane16_swap_b32_e32 v96, v82
	v_permlane16_swap_b32_e32 v97, v83
	v_permlane16_swap_b32_e32 v98, v84
	v_permlane16_swap_b32_e32 v99, v85
	v_fma_f32 v108, v114, v96, v129
	v_fma_f32 v109, v115, v97, v130
	v_fma_f32 v110, v116, v98, v131
	v_fma_f32 v111, v117, v99, v153
	v_fma_f32 v109, -v150, v108, v109
	v_fma_f32 v110, -v148, v108, v110
	v_fma_f32 v111, -v140, v108, v111
	v_fma_f32 v110, -v149, v109, v110
	v_fma_f32 v111, -v141, v109, v111
	v_fma_f32 v111, -v142, v110, v111
	v_cndmask_b32_e32 v182, v108, v109, vcc
	v_cndmask_b32_e64 v182, v182, v110, s[4:5]
	v_cndmask_b32_e64 v182, v182, v111, s[6:7]
	v_mul_f32_e32 v182, v152, v182
	s_cmp_lt_u32 s0, 0x2b800000
	s_cbranch_scc0 .Lgdn_nomat_5_0
	v_pk_mul_f32 v[184:185], v[184:185], v[240:241] op_sel_hi:[1,0]
	v_pk_mul_f32 v[186:187], v[186:187], v[240:241] op_sel_hi:[1,0]
	v_pk_mul_f32 v[188:189], v[188:189], v[240:241] op_sel_hi:[1,0]
	v_pk_mul_f32 v[190:191], v[190:191], v[240:241] op_sel_hi:[1,0]
	v_pk_mul_f32 v[192:193], v[192:193], v[240:241] op_sel_hi:[1,0]
	v_pk_mul_f32 v[194:195], v[194:195], v[240:241] op_sel_hi:[1,0]
	v_pk_mul_f32 v[196:197], v[196:197], v[240:241] op_sel_hi:[1,0]
	v_pk_mul_f32 v[198:199], v[198:199], v[240:241] op_sel_hi:[1,0]
	v_pk_mul_f32 v[200:201], v[200:201], v[240:241] op_sel_hi:[1,0]
	v_pk_mul_f32 v[202:203], v[202:203], v[240:241] op_sel_hi:[1,0]
	v_pk_mul_f32 v[204:205], v[204:205], v[240:241] op_sel_hi:[1,0]
	v_pk_mul_f32 v[206:207], v[206:207], v[240:241] op_sel_hi:[1,0]
	v_pk_mul_f32 v[208:209], v[208:209], v[240:241] op_sel_hi:[1,0]
	v_pk_mul_f32 v[210:211], v[210:211], v[240:241] op_sel_hi:[1,0]
	v_pk_mul_f32 v[212:213], v[212:213], v[240:241] op_sel_hi:[1,0]
	v_pk_mul_f32 v[214:215], v[214:215], v[240:241] op_sel_hi:[1,0]
	v_mov_b32_e32 v240, 1.0
	v_mov_b32_e32 v89, 1.0

.Lgdn_nomat_5_1:
	v_mov_b32_e32 v238, v240
	v_mul_f32_e32 v90, v182, v89
	s_nop 1
	v_mfma_f32_16x16x4_f32 v[184:187], v62, v90, v[184:187]
	v_mfma_f32_16x16x4_f32 v[188:191], v63, v90, v[188:191]
	v_mfma_f32_16x16x4_f32 v[192:195], v64, v90, v[192:195]
	v_mfma_f32_16x16x4_f32 v[196:199], v65, v90, v[196:199]
	v_mfma_f32_16x16x4_f32 v[200:203], v66, v90, v[200:203]
	v_mfma_f32_16x16x4_f32 v[204:207], v67, v90, v[204:207]
	v_mfma_f32_16x16x4_f32 v[208:211], v68, v90, v[208:211]
	v_mfma_f32_16x16x4_f32 v[212:215], v69, v90, v[212:215]
	v_cndmask_b32_e32 v183, v82, v83, vcc
	v_cndmask_b32_e64 v183, v183, v84, s[4:5]
	v_cndmask_b32_e64 v183, v183, v85, s[6:7]
	v_mul_f32_e32 v179, v235, v183
	v_fmac_f32_e32 v179, v228, v108
	v_fmac_f32_e32 v179, v229, v109
	v_fmac_f32_e32 v179, v230, v110
	v_fmac_f32_e32 v179, v231, v111
	ds_write_b32 v172, v179 offset:11264
	s_mov_b64 exec, s[40:41]
	ds_add_u32 v91, v92 offset:20
	s_mov_b64 exec, -1
	v_add_u32_e32 v170, 0x1080, v170
	v_add_u32_e32 v237, 0x1080, v237
	v_add_u32_e32 v95, 0x1080, v95
	s_waitcnt lgkmcnt(2)
	v_mfma_f32_16x16x4_f32 v[96:99], v22, v184, 0
	v_mfma_f32_16x16x4_f32 v[100:103], v23, v185, 0
	v_mfma_f32_16x16x4_f32 v[96:99], v24, v186, v[96:99]
	v_mfma_f32_16x16x4_f32 v[100:103], v25, v187, v[100:103]
	v_mul_f32_e32 v129, v132, v70
	v_mul_f32_e32 v130, v133, v71
	v_mul_f32_e32 v131, v134, v72
	v_mul_f32_e32 v153, v135, v73
	v_mfma_f32_16x16x4_f32 v[96:99], v26, v188, v[96:99]
	v_mfma_f32_16x16x4_f32 v[100:103], v27, v189, v[100:103]
	v_mfma_f32_16x16x4_f32 v[96:99], v28, v190, v[96:99]
	v_mfma_f32_16x16x4_f32 v[100:103], v29, v191, v[100:103]
	v_mul_f32_e64 v114, -v132, v136
	v_mul_f32_e64 v115, -v133, v137
	v_mul_f32_e64 v116, -v134, v138
	v_mul_f32_e64 v117, -v135, v139
	v_mfma_f32_16x16x4_f32 v[96:99], v30, v192, v[96:99]
	v_mfma_f32_16x16x4_f32 v[100:103], v31, v193, v[100:103]
	v_mfma_f32_16x16x4_f32 v[96:99], v32, v194, v[96:99]
	v_mfma_f32_16x16x4_f32 v[100:103], v33, v195, v[100:103]
	v_mul_f32_e32 v240, v238, v139
	v_rcp_f32_e32 v89, v240
	v_readfirstlane_b32 s0, v240
	ds_read_b32 v86, v87 offset:3072
	v_mfma_f32_16x16x4_f32 v[96:99], v34, v196, v[96:99]
	v_mfma_f32_16x16x4_f32 v[100:103], v35, v197, v[100:103]
	v_mfma_f32_16x16x4_f32 v[96:99], v36, v198, v[96:99]
	v_mfma_f32_16x16x4_f32 v[100:103], v37, v199, v[100:103]
	ds_read2_b32 v[62:63], v237 offset0:0 offset1:16
	ds_read2_b32 v[64:65], v237 offset0:32 offset1:48
	ds_read2_b32 v[66:67], v237 offset0:64 offset1:80
	ds_read2_b32 v[68:69], v237 offset0:96 offset1:112
	v_mfma_f32_16x16x4_f32 v[96:99], v38, v200, v[96:99]
	v_mfma_f32_16x16x4_f32 v[100:103], v39, v201, v[100:103]
	v_mfma_f32_16x16x4_f32 v[96:99], v40, v202, v[96:99]
	v_mfma_f32_16x16x4_f32 v[100:103], v41, v203, v[100:103]
	ds_read2st64_b32 v[74:75], v171 offset0:52 offset1:53
	ds_read2st64_b32 v[76:77], v171 offset0:54 offset1:55
	ds_read_b128 v[216:219], v175 offset:208
	ds_read_b128 v[220:223], v175 offset:464
	v_mfma_f32_16x16x4_f32 v[96:99], v42, v204, v[96:99]
	v_mfma_f32_16x16x4_f32 v[100:103], v43, v205, v[100:103]
	v_mfma_f32_16x16x4_f32 v[96:99], v44, v206, v[96:99]
	v_mfma_f32_16x16x4_f32 v[100:103], v45, v207, v[100:103]
	ds_read_b32 v235, v176 offset:464
	ds_read_b32 v236, v176 offset:720
	ds_read_b32 v234, v173 offset:3248
	ds_read_b64 v[232:233], v173 offset:3280
	v_mfma_f32_16x16x4_f32 v[96:99], v46, v208, v[96:99]
	v_mfma_f32_16x16x4_f32 v[100:103], v47, v209, v[100:103]
	v_mfma_f32_16x16x4_f32 v[96:99], v48, v210, v[96:99]
	v_mfma_f32_16x16x4_f32 v[100:103], v49, v211, v[100:103]
	ds_read_b128 v[224:227], v173 offset:3312
	ds_read_b128 v[228:231], v174 offset:3216
	v_mfma_f32_16x16x4_f32 v[96:99], v50, v212, v[96:99]
	v_mfma_f32_16x16x4_f32 v[100:103], v51, v213, v[100:103]
	v_mfma_f32_16x16x4_f32 v[96:99], v52, v214, v[96:99]
	v_mfma_f32_16x16x4_f32 v[100:103], v53, v215, v[100:103]
	s_nop 7
	s_nop 1
	v_pk_mul_f32 v[100:101], v[100:101], v[238:239] op_sel_hi:[1,0]
	v_pk_mul_f32 v[102:103], v[102:103], v[238:239] op_sel_hi:[1,0]
	v_pk_fma_f32 v[78:79], v[96:97], v[238:239], v[100:101] op_sel_hi:[1,0,1]
	v_pk_fma_f32 v[80:81], v[98:99], v[238:239], v[102:103] op_sel_hi:[1,0,1]
	v_pk_fma_f32 v[96:97], v[96:97], v[238:239], v[100:101] op_sel_hi:[1,0,1]
	v_pk_fma_f32 v[98:99], v[98:99], v[238:239], v[102:103] op_sel_hi:[1,0,1]
	s_nop 0
	v_permlane32_swap_b32_e32 v96, v78
	v_permlane32_swap_b32_e32 v97, v79
	v_permlane32_swap_b32_e32 v98, v80
	v_permlane32_swap_b32_e32 v99, v81
	v_mov_b32_e32 v82, v96
	v_mov_b32_e32 v83, v97
	v_mov_b32_e32 v84, v98
	v_mov_b32_e32 v85, v99
	s_nop 0
	v_permlane16_swap_b32_e32 v96, v82
	v_permlane16_swap_b32_e32 v97, v83
	v_permlane16_swap_b32_e32 v98, v84
	v_permlane16_swap_b32_e32 v99, v85
	v_fma_f32 v108, v114, v96, v129
	v_fma_f32 v109, v115, v97, v130
	v_fma_f32 v110, v116, v98, v131
	v_fma_f32 v111, v117, v99, v153
	v_fma_f32 v109, -v150, v108, v109
	v_fma_f32 v110, -v148, v108, v110
	v_fma_f32 v111, -v140, v108, v111
	v_fma_f32 v110, -v149, v109, v110
	v_fma_f32 v111, -v141, v109, v111
	v_fma_f32 v111, -v142, v110, v111
	v_cndmask_b32_e32 v182, v108, v109, vcc
	v_cndmask_b32_e64 v182, v182, v110, s[4:5]
	v_cndmask_b32_e64 v182, v182, v111, s[6:7]
	v_mul_f32_e32 v182, v152, v182
	s_cmp_lt_u32 s0, 0x2b800000
	s_cbranch_scc0 .Lgdn_nomat_6_0
	v_pk_mul_f32 v[184:185], v[184:185], v[240:241] op_sel_hi:[1,0]
	v_pk_mul_f32 v[186:187], v[186:187], v[240:241] op_sel_hi:[1,0]
	v_pk_mul_f32 v[188:189], v[188:189], v[240:241] op_sel_hi:[1,0]
	v_pk_mul_f32 v[190:191], v[190:191], v[240:241] op_sel_hi:[1,0]
	v_pk_mul_f32 v[192:193], v[192:193], v[240:241] op_sel_hi:[1,0]
	v_pk_mul_f32 v[194:195], v[194:195], v[240:241] op_sel_hi:[1,0]
	v_pk_mul_f32 v[196:197], v[196:197], v[240:241] op_sel_hi:[1,0]
	v_pk_mul_f32 v[198:199], v[198:199], v[240:241] op_sel_hi:[1,0]
	v_pk_mul_f32 v[200:201], v[200:201], v[240:241] op_sel_hi:[1,0]
	v_pk_mul_f32 v[202:203], v[202:203], v[240:241] op_sel_hi:[1,0]
	v_pk_mul_f32 v[204:205], v[204:205], v[240:241] op_sel_hi:[1,0]
	v_pk_mul_f32 v[206:207], v[206:207], v[240:241] op_sel_hi:[1,0]
	v_pk_mul_f32 v[208:209], v[208:209], v[240:241] op_sel_hi:[1,0]
	v_pk_mul_f32 v[210:211], v[210:211], v[240:241] op_sel_hi:[1,0]
	v_pk_mul_f32 v[212:213], v[212:213], v[240:241] op_sel_hi:[1,0]
	v_pk_mul_f32 v[214:215], v[214:215], v[240:241] op_sel_hi:[1,0]
	v_mov_b32_e32 v240, 1.0
	v_mov_b32_e32 v89, 1.0

.Lgdn_nomat_6_1:
	v_mov_b32_e32 v238, v240
	v_mul_f32_e32 v90, v182, v89
	s_nop 1
	v_mfma_f32_16x16x4_f32 v[184:187], v62, v90, v[184:187]
	v_mfma_f32_16x16x4_f32 v[188:191], v63, v90, v[188:191]
	v_mfma_f32_16x16x4_f32 v[192:195], v64, v90, v[192:195]
	v_mfma_f32_16x16x4_f32 v[196:199], v65, v90, v[196:199]
	v_mfma_f32_16x16x4_f32 v[200:203], v66, v90, v[200:203]
	v_mfma_f32_16x16x4_f32 v[204:207], v67, v90, v[204:207]
	v_mfma_f32_16x16x4_f32 v[208:211], v68, v90, v[208:211]
	v_mfma_f32_16x16x4_f32 v[212:215], v69, v90, v[212:215]
	v_cndmask_b32_e32 v183, v82, v83, vcc
	v_cndmask_b32_e64 v183, v183, v84, s[4:5]
	v_cndmask_b32_e64 v183, v183, v85, s[6:7]
	v_mul_f32_e32 v179, v235, v183
	v_fmac_f32_e32 v179, v228, v108
	v_fmac_f32_e32 v179, v229, v109
	v_fmac_f32_e32 v179, v230, v110
	v_fmac_f32_e32 v179, v231, v111
	ds_write_b32 v172, v179 offset:13312
	s_mov_b64 exec, s[40:41]
	ds_add_u32 v91, v92 offset:24
	s_mov_b64 exec, -1
	v_add_u32_e32 v170, 0x1080, v170
	v_add_u32_e32 v237, 0x1080, v237
	v_add_u32_e32 v95, 0x1080, v95
	s_waitcnt lgkmcnt(2)
	v_mfma_f32_16x16x4_f32 v[96:99], v22, v184, 0
	v_mfma_f32_16x16x4_f32 v[100:103], v23, v185, 0
	v_mfma_f32_16x16x4_f32 v[96:99], v24, v186, v[96:99]
	v_mfma_f32_16x16x4_f32 v[100:103], v25, v187, v[100:103]
	v_mul_f32_e32 v129, v132, v70
	v_mul_f32_e32 v130, v133, v71
	v_mul_f32_e32 v131, v134, v72
	v_mul_f32_e32 v153, v135, v73
	v_mfma_f32_16x16x4_f32 v[96:99], v26, v188, v[96:99]
	v_mfma_f32_16x16x4_f32 v[100:103], v27, v189, v[100:103]
	v_mfma_f32_16x16x4_f32 v[96:99], v28, v190, v[96:99]
	v_mfma_f32_16x16x4_f32 v[100:103], v29, v191, v[100:103]
	v_mul_f32_e64 v114, -v132, v136
	v_mul_f32_e64 v115, -v133, v137
	v_mul_f32_e64 v116, -v134, v138
	v_mul_f32_e64 v117, -v135, v139
	v_mfma_f32_16x16x4_f32 v[96:99], v30, v192, v[96:99]
	v_mfma_f32_16x16x4_f32 v[100:103], v31, v193, v[100:103]
	v_mfma_f32_16x16x4_f32 v[96:99], v32, v194, v[96:99]
	v_mfma_f32_16x16x4_f32 v[100:103], v33, v195, v[100:103]
	v_mul_f32_e32 v240, v238, v139
	v_rcp_f32_e32 v89, v240
	v_readfirstlane_b32 s0, v240
	ds_read_b32 v86, v87 offset:3584
	v_mfma_f32_16x16x4_f32 v[96:99], v34, v196, v[96:99]
	v_mfma_f32_16x16x4_f32 v[100:103], v35, v197, v[100:103]
	v_mfma_f32_16x16x4_f32 v[96:99], v36, v198, v[96:99]
	v_mfma_f32_16x16x4_f32 v[100:103], v37, v199, v[100:103]
	ds_read2_b32 v[62:63], v237 offset0:0 offset1:16
	ds_read2_b32 v[64:65], v237 offset0:32 offset1:48
	ds_read2_b32 v[66:67], v237 offset0:64 offset1:80
	ds_read2_b32 v[68:69], v237 offset0:96 offset1:112
	v_mfma_f32_16x16x4_f32 v[96:99], v38, v200, v[96:99]
	v_mfma_f32_16x16x4_f32 v[100:103], v39, v201, v[100:103]
	v_mfma_f32_16x16x4_f32 v[96:99], v40, v202, v[96:99]
	v_mfma_f32_16x16x4_f32 v[100:103], v41, v203, v[100:103]
	ds_read2st64_b32 v[74:75], v171 offset0:60 offset1:61
	ds_read2st64_b32 v[76:77], v171 offset0:62 offset1:63
	ds_read_b128 v[216:219], v175 offset:240
	ds_read_b128 v[220:223], v175 offset:496
	v_mfma_f32_16x16x4_f32 v[96:99], v42, v204, v[96:99]
	v_mfma_f32_16x16x4_f32 v[100:103], v43, v205, v[100:103]
	v_mfma_f32_16x16x4_f32 v[96:99], v44, v206, v[96:99]
	v_mfma_f32_16x16x4_f32 v[100:103], v45, v207, v[100:103]
	ds_read_b32 v235, v176 offset:496
	ds_read_b32 v236, v176 offset:752
	ds_read_b32 v234, v173 offset:3760
	ds_read_b64 v[232:233], v173 offset:3792
	v_mfma_f32_16x16x4_f32 v[96:99], v46, v208, v[96:99]
	v_mfma_f32_16x16x4_f32 v[100:103], v47, v209, v[100:103]
	v_mfma_f32_16x16x4_f32 v[96:99], v48, v210, v[96:99]
	v_mfma_f32_16x16x4_f32 v[100:103], v49, v211, v[100:103]
	ds_read_b128 v[224:227], v173 offset:3824
	ds_read_b128 v[228:231], v174 offset:3728
	v_mfma_f32_16x16x4_f32 v[96:99], v50, v212, v[96:99]
	v_mfma_f32_16x16x4_f32 v[100:103], v51, v213, v[100:103]
	v_mfma_f32_16x16x4_f32 v[96:99], v52, v214, v[96:99]
	v_mfma_f32_16x16x4_f32 v[100:103], v53, v215, v[100:103]
	s_nop 7
	s_nop 1
	v_pk_mul_f32 v[100:101], v[100:101], v[238:239] op_sel_hi:[1,0]
	v_pk_mul_f32 v[102:103], v[102:103], v[238:239] op_sel_hi:[1,0]
	v_pk_fma_f32 v[78:79], v[96:97], v[238:239], v[100:101] op_sel_hi:[1,0,1]
	v_pk_fma_f32 v[80:81], v[98:99], v[238:239], v[102:103] op_sel_hi:[1,0,1]
	v_pk_fma_f32 v[96:97], v[96:97], v[238:239], v[100:101] op_sel_hi:[1,0,1]
	v_pk_fma_f32 v[98:99], v[98:99], v[238:239], v[102:103] op_sel_hi:[1,0,1]
	s_nop 0
	v_permlane32_swap_b32_e32 v96, v78
	v_permlane32_swap_b32_e32 v97, v79
	v_permlane32_swap_b32_e32 v98, v80
	v_permlane32_swap_b32_e32 v99, v81
	v_mov_b32_e32 v82, v96
	v_mov_b32_e32 v83, v97
	v_mov_b32_e32 v84, v98
	v_mov_b32_e32 v85, v99
	s_nop 0
	v_permlane16_swap_b32_e32 v96, v82
	v_permlane16_swap_b32_e32 v97, v83
	v_permlane16_swap_b32_e32 v98, v84
	v_permlane16_swap_b32_e32 v99, v85
	v_fma_f32 v108, v114, v96, v129
	v_fma_f32 v109, v115, v97, v130
	v_fma_f32 v110, v116, v98, v131
	v_fma_f32 v111, v117, v99, v153
	v_fma_f32 v109, -v150, v108, v109
	v_fma_f32 v110, -v148, v108, v110
	v_fma_f32 v111, -v140, v108, v111
	v_fma_f32 v110, -v149, v109, v110
	v_fma_f32 v111, -v141, v109, v111
	v_fma_f32 v111, -v142, v110, v111
	v_cndmask_b32_e32 v182, v108, v109, vcc
	v_cndmask_b32_e64 v182, v182, v110, s[4:5]
	v_cndmask_b32_e64 v182, v182, v111, s[6:7]
	v_mul_f32_e32 v182, v152, v182
	s_cmp_lt_u32 s0, 0x2b800000
	s_cbranch_scc0 .Lgdn_nomat_7_0
	v_pk_mul_f32 v[184:185], v[184:185], v[240:241] op_sel_hi:[1,0]
	v_pk_mul_f32 v[186:187], v[186:187], v[240:241] op_sel_hi:[1,0]
	v_pk_mul_f32 v[188:189], v[188:189], v[240:241] op_sel_hi:[1,0]
	v_pk_mul_f32 v[190:191], v[190:191], v[240:241] op_sel_hi:[1,0]
	v_pk_mul_f32 v[192:193], v[192:193], v[240:241] op_sel_hi:[1,0]
	v_pk_mul_f32 v[194:195], v[194:195], v[240:241] op_sel_hi:[1,0]
	v_pk_mul_f32 v[196:197], v[196:197], v[240:241] op_sel_hi:[1,0]
	v_pk_mul_f32 v[198:199], v[198:199], v[240:241] op_sel_hi:[1,0]
	v_pk_mul_f32 v[200:201], v[200:201], v[240:241] op_sel_hi:[1,0]
	v_pk_mul_f32 v[202:203], v[202:203], v[240:241] op_sel_hi:[1,0]
	v_pk_mul_f32 v[204:205], v[204:205], v[240:241] op_sel_hi:[1,0]
	v_pk_mul_f32 v[206:207], v[206:207], v[240:241] op_sel_hi:[1,0]
	v_pk_mul_f32 v[208:209], v[208:209], v[240:241] op_sel_hi:[1,0]
	v_pk_mul_f32 v[210:211], v[210:211], v[240:241] op_sel_hi:[1,0]
	v_pk_mul_f32 v[212:213], v[212:213], v[240:241] op_sel_hi:[1,0]
	v_pk_mul_f32 v[214:215], v[214:215], v[240:241] op_sel_hi:[1,0]
	v_mov_b32_e32 v240, 1.0
	v_mov_b32_e32 v89, 1.0

.Lgdn_nomat_7_1:
	v_mov_b32_e32 v238, v240
	v_mul_f32_e32 v90, v182, v89
	s_nop 1
	v_mfma_f32_16x16x4_f32 v[184:187], v62, v90, v[184:187]
	v_mfma_f32_16x16x4_f32 v[188:191], v63, v90, v[188:191]
	v_mfma_f32_16x16x4_f32 v[192:195], v64, v90, v[192:195]
	v_mfma_f32_16x16x4_f32 v[196:199], v65, v90, v[196:199]
	v_mfma_f32_16x16x4_f32 v[200:203], v66, v90, v[200:203]
	v_mfma_f32_16x16x4_f32 v[204:207], v67, v90, v[204:207]
	v_mfma_f32_16x16x4_f32 v[208:211], v68, v90, v[208:211]
	v_mfma_f32_16x16x4_f32 v[212:215], v69, v90, v[212:215]
	v_cndmask_b32_e32 v183, v82, v83, vcc
	v_cndmask_b32_e64 v183, v183, v84, s[4:5]
	v_cndmask_b32_e64 v183, v183, v85, s[6:7]
	v_mul_f32_e32 v179, v235, v183
	v_fmac_f32_e32 v179, v228, v108
	v_fmac_f32_e32 v179, v229, v109
	v_fmac_f32_e32 v179, v230, v110
	v_fmac_f32_e32 v179, v231, v111
	ds_write_b32 v172, v179 offset:15360
	s_mov_b64 exec, s[40:41]
	ds_add_u32 v91, v92 offset:28
	s_mov_b64 exec, -1
	s_branch .Lgdn_done
.Lgdn_out:
	v_and_b32_e32 v166, 63, v180
	v_lshrrev_b32_e32 v167, 6, v180
	v_subrev_u32_e32 v167, 4, v167
	v_lshlrev_b32_e32 v169, 2, v166
	v_lshl_add_u32 v168, v167, 9, v169
	v_add_u32_e32 v168, 0x1d800, v168
	v_lshl_add_u32 v169, v167, 12, v169
	v_mov_b32_e32 v172, 0x15800
	s_lshl_b32 s0, s72, 11
	s_add_u32 s4, s10, s0
	s_addc_u32 s5, s11, 0
	s_lshl_b32 s3, s17, 2
	s_add_u32 s3, s3, 4
.Lgdn_poll_0:
	ds_read_b32 v173, v172 offset:0
	s_waitcnt lgkmcnt(0)
	v_readfirstlane_b32 s1, v173
	s_cmp_ge_u32 s1, s3
	s_cbranch_scc1 .Lgdn_go_0
	s_sleep 2
	s_branch .Lgdn_poll_0
.Lgdn_go_0:
	ds_read_b32 v170, v168 offset:0
	ds_read_b32 v171, v168 offset:256
	s_waitcnt lgkmcnt(0)
	global_store_dword v169, v170, s[4:5]
	global_store_dword v169, v171, s[4:5] offset:2048
	s_add_u32 s4, s4, 0x4000
	s_addc_u32 s5, s5, 0
.Lgdn_poll_1:
	ds_read_b32 v173, v172 offset:4
	s_waitcnt lgkmcnt(0)
	v_readfirstlane_b32 s1, v173
	s_cmp_ge_u32 s1, s3
	s_cbranch_scc1 .Lgdn_go_1
	s_sleep 2
	s_branch .Lgdn_poll_1
.Lgdn_go_1:
	ds_read_b32 v170, v168 offset:2048
	ds_read_b32 v171, v168 offset:2304
	s_waitcnt lgkmcnt(0)
	global_store_dword v169, v170, s[4:5]
	global_store_dword v169, v171, s[4:5] offset:2048
	s_add_u32 s4, s4, 0x4000
	s_addc_u32 s5, s5, 0
.Lgdn_poll_2:
	ds_read_b32 v173, v172 offset:8
	s_waitcnt lgkmcnt(0)
	v_readfirstlane_b32 s1, v173
	s_cmp_ge_u32 s1, s3
	s_cbranch_scc1 .Lgdn_go_2
	s_sleep 2
	s_branch .Lgdn_poll_2
.Lgdn_go_2:
	ds_read_b32 v170, v168 offset:4096
	ds_read_b32 v171, v168 offset:4352
	s_waitcnt lgkmcnt(0)
	global_store_dword v169, v170, s[4:5]
	global_store_dword v169, v171, s[4:5] offset:2048
	s_add_u32 s4, s4, 0x4000
	s_addc_u32 s5, s5, 0
.Lgdn_poll_3:
	ds_read_b32 v173, v172 offset:12
	s_waitcnt lgkmcnt(0)
	v_readfirstlane_b32 s1, v173
	s_cmp_ge_u32 s1, s3
	s_cbranch_scc1 .Lgdn_go_3
	s_sleep 2
	s_branch .Lgdn_poll_3
.Lgdn_go_3:
	ds_read_b32 v170, v168 offset:6144
	ds_read_b32 v171, v168 offset:6400
	s_waitcnt lgkmcnt(0)
	global_store_dword v169, v170, s[4:5]
	global_store_dword v169, v171, s[4:5] offset:2048
	s_add_u32 s4, s4, 0x4000
	s_addc_u32 s5, s5, 0
.Lgdn_poll_4:
	ds_read_b32 v173, v172 offset:16
	s_waitcnt lgkmcnt(0)
	v_readfirstlane_b32 s1, v173
	s_cmp_ge_u32 s1, s3
	s_cbranch_scc1 .Lgdn_go_4
	s_sleep 2
	s_branch .Lgdn_poll_4
.Lgdn_go_4:
	ds_read_b32 v170, v168 offset:8192
	ds_read_b32 v171, v168 offset:8448
	s_waitcnt lgkmcnt(0)
	global_store_dword v169, v170, s[4:5]
	global_store_dword v169, v171, s[4:5] offset:2048
	s_add_u32 s4, s4, 0x4000
	s_addc_u32 s5, s5, 0
.Lgdn_poll_5:
	ds_read_b32 v173, v172 offset:20
	s_waitcnt lgkmcnt(0)
	v_readfirstlane_b32 s1, v173
	s_cmp_ge_u32 s1, s3
	s_cbranch_scc1 .Lgdn_go_5
	s_sleep 2
	s_branch .Lgdn_poll_5
.Lgdn_go_5:
	ds_read_b32 v170, v168 offset:10240
	ds_read_b32 v171, v168 offset:10496
	s_waitcnt lgkmcnt(0)
	global_store_dword v169, v170, s[4:5]
	global_store_dword v169, v171, s[4:5] offset:2048
	s_add_u32 s4, s4, 0x4000
	s_addc_u32 s5, s5, 0
.Lgdn_poll_6:
	ds_read_b32 v173, v172 offset:24
	s_waitcnt lgkmcnt(0)
	v_readfirstlane_b32 s1, v173
	s_cmp_ge_u32 s1, s3
	s_cbranch_scc1 .Lgdn_go_6
	s_sleep 2
	s_branch .Lgdn_poll_6
.Lgdn_go_6:
	ds_read_b32 v170, v168 offset:12288
	ds_read_b32 v171, v168 offset:12544
	s_waitcnt lgkmcnt(0)
	global_store_dword v169, v170, s[4:5]
	global_store_dword v169, v171, s[4:5] offset:2048
	s_add_u32 s4, s4, 0x4000
	s_addc_u32 s5, s5, 0
.Lgdn_poll_7:
	ds_read_b32 v173, v172 offset:28
	s_waitcnt lgkmcnt(0)
	v_readfirstlane_b32 s1, v173
	s_cmp_ge_u32 s1, s3
	s_cbranch_scc1 .Lgdn_go_7
	s_sleep 2
	s_branch .Lgdn_poll_7
.Lgdn_go_7:
	ds_read_b32 v170, v168 offset:14336
	ds_read_b32 v171, v168 offset:14592
	s_waitcnt lgkmcnt(0)
	global_store_dword v169, v170, s[4:5]
	global_store_dword v169, v171, s[4:5] offset:2048
	s_add_u32 s4, s4, 0x4000
	s_addc_u32 s5, s5, 0
.Lgdn_done:
	v_cmp_gt_i32_e32 vcc, s88, v112
	s_waitcnt lgkmcnt(0)
	s_barrier
	s_mov_b64 s[0:1], exec
	s_branch .LBB0_536

.LBB0_563:
	s_or_b64 exec, exec, s[0:1]
	v_lshlrev_b64 v[2:3], 9, v[2:3]
	v_mov_b32_e32 v7, v94
	v_or_b32_e32 v2, v2, v1
	v_lshl_add_u64 v[4:5], v[4:5], 0, v[6:7]
	v_lshl_add_u64 v[8:9], v[2:3], 2, s[34:35]
	v_lshl_add_u64 v[6:7], v[2:3], 1, s[62:63]
	s_waitcnt vmcnt(4)
	v_lshl_add_u64 v[10:11], v[4:5], 0, s[76:77]
	global_load_dword v107, v[8:9], off
	global_load_ushort v18, v[4:5], off
	global_load_ushort v1, v[4:5], off offset:3072
	global_load_ushort v19, v[10:11], off offset:1024
	global_load_ushort v20, v[4:5], off offset:1024
	global_load_ushort v21, v[10:11], off offset:2048
	global_load_ushort v22, v[6:7], off
	global_load_ushort v23, v[4:5], off offset:2048
	v_or_b32_e32 v4, 0x200, v2
	v_mov_b32_e32 v5, v3
	v_lshl_add_u64 v[6:7], v[4:5], 1, s[62:63]
	v_lshl_add_u64 v[4:5], v[4:5], 2, s[34:35]
	v_or_b32_e32 v12, 0x400, v2
	v_mov_b32_e32 v13, v3
	v_lshl_add_u64 v[8:9], v[10:11], 0, s[76:77]
	s_waitcnt vmcnt(11)
	v_lshl_add_u64 v[14:15], v[12:13], 1, s[62:63]
	v_lshl_add_u64 v[12:13], v[12:13], 2, s[34:35]
	global_load_ushort v24, v[6:7], off
	global_load_dword v108, v[4:5], off
	global_load_ushort v25, v[8:9], off offset:3072
	global_load_ushort v26, v[8:9], off offset:1024
	global_load_ushort v27, v[14:15], off
	global_load_dword v109, v[12:13], off
	global_load_ushort v28, v[8:9], off offset:2048
	global_load_ushort v29, v[10:11], off offset:3072
	v_or_b32_e32 v4, 0x600, v2
	v_mov_b32_e32 v5, v3
	v_lshl_add_u64 v[16:17], v[8:9], 0, s[76:77]
	v_lshl_add_u64 v[6:7], v[4:5], 1, s[62:63]
	v_lshl_add_u64 v[4:5], v[4:5], 2, s[34:35]
	v_lshl_add_u64 v[8:9], v[16:17], 0, s[76:77]
	global_load_ushort v30, v[16:17], off offset:1024
	global_load_ushort v31, v[16:17], off offset:2048
	global_load_ushort v32, v[6:7], off
	global_load_dword v110, v[4:5], off
	global_load_ushort v33, v[8:9], off offset:3072
	global_load_ushort v36, v[8:9], off offset:1024
	global_load_ushort v37, v[8:9], off offset:2048
	s_nop 0
	global_load_ushort v16, v[16:17], off offset:3072
	v_or_b32_e32 v4, 0xa00, v2
	v_mov_b32_e32 v5, v3
	v_or_b32_e32 v10, 0x800, v2
	v_mov_b32_e32 v11, v3
	v_lshl_add_u64 v[14:15], v[8:9], 0, s[76:77]
	v_lshl_add_u64 v[6:7], v[4:5], 1, s[62:63]
	v_lshl_add_u64 v[4:5], v[4:5], 2, s[34:35]
	v_lshl_add_u64 v[12:13], v[10:11], 1, s[62:63]
	global_load_ushort v17, v[14:15], off offset:1024
	global_load_ushort v38, v[14:15], off offset:2048
	global_load_ushort v39, v[6:7], off
	global_load_dword v112, v[4:5], off
	global_load_ushort v40, v[14:15], off offset:3072
	global_load_ushort v41, v[12:13], off
	v_lshl_add_u64 v[4:5], v[14:15], 0, s[76:77]
	v_or_b32_e32 v6, 0xc00, v2
	v_mov_b32_e32 v7, v3
	v_lshl_add_u64 v[12:13], v[4:5], 0, s[76:77]
	v_or_b32_e32 v2, 0xe00, v2
	v_lshl_add_u64 v[8:9], v[6:7], 1, s[62:63]
	global_load_ushort v14, v[12:13], off offset:1024
	s_nop 0
	global_load_ushort v12, v[12:13], off offset:2048
	s_nop 0
	global_load_ushort v13, v[4:5], off offset:3072
	global_load_ushort v15, v[4:5], off offset:1024
	global_load_ushort v42, v[4:5], off offset:2048
	v_lshl_add_u64 v[4:5], v[2:3], 1, s[62:63]
	global_load_ushort v43, v[4:5], off
	s_nop 0
	global_load_ushort v8, v[8:9], off
	v_lshl_add_u64 v[4:5], v[6:7], 2, s[34:35]
	v_lshl_add_u64 v[2:3], v[2:3], 2, s[34:35]
	v_lshl_add_u64 v[10:11], v[10:11], 2, s[34:35]
	global_load_dword v113, v[4:5], off
	global_load_dword v114, v[2:3], off
	global_load_dword v111, v[10:11], off
	s_waitcnt vmcnt(38)
	v_lshlrev_b32_e32 v44, 16, v18
	s_waitcnt vmcnt(37)
	v_lshlrev_b32_e32 v1, 16, v1
	s_waitcnt vmcnt(36)
	v_lshlrev_b32_e32 v45, 16, v19
	s_waitcnt vmcnt(35)
	v_lshlrev_b32_e32 v46, 16, v20
	s_waitcnt vmcnt(34)
	v_lshlrev_b32_e32 v47, 16, v21
	s_waitcnt vmcnt(33)
	v_lshlrev_b32_e32 v50, 16, v22
	s_waitcnt vmcnt(32)
	v_lshlrev_b32_e32 v48, 16, v23
	s_waitcnt vmcnt(31)
	v_lshlrev_b32_e32 v51, 16, v24
	s_waitcnt vmcnt(29)
	v_lshlrev_b32_e32 v49, 16, v25
	s_waitcnt vmcnt(28)
	v_lshlrev_b32_e32 v54, 16, v26
	s_waitcnt vmcnt(27)
	v_lshlrev_b32_e32 v58, 16, v27
	s_waitcnt vmcnt(25)
	v_lshlrev_b32_e32 v56, 16, v28
	s_waitcnt vmcnt(24)
	v_lshlrev_b32_e32 v52, 16, v29
	s_waitcnt vmcnt(23)
	v_lshlrev_b32_e32 v53, 16, v30
	s_waitcnt vmcnt(22)
	v_lshlrev_b32_e32 v55, 16, v31
	s_waitcnt vmcnt(21)
	v_lshlrev_b32_e32 v57, 16, v32
	s_waitcnt vmcnt(19)
	v_lshlrev_b32_e32 v59, 16, v33
	s_waitcnt vmcnt(18)
	v_lshlrev_b32_e32 v62, 16, v36
	s_waitcnt vmcnt(17)
	v_lshlrev_b32_e32 v64, 16, v37
	s_waitcnt vmcnt(16)
	v_lshlrev_b32_e32 v60, 16, v16
	v_mov_b64_e32 v[36:37], v[94:95]
	s_waitcnt vmcnt(15)
	v_lshlrev_b32_e32 v61, 16, v17
	s_waitcnt vmcnt(14)
	v_lshlrev_b32_e32 v63, 16, v38
	s_waitcnt vmcnt(13)
	v_lshlrev_b32_e32 v65, 16, v39
	v_mov_b64_e32 v[38:39], v[94:95]
	s_waitcnt vmcnt(11)
	v_lshlrev_b32_e32 v67, 16, v40
	s_waitcnt vmcnt(10)
	v_lshlrev_b32_e32 v66, 16, v41
	v_mov_b64_e32 v[40:41], v[94:95]
	s_waitcnt vmcnt(9)
	v_lshlrev_b32_e32 v70, 16, v14
	s_waitcnt vmcnt(8)
	v_lshlrev_b32_e32 v72, 16, v12
	s_waitcnt vmcnt(7)
	v_lshlrev_b32_e32 v68, 16, v13
	s_waitcnt vmcnt(6)
	v_lshlrev_b32_e32 v69, 16, v15
	s_waitcnt vmcnt(5)
	v_lshlrev_b32_e32 v71, 16, v42
	s_waitcnt vmcnt(4)
	v_lshlrev_b32_e32 v73, 16, v43
	s_waitcnt vmcnt(3)
	v_lshlrev_b32_e32 v74, 16, v8
	v_mov_b64_e32 v[42:43], v[94:95]
	v_mov_b32_e32 v224, 0
	v_mov_b32_e32 v225, 0
	v_mov_b32_e32 v226, 0
	v_mov_b32_e32 v227, 0
	v_mov_b32_e32 v228, 0
	v_mov_b32_e32 v229, 0
	v_mov_b32_e32 v230, 0
	v_mov_b32_e32 v231, 0
	v_mov_b32_e32 v232, 0
	v_mov_b32_e32 v233, 0
	v_mov_b32_e32 v234, 0
	v_mov_b32_e32 v235, 0
	v_mov_b32_e32 v236, 0
	v_mov_b32_e32 v237, 0
	v_mov_b32_e32 v238, 0
	v_mov_b32_e32 v239, 0
	v_mov_b32_e32 v179, 0x27f00
	ds_write_b32 v179, v224 offset:0
	ds_write_b32 v179, v224 offset:4
	ds_write_b32 v179, v224 offset:8
	ds_write_b32 v179, v224 offset:12
	ds_write_b32 v179, v224 offset:16
	ds_write_b32 v179, v224 offset:20
	ds_write_b32 v179, v224 offset:24
	ds_write_b32 v179, v224 offset:28

.LBB0_586:
.Lrw_entry:
	v_readfirstlane_b32 s0, v180
	s_nop 1
	s_cmpk_ge_u32 s0, 0x100
	s_cbranch_scc1 .Lrw_epi
	v_and_b32_e32 v222, 15, v180
	v_bfe_u32 v223, v180, 4, 2
	v_lshrrev_b32_e32 v240, 6, v180
	v_and_b32_e32 v176, 7, v222
	v_mul_u32_u24_e32 v176, 0x110, v176
	v_and_b32_e32 v177, 8, v222
	v_mul_u32_u24_e32 v177, 0x880, v177
	v_lshl_add_u32 v168, v223, 4, v176
	v_add_u32_e32 v168, v168, v177
	v_lshlrev_b32_e32 v178, 6, v240
	v_lshl_add_u32 v178, v222, 2, v178
	v_lshl_add_u32 v169, v223, 8, v178
	v_add_u32_e32 v169, s41, v169
	v_lshl_add_u32 v175, v223, 10, v178
	v_add_u32_e32 v175, 0x1f000, v175
	v_mov_b32_e32 v170, 0x15800
	v_lshlrev_b32_e32 v176, 5, v222
	v_lshl_add_u32 v176, v223, 2, v176
	v_and_b32_e32 v177, 8, v222
	v_lshl_add_u32 v172, v177, 5, v176
	v_add_u32_e32 v171, 0x15900, v172
	v_add_u32_e32 v172, 0x15800, v172
	v_mul_u32_u24_e32 v176, 0x110, v223
	v_lshl_add_u32 v173, v222, 2, v176
	v_add_u32_e32 v173, 0x8800, v173
	v_add_u32_e32 v2, 0x440, v173
	v_add_u32_e32 v3, 0x4400, v173
	v_add_u32_e32 v5, 0x4840, v173
	v_lshlrev_b32_e32 v174, 4, v223
	v_add_u32_e32 v174, 0x11000, v174
	v_cmp_eq_u32_e32 vcc, 1, v223
	v_cmp_eq_u32_e64 s[4:5], 2, v223
	v_cmp_eq_u32_e64 s[6:7], 3, v223
	s_mov_b32 s8, 0
	s_mov_b32 s9, -1
	s_mov_b32 s14, 0
	s_mov_b32 s15, 1
	v_mov_b32_e32 v179, 0x27f00
	v_mov_b32_e32 v241, 1
	v_mov_b32_e32 v198, 1.0
	v_mov_b32_e32 v199, 1.0
	v_mov_b32_e32 v200, 1.0
	v_mov_b32_e32 v201, 1.0
	v_mov_b32_e32 v202, 1.0
	v_mov_b32_e32 v203, 1.0
	v_mov_b32_e32 v204, 1.0
	v_mov_b32_e32 v205, 1.0
	v_mov_b32_e32 v206, 1.0
	v_mov_b32_e32 v207, 1.0
	v_mov_b32_e32 v208, 1.0
	v_mov_b32_e32 v209, 1.0
	v_mov_b32_e32 v210, 1.0
	v_mov_b32_e32 v211, 1.0
	v_mov_b32_e32 v212, 1.0
	v_mov_b32_e32 v213, 1.0
	ds_read_b128 v[44:47], v168 offset:0
	ds_read_b128 v[48:51], v168 offset:64
	ds_read_b128 v[68:71], v168 offset:128
	ds_read_b128 v[96:99], v168 offset:192
	ds_read_b32 v216, v171 offset:0
	ds_read_b32 v217, v171 offset:16
	ds_read_b32 v214, v169 offset:0
	ds_read_b32 v215, v169 offset:1024
	ds_read_b128 v[124:127], v170 offset:32
	ds_read_b128 v[128:131], v170 offset:64
	ds_read_b128 v[132:135], v170 offset:96
	ds_read_b128 v[136:139], v170 offset:128
	ds_read_b128 v[144:147], v170 offset:160
	ds_read_b128 v[148:151], v170 offset:176
	ds_read_b128 v[152:155], v170 offset:192
	ds_read_b128 v[156:159], v170 offset:208
	ds_read_b128 v[160:163], v170 offset:224
	ds_read_b128 v[164:167], v170 offset:240
	ds_read_b32 v218, v172 offset:0
	ds_read_b32 v219, v172 offset:16
	ds_read2_b32 v[182:183], v173 offset0:0 offset1:16
	ds_read2_b32 v[184:185], v173 offset0:32 offset1:48
	ds_read2_b32 v[186:187], v2 offset0:0 offset1:16
	ds_read2_b32 v[188:189], v2 offset0:32 offset1:48
	ds_read2_b32 v[190:191], v3 offset0:0 offset1:16
	ds_read2_b32 v[192:193], v3 offset0:32 offset1:48
	ds_read2_b32 v[194:195], v5 offset0:0 offset1:16
	ds_read2_b32 v[196:197], v5 offset0:32 offset1:48
	s_mov_b32 s1, 0
	s_waitcnt lgkmcnt(0)
	s_waitcnt lgkmcnt(4)
	v_pk_mul_f32 v[224:225], v[224:225], v[198:199]
	v_pk_mul_f32 v[226:227], v[226:227], v[200:201]
	v_pk_mul_f32 v[228:229], v[228:229], v[202:203]
	v_pk_mul_f32 v[230:231], v[230:231], v[204:205]
	v_mfma_f32_16x16x4_f32 v[36:39], v44, v224, 0
	v_mfma_f32_16x16x4_f32 v[40:43], v45, v225, 0
	v_mfma_f32_16x16x4_f32 v[36:39], v46, v226, v[36:39]
	v_mfma_f32_16x16x4_f32 v[40:43], v47, v227, v[40:43]
	v_pk_mul_f32 v[232:233], v[232:233], v[206:207]
	v_pk_mul_f32 v[234:235], v[234:235], v[208:209]
	v_mfma_f32_16x16x4_f32 v[36:39], v48, v228, v[36:39]
	v_mfma_f32_16x16x4_f32 v[40:43], v49, v229, v[40:43]
	v_mfma_f32_16x16x4_f32 v[36:39], v50, v230, v[36:39]
	v_mfma_f32_16x16x4_f32 v[40:43], v51, v231, v[40:43]
	v_pk_mul_f32 v[236:237], v[236:237], v[210:211]
	v_pk_mul_f32 v[238:239], v[238:239], v[212:213]
	v_mfma_f32_16x16x4_f32 v[36:39], v68, v232, v[36:39]
	v_mfma_f32_16x16x4_f32 v[40:43], v69, v233, v[40:43]
	v_mfma_f32_16x16x4_f32 v[36:39], v70, v234, v[36:39]
	v_mfma_f32_16x16x4_f32 v[40:43], v71, v235, v[40:43]
	v_mfma_f32_16x16x4_f32 v[36:39], v96, v236, v[36:39]
	v_mfma_f32_16x16x4_f32 v[40:43], v97, v237, v[40:43]
	v_mfma_f32_16x16x4_f32 v[36:39], v98, v238, v[36:39]
	v_mfma_f32_16x16x4_f32 v[40:43], v99, v239, v[40:43]
	v_mfma_f32_16x16x4_f32 v[36:39], v216, v214, v[36:39]
	v_mfma_f32_16x16x4_f32 v[40:43], v217, v215, v[40:43]
	ds_read_b128 v[44:47], v168 offset:2176
	ds_read_b128 v[48:51], v168 offset:2240
	ds_read_b128 v[68:71], v168 offset:2304
	ds_read_b128 v[96:99], v168 offset:2368
	ds_read_b32 v216, v171 offset:1024
	ds_read_b32 v217, v171 offset:1040
	ds_read_b128 v[198:201], v174 offset:0
	ds_read_b128 v[202:205], v174 offset:64
	ds_read_b128 v[206:209], v174 offset:128
	ds_read_b128 v[210:213], v174 offset:192
	v_mfma_f32_16x16x4_f32 v[224:227], v190, v214, v[224:227]
	v_mfma_f32_16x16x4_f32 v[224:227], v194, v215, v[224:227]
	v_mfma_f32_16x16x4_f32 v[228:231], v191, v214, v[228:231]
	v_mfma_f32_16x16x4_f32 v[228:231], v195, v215, v[228:231]
	v_mfma_f32_16x16x4_f32 v[232:235], v192, v214, v[232:235]
	v_mfma_f32_16x16x4_f32 v[232:235], v196, v215, v[232:235]
	v_mfma_f32_16x16x4_f32 v[236:239], v193, v214, v[236:239]
	v_mfma_f32_16x16x4_f32 v[236:239], v197, v215, v[236:239]
	ds_read_b32 v214, v169 offset:2048
	ds_read_b32 v215, v169 offset:3072
	v_pk_add_f32 v[80:81], v[36:37], v[40:41]
	v_pk_add_f32 v[82:83], v[38:39], v[42:43]
	v_pk_add_f32 v[84:85], v[36:37], v[40:41]
	v_pk_add_f32 v[86:87], v[38:39], v[42:43]
	v_pk_add_f32 v[36:37], v[36:37], v[40:41]
	v_pk_add_f32 v[38:39], v[38:39], v[42:43]
	v_permlane32_swap_b32_e32 v80, v84
	v_permlane32_swap_b32_e32 v81, v85
	v_permlane32_swap_b32_e32 v82, v86
	v_permlane32_swap_b32_e32 v83, v87
	v_mov_b32_e32 v88, v80
	v_mov_b32_e32 v89, v81
	v_mov_b32_e32 v90, v82
	v_mov_b32_e32 v91, v83
	s_nop 0
	v_permlane16_swap_b32_e32 v80, v88
	v_permlane16_swap_b32_e32 v81, v89
	v_permlane16_swap_b32_e32 v82, v90
	v_permlane16_swap_b32_e32 v83, v91
	v_fmac_f32_e32 v81, v124, v80
	v_fmac_f32_e32 v82, v128, v80
	v_fmac_f32_e32 v83, v132, v80
	v_fmac_f32_e32 v88, v136, v80
	v_fmac_f32_e32 v89, v144, v80
	v_fmac_f32_e32 v90, v152, v80
	v_fmac_f32_e32 v91, v160, v80
	v_fmac_f32_e32 v82, v129, v81
	v_fmac_f32_e32 v83, v133, v81
	v_fmac_f32_e32 v88, v137, v81
	v_fmac_f32_e32 v89, v145, v81
	v_fmac_f32_e32 v90, v153, v81
	v_fmac_f32_e32 v91, v161, v81
	v_fmac_f32_e32 v83, v134, v82
	v_fmac_f32_e32 v88, v138, v82
	v_fmac_f32_e32 v89, v146, v82
	v_fmac_f32_e32 v90, v154, v82
	v_fmac_f32_e32 v91, v162, v82
	v_fmac_f32_e32 v88, v139, v83
	v_fmac_f32_e32 v89, v147, v83
	v_fmac_f32_e32 v90, v155, v83
	v_fmac_f32_e32 v91, v163, v83
	v_fmac_f32_e32 v89, v148, v88
	v_fmac_f32_e32 v90, v156, v88
	v_fmac_f32_e32 v91, v164, v88
	v_fmac_f32_e32 v90, v157, v89
	v_fmac_f32_e32 v91, v165, v89
	v_fmac_f32_e32 v91, v166, v90
	ds_read_b128 v[124:127], v170 offset:1056
	ds_read_b128 v[128:131], v170 offset:1088
	ds_read_b128 v[132:135], v170 offset:1120
	ds_read_b128 v[136:139], v170 offset:1152
	ds_read_b128 v[144:147], v170 offset:1184
	ds_read_b128 v[148:151], v170 offset:1200
	ds_read_b128 v[152:155], v170 offset:1216
	ds_read_b128 v[156:159], v170 offset:1232
	ds_read_b128 v[160:163], v170 offset:1248
	ds_read_b128 v[164:167], v170 offset:1264
	v_cndmask_b32_e32 v220, v80, v81, vcc
	v_cndmask_b32_e64 v220, v220, v82, s[4:5]
	v_cndmask_b32_e64 v220, v220, v83, s[6:7]
	v_cndmask_b32_e32 v221, v88, v89, vcc
	v_cndmask_b32_e64 v221, v221, v90, s[4:5]
	v_cndmask_b32_e64 v221, v221, v91, s[6:7]
	s_nop 1
	v_mfma_f32_16x16x4_f32 v[84:87], v218, v220, v[36:39]
	v_mfma_f32_16x16x4_f32 v[84:87], v219, v221, v[84:87]
	ds_read_b32 v218, v172 offset:1024
	ds_read_b32 v219, v172 offset:1040
	v_mfma_f32_16x16x4_f32 v[224:227], v182, v220, v[224:227]
	v_mfma_f32_16x16x4_f32 v[224:227], v186, v221, v[224:227]
	v_mfma_f32_16x16x4_f32 v[228:231], v183, v220, v[228:231]
	v_mfma_f32_16x16x4_f32 v[228:231], v187, v221, v[228:231]
	v_mfma_f32_16x16x4_f32 v[232:235], v184, v220, v[232:235]
	v_mfma_f32_16x16x4_f32 v[232:235], v188, v221, v[232:235]
	v_mfma_f32_16x16x4_f32 v[236:239], v185, v220, v[236:239]
	v_mfma_f32_16x16x4_f32 v[236:239], v189, v221, v[236:239]
	v_add_u32_e32 v173, 0x880, v173
	v_add_u32_e32 v2, 0x880, v2
	v_add_u32_e32 v3, 0x880, v3
	v_add_u32_e32 v5, 0x880, v5
	ds_read2_b32 v[182:183], v173 offset0:0 offset1:16
	ds_read2_b32 v[184:185], v173 offset0:32 offset1:48
	ds_read2_b32 v[186:187], v2 offset0:0 offset1:16
	ds_read2_b32 v[188:189], v2 offset0:32 offset1:48
	ds_read2_b32 v[190:191], v3 offset0:0 offset1:16
	ds_read2_b32 v[192:193], v3 offset0:32 offset1:48
	ds_read2_b32 v[194:195], v5 offset0:0 offset1:16
	ds_read2_b32 v[196:197], v5 offset0:32 offset1:48
	s_mov_b64 exec, s[8:9]
	ds_write_b32 v175, v84 offset:0
	ds_write_b32 v175, v85 offset:256
	ds_write_b32 v175, v86 offset:512
	ds_write_b32 v175, v87 offset:768
	s_mov_b64 exec, s[14:15]
	ds_add_u32 v179, v241 offset:0
	s_mov_b64 exec, -1
	s_waitcnt lgkmcnt(4)
	v_pk_mul_f32 v[224:225], v[224:225], v[198:199]
	v_pk_mul_f32 v[226:227], v[226:227], v[200:201]
	v_pk_mul_f32 v[228:229], v[228:229], v[202:203]
	v_pk_mul_f32 v[230:231], v[230:231], v[204:205]
	v_mfma_f32_16x16x4_f32 v[36:39], v44, v224, 0
	v_mfma_f32_16x16x4_f32 v[40:43], v45, v225, 0
	v_mfma_f32_16x16x4_f32 v[36:39], v46, v226, v[36:39]
	v_mfma_f32_16x16x4_f32 v[40:43], v47, v227, v[40:43]
	v_pk_mul_f32 v[232:233], v[232:233], v[206:207]
	v_pk_mul_f32 v[234:235], v[234:235], v[208:209]
	v_mfma_f32_16x16x4_f32 v[36:39], v48, v228, v[36:39]
	v_mfma_f32_16x16x4_f32 v[40:43], v49, v229, v[40:43]
	v_mfma_f32_16x16x4_f32 v[36:39], v50, v230, v[36:39]
	v_mfma_f32_16x16x4_f32 v[40:43], v51, v231, v[40:43]
	v_pk_mul_f32 v[236:237], v[236:237], v[210:211]
	v_pk_mul_f32 v[238:239], v[238:239], v[212:213]
	v_mfma_f32_16x16x4_f32 v[36:39], v68, v232, v[36:39]
	v_mfma_f32_16x16x4_f32 v[40:43], v69, v233, v[40:43]
	v_mfma_f32_16x16x4_f32 v[36:39], v70, v234, v[36:39]
	v_mfma_f32_16x16x4_f32 v[40:43], v71, v235, v[40:43]
	v_mfma_f32_16x16x4_f32 v[36:39], v96, v236, v[36:39]
	v_mfma_f32_16x16x4_f32 v[40:43], v97, v237, v[40:43]
	v_mfma_f32_16x16x4_f32 v[36:39], v98, v238, v[36:39]
	v_mfma_f32_16x16x4_f32 v[40:43], v99, v239, v[40:43]
	v_mfma_f32_16x16x4_f32 v[36:39], v216, v214, v[36:39]
	v_mfma_f32_16x16x4_f32 v[40:43], v217, v215, v[40:43]
	ds_read_b128 v[44:47], v168 offset:4352
	ds_read_b128 v[48:51], v168 offset:4416
	ds_read_b128 v[68:71], v168 offset:4480
	ds_read_b128 v[96:99], v168 offset:4544
	ds_read_b32 v216, v171 offset:2048
	ds_read_b32 v217, v171 offset:2064
	ds_read_b128 v[198:201], v174 offset:256
	ds_read_b128 v[202:205], v174 offset:320
	ds_read_b128 v[206:209], v174 offset:384
	ds_read_b128 v[210:213], v174 offset:448
	v_mfma_f32_16x16x4_f32 v[224:227], v190, v214, v[224:227]
	v_mfma_f32_16x16x4_f32 v[224:227], v194, v215, v[224:227]
	v_mfma_f32_16x16x4_f32 v[228:231], v191, v214, v[228:231]
	v_mfma_f32_16x16x4_f32 v[228:231], v195, v215, v[228:231]
	v_mfma_f32_16x16x4_f32 v[232:235], v192, v214, v[232:235]
	v_mfma_f32_16x16x4_f32 v[232:235], v196, v215, v[232:235]
	v_mfma_f32_16x16x4_f32 v[236:239], v193, v214, v[236:239]
	v_mfma_f32_16x16x4_f32 v[236:239], v197, v215, v[236:239]
	ds_read_b32 v214, v169 offset:4096
	ds_read_b32 v215, v169 offset:5120
	v_pk_add_f32 v[80:81], v[36:37], v[40:41]
	v_pk_add_f32 v[82:83], v[38:39], v[42:43]
	v_pk_add_f32 v[84:85], v[36:37], v[40:41]
	v_pk_add_f32 v[86:87], v[38:39], v[42:43]
	v_pk_add_f32 v[36:37], v[36:37], v[40:41]
	v_pk_add_f32 v[38:39], v[38:39], v[42:43]
	v_permlane32_swap_b32_e32 v80, v84
	v_permlane32_swap_b32_e32 v81, v85
	v_permlane32_swap_b32_e32 v82, v86
	v_permlane32_swap_b32_e32 v83, v87
	v_mov_b32_e32 v88, v80
	v_mov_b32_e32 v89, v81
	v_mov_b32_e32 v90, v82
	v_mov_b32_e32 v91, v83
	s_nop 0
	v_permlane16_swap_b32_e32 v80, v88
	v_permlane16_swap_b32_e32 v81, v89
	v_permlane16_swap_b32_e32 v82, v90
	v_permlane16_swap_b32_e32 v83, v91
	v_fmac_f32_e32 v81, v124, v80
	v_fmac_f32_e32 v82, v128, v80
	v_fmac_f32_e32 v83, v132, v80
	v_fmac_f32_e32 v88, v136, v80
	v_fmac_f32_e32 v89, v144, v80
	v_fmac_f32_e32 v90, v152, v80
	v_fmac_f32_e32 v91, v160, v80
	v_fmac_f32_e32 v82, v129, v81
	v_fmac_f32_e32 v83, v133, v81
	v_fmac_f32_e32 v88, v137, v81
	v_fmac_f32_e32 v89, v145, v81
	v_fmac_f32_e32 v90, v153, v81
	v_fmac_f32_e32 v91, v161, v81
	v_fmac_f32_e32 v83, v134, v82
	v_fmac_f32_e32 v88, v138, v82
	v_fmac_f32_e32 v89, v146, v82
	v_fmac_f32_e32 v90, v154, v82
	v_fmac_f32_e32 v91, v162, v82
	v_fmac_f32_e32 v88, v139, v83
	v_fmac_f32_e32 v89, v147, v83
	v_fmac_f32_e32 v90, v155, v83
	v_fmac_f32_e32 v91, v163, v83
	v_fmac_f32_e32 v89, v148, v88
	v_fmac_f32_e32 v90, v156, v88
	v_fmac_f32_e32 v91, v164, v88
	v_fmac_f32_e32 v90, v157, v89
	v_fmac_f32_e32 v91, v165, v89
	v_fmac_f32_e32 v91, v166, v90
	ds_read_b128 v[124:127], v170 offset:2080
	ds_read_b128 v[128:131], v170 offset:2112
	ds_read_b128 v[132:135], v170 offset:2144
	ds_read_b128 v[136:139], v170 offset:2176
	ds_read_b128 v[144:147], v170 offset:2208
	ds_read_b128 v[148:151], v170 offset:2224
	ds_read_b128 v[152:155], v170 offset:2240
	ds_read_b128 v[156:159], v170 offset:2256
	ds_read_b128 v[160:163], v170 offset:2272
	ds_read_b128 v[164:167], v170 offset:2288
	v_cndmask_b32_e32 v220, v80, v81, vcc
	v_cndmask_b32_e64 v220, v220, v82, s[4:5]
	v_cndmask_b32_e64 v220, v220, v83, s[6:7]
	v_cndmask_b32_e32 v221, v88, v89, vcc
	v_cndmask_b32_e64 v221, v221, v90, s[4:5]
	v_cndmask_b32_e64 v221, v221, v91, s[6:7]
	s_nop 1
	v_mfma_f32_16x16x4_f32 v[84:87], v218, v220, v[36:39]
	v_mfma_f32_16x16x4_f32 v[84:87], v219, v221, v[84:87]
	ds_read_b32 v218, v172 offset:2048
	ds_read_b32 v219, v172 offset:2064
	v_mfma_f32_16x16x4_f32 v[224:227], v182, v220, v[224:227]
	v_mfma_f32_16x16x4_f32 v[224:227], v186, v221, v[224:227]
	v_mfma_f32_16x16x4_f32 v[228:231], v183, v220, v[228:231]
	v_mfma_f32_16x16x4_f32 v[228:231], v187, v221, v[228:231]
	v_mfma_f32_16x16x4_f32 v[232:235], v184, v220, v[232:235]
	v_mfma_f32_16x16x4_f32 v[232:235], v188, v221, v[232:235]
	v_mfma_f32_16x16x4_f32 v[236:239], v185, v220, v[236:239]
	v_mfma_f32_16x16x4_f32 v[236:239], v189, v221, v[236:239]
	v_add_u32_e32 v173, 0x880, v173
	v_add_u32_e32 v2, 0x880, v2
	v_add_u32_e32 v3, 0x880, v3
	v_add_u32_e32 v5, 0x880, v5
	ds_read2_b32 v[182:183], v173 offset0:0 offset1:16
	ds_read2_b32 v[184:185], v173 offset0:32 offset1:48
	ds_read2_b32 v[186:187], v2 offset0:0 offset1:16
	ds_read2_b32 v[188:189], v2 offset0:32 offset1:48
	ds_read2_b32 v[190:191], v3 offset0:0 offset1:16
	ds_read2_b32 v[192:193], v3 offset0:32 offset1:48
	ds_read2_b32 v[194:195], v5 offset0:0 offset1:16
	ds_read2_b32 v[196:197], v5 offset0:32 offset1:48
	s_mov_b64 exec, s[8:9]
	ds_write_b32 v175, v84 offset:2048
	ds_write_b32 v175, v85 offset:2304
	ds_write_b32 v175, v86 offset:2560
	ds_write_b32 v175, v87 offset:2816
	s_mov_b64 exec, s[14:15]
	ds_add_u32 v179, v241 offset:4
	s_mov_b64 exec, -1
	s_waitcnt lgkmcnt(4)
	v_pk_mul_f32 v[224:225], v[224:225], v[198:199]
	v_pk_mul_f32 v[226:227], v[226:227], v[200:201]
	v_pk_mul_f32 v[228:229], v[228:229], v[202:203]
	v_pk_mul_f32 v[230:231], v[230:231], v[204:205]
	v_mfma_f32_16x16x4_f32 v[36:39], v44, v224, 0
	v_mfma_f32_16x16x4_f32 v[40:43], v45, v225, 0
	v_mfma_f32_16x16x4_f32 v[36:39], v46, v226, v[36:39]
	v_mfma_f32_16x16x4_f32 v[40:43], v47, v227, v[40:43]
	v_pk_mul_f32 v[232:233], v[232:233], v[206:207]
	v_pk_mul_f32 v[234:235], v[234:235], v[208:209]
	v_mfma_f32_16x16x4_f32 v[36:39], v48, v228, v[36:39]
	v_mfma_f32_16x16x4_f32 v[40:43], v49, v229, v[40:43]
	v_mfma_f32_16x16x4_f32 v[36:39], v50, v230, v[36:39]
	v_mfma_f32_16x16x4_f32 v[40:43], v51, v231, v[40:43]
	v_pk_mul_f32 v[236:237], v[236:237], v[210:211]
	v_pk_mul_f32 v[238:239], v[238:239], v[212:213]
	v_mfma_f32_16x16x4_f32 v[36:39], v68, v232, v[36:39]
	v_mfma_f32_16x16x4_f32 v[40:43], v69, v233, v[40:43]
	v_mfma_f32_16x16x4_f32 v[36:39], v70, v234, v[36:39]
	v_mfma_f32_16x16x4_f32 v[40:43], v71, v235, v[40:43]
	v_mfma_f32_16x16x4_f32 v[36:39], v96, v236, v[36:39]
	v_mfma_f32_16x16x4_f32 v[40:43], v97, v237, v[40:43]
	v_mfma_f32_16x16x4_f32 v[36:39], v98, v238, v[36:39]
	v_mfma_f32_16x16x4_f32 v[40:43], v99, v239, v[40:43]
	v_mfma_f32_16x16x4_f32 v[36:39], v216, v214, v[36:39]
	v_mfma_f32_16x16x4_f32 v[40:43], v217, v215, v[40:43]
	ds_read_b128 v[44:47], v168 offset:6528
	ds_read_b128 v[48:51], v168 offset:6592
	ds_read_b128 v[68:71], v168 offset:6656
	ds_read_b128 v[96:99], v168 offset:6720
	ds_read_b32 v216, v171 offset:3072
	ds_read_b32 v217, v171 offset:3088
	ds_read_b128 v[198:201], v174 offset:512
	ds_read_b128 v[202:205], v174 offset:576
	ds_read_b128 v[206:209], v174 offset:640
	ds_read_b128 v[210:213], v174 offset:704
	v_mfma_f32_16x16x4_f32 v[224:227], v190, v214, v[224:227]
	v_mfma_f32_16x16x4_f32 v[224:227], v194, v215, v[224:227]
	v_mfma_f32_16x16x4_f32 v[228:231], v191, v214, v[228:231]
	v_mfma_f32_16x16x4_f32 v[228:231], v195, v215, v[228:231]
	v_mfma_f32_16x16x4_f32 v[232:235], v192, v214, v[232:235]
	v_mfma_f32_16x16x4_f32 v[232:235], v196, v215, v[232:235]
	v_mfma_f32_16x16x4_f32 v[236:239], v193, v214, v[236:239]
	v_mfma_f32_16x16x4_f32 v[236:239], v197, v215, v[236:239]
	ds_read_b32 v214, v169 offset:6144
	ds_read_b32 v215, v169 offset:7168
	v_pk_add_f32 v[80:81], v[36:37], v[40:41]
	v_pk_add_f32 v[82:83], v[38:39], v[42:43]
	v_pk_add_f32 v[84:85], v[36:37], v[40:41]
	v_pk_add_f32 v[86:87], v[38:39], v[42:43]
	v_pk_add_f32 v[36:37], v[36:37], v[40:41]
	v_pk_add_f32 v[38:39], v[38:39], v[42:43]
	v_permlane32_swap_b32_e32 v80, v84
	v_permlane32_swap_b32_e32 v81, v85
	v_permlane32_swap_b32_e32 v82, v86
	v_permlane32_swap_b32_e32 v83, v87
	v_mov_b32_e32 v88, v80
	v_mov_b32_e32 v89, v81
	v_mov_b32_e32 v90, v82
	v_mov_b32_e32 v91, v83
	s_nop 0
	v_permlane16_swap_b32_e32 v80, v88
	v_permlane16_swap_b32_e32 v81, v89
	v_permlane16_swap_b32_e32 v82, v90
	v_permlane16_swap_b32_e32 v83, v91
	v_fmac_f32_e32 v81, v124, v80
	v_fmac_f32_e32 v82, v128, v80
	v_fmac_f32_e32 v83, v132, v80
	v_fmac_f32_e32 v88, v136, v80
	v_fmac_f32_e32 v89, v144, v80
	v_fmac_f32_e32 v90, v152, v80
	v_fmac_f32_e32 v91, v160, v80
	v_fmac_f32_e32 v82, v129, v81
	v_fmac_f32_e32 v83, v133, v81
	v_fmac_f32_e32 v88, v137, v81
	v_fmac_f32_e32 v89, v145, v81
	v_fmac_f32_e32 v90, v153, v81
	v_fmac_f32_e32 v91, v161, v81
	v_fmac_f32_e32 v83, v134, v82
	v_fmac_f32_e32 v88, v138, v82
	v_fmac_f32_e32 v89, v146, v82
	v_fmac_f32_e32 v90, v154, v82
	v_fmac_f32_e32 v91, v162, v82
	v_fmac_f32_e32 v88, v139, v83
	v_fmac_f32_e32 v89, v147, v83
	v_fmac_f32_e32 v90, v155, v83
	v_fmac_f32_e32 v91, v163, v83
	v_fmac_f32_e32 v89, v148, v88
	v_fmac_f32_e32 v90, v156, v88
	v_fmac_f32_e32 v91, v164, v88
	v_fmac_f32_e32 v90, v157, v89
	v_fmac_f32_e32 v91, v165, v89
	v_fmac_f32_e32 v91, v166, v90
	ds_read_b128 v[124:127], v170 offset:3104
	ds_read_b128 v[128:131], v170 offset:3136
	ds_read_b128 v[132:135], v170 offset:3168
	ds_read_b128 v[136:139], v170 offset:3200
	ds_read_b128 v[144:147], v170 offset:3232
	ds_read_b128 v[148:151], v170 offset:3248
	ds_read_b128 v[152:155], v170 offset:3264
	ds_read_b128 v[156:159], v170 offset:3280
	ds_read_b128 v[160:163], v170 offset:3296
	ds_read_b128 v[164:167], v170 offset:3312
	v_cndmask_b32_e32 v220, v80, v81, vcc
	v_cndmask_b32_e64 v220, v220, v82, s[4:5]
	v_cndmask_b32_e64 v220, v220, v83, s[6:7]
	v_cndmask_b32_e32 v221, v88, v89, vcc
	v_cndmask_b32_e64 v221, v221, v90, s[4:5]
	v_cndmask_b32_e64 v221, v221, v91, s[6:7]
	s_nop 1
	v_mfma_f32_16x16x4_f32 v[84:87], v218, v220, v[36:39]
	v_mfma_f32_16x16x4_f32 v[84:87], v219, v221, v[84:87]
	ds_read_b32 v218, v172 offset:3072
	ds_read_b32 v219, v172 offset:3088
	v_mfma_f32_16x16x4_f32 v[224:227], v182, v220, v[224:227]
	v_mfma_f32_16x16x4_f32 v[224:227], v186, v221, v[224:227]
	v_mfma_f32_16x16x4_f32 v[228:231], v183, v220, v[228:231]
	v_mfma_f32_16x16x4_f32 v[228:231], v187, v221, v[228:231]
	v_mfma_f32_16x16x4_f32 v[232:235], v184, v220, v[232:235]
	v_mfma_f32_16x16x4_f32 v[232:235], v188, v221, v[232:235]
	v_mfma_f32_16x16x4_f32 v[236:239], v185, v220, v[236:239]
	v_mfma_f32_16x16x4_f32 v[236:239], v189, v221, v[236:239]
	v_add_u32_e32 v173, 0x880, v173
	v_add_u32_e32 v2, 0x880, v2
	v_add_u32_e32 v3, 0x880, v3
	v_add_u32_e32 v5, 0x880, v5
	ds_read2_b32 v[182:183], v173 offset0:0 offset1:16
	ds_read2_b32 v[184:185], v173 offset0:32 offset1:48
	ds_read2_b32 v[186:187], v2 offset0:0 offset1:16
	ds_read2_b32 v[188:189], v2 offset0:32 offset1:48
	ds_read2_b32 v[190:191], v3 offset0:0 offset1:16
	ds_read2_b32 v[192:193], v3 offset0:32 offset1:48
	ds_read2_b32 v[194:195], v5 offset0:0 offset1:16
	ds_read2_b32 v[196:197], v5 offset0:32 offset1:48
	s_mov_b64 exec, s[8:9]
	ds_write_b32 v175, v84 offset:4096
	ds_write_b32 v175, v85 offset:4352
	ds_write_b32 v175, v86 offset:4608
	ds_write_b32 v175, v87 offset:4864
	s_mov_b64 exec, s[14:15]
	ds_add_u32 v179, v241 offset:8
	s_mov_b64 exec, -1
	s_waitcnt lgkmcnt(4)
	v_pk_mul_f32 v[224:225], v[224:225], v[198:199]
	v_pk_mul_f32 v[226:227], v[226:227], v[200:201]
	v_pk_mul_f32 v[228:229], v[228:229], v[202:203]
	v_pk_mul_f32 v[230:231], v[230:231], v[204:205]
	v_mfma_f32_16x16x4_f32 v[36:39], v44, v224, 0
	v_mfma_f32_16x16x4_f32 v[40:43], v45, v225, 0
	v_mfma_f32_16x16x4_f32 v[36:39], v46, v226, v[36:39]
	v_mfma_f32_16x16x4_f32 v[40:43], v47, v227, v[40:43]
	v_pk_mul_f32 v[232:233], v[232:233], v[206:207]
	v_pk_mul_f32 v[234:235], v[234:235], v[208:209]
	v_mfma_f32_16x16x4_f32 v[36:39], v48, v228, v[36:39]
	v_mfma_f32_16x16x4_f32 v[40:43], v49, v229, v[40:43]
	v_mfma_f32_16x16x4_f32 v[36:39], v50, v230, v[36:39]
	v_mfma_f32_16x16x4_f32 v[40:43], v51, v231, v[40:43]
	v_pk_mul_f32 v[236:237], v[236:237], v[210:211]
	v_pk_mul_f32 v[238:239], v[238:239], v[212:213]
	v_mfma_f32_16x16x4_f32 v[36:39], v68, v232, v[36:39]
	v_mfma_f32_16x16x4_f32 v[40:43], v69, v233, v[40:43]
	v_mfma_f32_16x16x4_f32 v[36:39], v70, v234, v[36:39]
	v_mfma_f32_16x16x4_f32 v[40:43], v71, v235, v[40:43]
	v_mfma_f32_16x16x4_f32 v[36:39], v96, v236, v[36:39]
	v_mfma_f32_16x16x4_f32 v[40:43], v97, v237, v[40:43]
	v_mfma_f32_16x16x4_f32 v[36:39], v98, v238, v[36:39]
	v_mfma_f32_16x16x4_f32 v[40:43], v99, v239, v[40:43]
	v_mfma_f32_16x16x4_f32 v[36:39], v216, v214, v[36:39]
	v_mfma_f32_16x16x4_f32 v[40:43], v217, v215, v[40:43]
	ds_read_b128 v[44:47], v168 offset:8704
	ds_read_b128 v[48:51], v168 offset:8768
	ds_read_b128 v[68:71], v168 offset:8832
	ds_read_b128 v[96:99], v168 offset:8896
	ds_read_b32 v216, v171 offset:4096
	ds_read_b32 v217, v171 offset:4112
	ds_read_b128 v[198:201], v174 offset:768
	ds_read_b128 v[202:205], v174 offset:832
	ds_read_b128 v[206:209], v174 offset:896
	ds_read_b128 v[210:213], v174 offset:960
	v_mfma_f32_16x16x4_f32 v[224:227], v190, v214, v[224:227]
	v_mfma_f32_16x16x4_f32 v[224:227], v194, v215, v[224:227]
	v_mfma_f32_16x16x4_f32 v[228:231], v191, v214, v[228:231]
	v_mfma_f32_16x16x4_f32 v[228:231], v195, v215, v[228:231]
	v_mfma_f32_16x16x4_f32 v[232:235], v192, v214, v[232:235]
	v_mfma_f32_16x16x4_f32 v[232:235], v196, v215, v[232:235]
	v_mfma_f32_16x16x4_f32 v[236:239], v193, v214, v[236:239]
	v_mfma_f32_16x16x4_f32 v[236:239], v197, v215, v[236:239]
	ds_read_b32 v214, v169 offset:8192
	ds_read_b32 v215, v169 offset:9216
	v_pk_add_f32 v[80:81], v[36:37], v[40:41]
	v_pk_add_f32 v[82:83], v[38:39], v[42:43]
	v_pk_add_f32 v[84:85], v[36:37], v[40:41]
	v_pk_add_f32 v[86:87], v[38:39], v[42:43]
	v_pk_add_f32 v[36:37], v[36:37], v[40:41]
	v_pk_add_f32 v[38:39], v[38:39], v[42:43]
	v_permlane32_swap_b32_e32 v80, v84
	v_permlane32_swap_b32_e32 v81, v85
	v_permlane32_swap_b32_e32 v82, v86
	v_permlane32_swap_b32_e32 v83, v87
	v_mov_b32_e32 v88, v80
	v_mov_b32_e32 v89, v81
	v_mov_b32_e32 v90, v82
	v_mov_b32_e32 v91, v83
	s_nop 0
	v_permlane16_swap_b32_e32 v80, v88
	v_permlane16_swap_b32_e32 v81, v89
	v_permlane16_swap_b32_e32 v82, v90
	v_permlane16_swap_b32_e32 v83, v91
	v_fmac_f32_e32 v81, v124, v80
	v_fmac_f32_e32 v82, v128, v80
	v_fmac_f32_e32 v83, v132, v80
	v_fmac_f32_e32 v88, v136, v80
	v_fmac_f32_e32 v89, v144, v80
	v_fmac_f32_e32 v90, v152, v80
	v_fmac_f32_e32 v91, v160, v80
	v_fmac_f32_e32 v82, v129, v81
	v_fmac_f32_e32 v83, v133, v81
	v_fmac_f32_e32 v88, v137, v81
	v_fmac_f32_e32 v89, v145, v81
	v_fmac_f32_e32 v90, v153, v81
	v_fmac_f32_e32 v91, v161, v81
	v_fmac_f32_e32 v83, v134, v82
	v_fmac_f32_e32 v88, v138, v82
	v_fmac_f32_e32 v89, v146, v82
	v_fmac_f32_e32 v90, v154, v82
	v_fmac_f32_e32 v91, v162, v82
	v_fmac_f32_e32 v88, v139, v83
	v_fmac_f32_e32 v89, v147, v83
	v_fmac_f32_e32 v90, v155, v83
	v_fmac_f32_e32 v91, v163, v83
	v_fmac_f32_e32 v89, v148, v88
	v_fmac_f32_e32 v90, v156, v88
	v_fmac_f32_e32 v91, v164, v88
	v_fmac_f32_e32 v90, v157, v89
	v_fmac_f32_e32 v91, v165, v89
	v_fmac_f32_e32 v91, v166, v90
	ds_read_b128 v[124:127], v170 offset:4128
	ds_read_b128 v[128:131], v170 offset:4160
	ds_read_b128 v[132:135], v170 offset:4192
	ds_read_b128 v[136:139], v170 offset:4224
	ds_read_b128 v[144:147], v170 offset:4256
	ds_read_b128 v[148:151], v170 offset:4272
	ds_read_b128 v[152:155], v170 offset:4288
	ds_read_b128 v[156:159], v170 offset:4304
	ds_read_b128 v[160:163], v170 offset:4320
	ds_read_b128 v[164:167], v170 offset:4336
	v_cndmask_b32_e32 v220, v80, v81, vcc
	v_cndmask_b32_e64 v220, v220, v82, s[4:5]
	v_cndmask_b32_e64 v220, v220, v83, s[6:7]
	v_cndmask_b32_e32 v221, v88, v89, vcc
	v_cndmask_b32_e64 v221, v221, v90, s[4:5]
	v_cndmask_b32_e64 v221, v221, v91, s[6:7]
	s_nop 1
	v_mfma_f32_16x16x4_f32 v[84:87], v218, v220, v[36:39]
	v_mfma_f32_16x16x4_f32 v[84:87], v219, v221, v[84:87]
	ds_read_b32 v218, v172 offset:4096
	ds_read_b32 v219, v172 offset:4112
	v_mfma_f32_16x16x4_f32 v[224:227], v182, v220, v[224:227]
	v_mfma_f32_16x16x4_f32 v[224:227], v186, v221, v[224:227]
	v_mfma_f32_16x16x4_f32 v[228:231], v183, v220, v[228:231]
	v_mfma_f32_16x16x4_f32 v[228:231], v187, v221, v[228:231]
	v_mfma_f32_16x16x4_f32 v[232:235], v184, v220, v[232:235]
	v_mfma_f32_16x16x4_f32 v[232:235], v188, v221, v[232:235]
	v_mfma_f32_16x16x4_f32 v[236:239], v185, v220, v[236:239]
	v_mfma_f32_16x16x4_f32 v[236:239], v189, v221, v[236:239]
	v_add_u32_e32 v173, 0x880, v173
	v_add_u32_e32 v2, 0x880, v2
	v_add_u32_e32 v3, 0x880, v3
	v_add_u32_e32 v5, 0x880, v5
	ds_read2_b32 v[182:183], v173 offset0:0 offset1:16
	ds_read2_b32 v[184:185], v173 offset0:32 offset1:48
	ds_read2_b32 v[186:187], v2 offset0:0 offset1:16
	ds_read2_b32 v[188:189], v2 offset0:32 offset1:48
	ds_read2_b32 v[190:191], v3 offset0:0 offset1:16
	ds_read2_b32 v[192:193], v3 offset0:32 offset1:48
	ds_read2_b32 v[194:195], v5 offset0:0 offset1:16
	ds_read2_b32 v[196:197], v5 offset0:32 offset1:48
	s_mov_b64 exec, s[8:9]
	ds_write_b32 v175, v84 offset:6144
	ds_write_b32 v175, v85 offset:6400
	ds_write_b32 v175, v86 offset:6656
	ds_write_b32 v175, v87 offset:6912
	s_mov_b64 exec, s[14:15]
	ds_add_u32 v179, v241 offset:12
	s_mov_b64 exec, -1
	s_waitcnt lgkmcnt(4)
	v_pk_mul_f32 v[224:225], v[224:225], v[198:199]
	v_pk_mul_f32 v[226:227], v[226:227], v[200:201]
	v_pk_mul_f32 v[228:229], v[228:229], v[202:203]
	v_pk_mul_f32 v[230:231], v[230:231], v[204:205]
	v_mfma_f32_16x16x4_f32 v[36:39], v44, v224, 0
	v_mfma_f32_16x16x4_f32 v[40:43], v45, v225, 0
	v_mfma_f32_16x16x4_f32 v[36:39], v46, v226, v[36:39]
	v_mfma_f32_16x16x4_f32 v[40:43], v47, v227, v[40:43]
	v_pk_mul_f32 v[232:233], v[232:233], v[206:207]
	v_pk_mul_f32 v[234:235], v[234:235], v[208:209]
	v_mfma_f32_16x16x4_f32 v[36:39], v48, v228, v[36:39]
	v_mfma_f32_16x16x4_f32 v[40:43], v49, v229, v[40:43]
	v_mfma_f32_16x16x4_f32 v[36:39], v50, v230, v[36:39]
	v_mfma_f32_16x16x4_f32 v[40:43], v51, v231, v[40:43]
	v_pk_mul_f32 v[236:237], v[236:237], v[210:211]
	v_pk_mul_f32 v[238:239], v[238:239], v[212:213]
	v_mfma_f32_16x16x4_f32 v[36:39], v68, v232, v[36:39]
	v_mfma_f32_16x16x4_f32 v[40:43], v69, v233, v[40:43]
	v_mfma_f32_16x16x4_f32 v[36:39], v70, v234, v[36:39]
	v_mfma_f32_16x16x4_f32 v[40:43], v71, v235, v[40:43]
	v_mfma_f32_16x16x4_f32 v[36:39], v96, v236, v[36:39]
	v_mfma_f32_16x16x4_f32 v[40:43], v97, v237, v[40:43]
	v_mfma_f32_16x16x4_f32 v[36:39], v98, v238, v[36:39]
	v_mfma_f32_16x16x4_f32 v[40:43], v99, v239, v[40:43]
	v_mfma_f32_16x16x4_f32 v[36:39], v216, v214, v[36:39]
	v_mfma_f32_16x16x4_f32 v[40:43], v217, v215, v[40:43]
	ds_read_b128 v[44:47], v168 offset:10880
	ds_read_b128 v[48:51], v168 offset:10944
	ds_read_b128 v[68:71], v168 offset:11008
	ds_read_b128 v[96:99], v168 offset:11072
	ds_read_b32 v216, v171 offset:5120
	ds_read_b32 v217, v171 offset:5136
	ds_read_b128 v[198:201], v174 offset:1024
	ds_read_b128 v[202:205], v174 offset:1088
	ds_read_b128 v[206:209], v174 offset:1152
	ds_read_b128 v[210:213], v174 offset:1216
	v_mfma_f32_16x16x4_f32 v[224:227], v190, v214, v[224:227]
	v_mfma_f32_16x16x4_f32 v[224:227], v194, v215, v[224:227]
	v_mfma_f32_16x16x4_f32 v[228:231], v191, v214, v[228:231]
	v_mfma_f32_16x16x4_f32 v[228:231], v195, v215, v[228:231]
	v_mfma_f32_16x16x4_f32 v[232:235], v192, v214, v[232:235]
	v_mfma_f32_16x16x4_f32 v[232:235], v196, v215, v[232:235]
	v_mfma_f32_16x16x4_f32 v[236:239], v193, v214, v[236:239]
	v_mfma_f32_16x16x4_f32 v[236:239], v197, v215, v[236:239]
	ds_read_b32 v214, v169 offset:10240
	ds_read_b32 v215, v169 offset:11264
	v_pk_add_f32 v[80:81], v[36:37], v[40:41]
	v_pk_add_f32 v[82:83], v[38:39], v[42:43]
	v_pk_add_f32 v[84:85], v[36:37], v[40:41]
	v_pk_add_f32 v[86:87], v[38:39], v[42:43]
	v_pk_add_f32 v[36:37], v[36:37], v[40:41]
	v_pk_add_f32 v[38:39], v[38:39], v[42:43]
	v_permlane32_swap_b32_e32 v80, v84
	v_permlane32_swap_b32_e32 v81, v85
	v_permlane32_swap_b32_e32 v82, v86
	v_permlane32_swap_b32_e32 v83, v87
	v_mov_b32_e32 v88, v80
	v_mov_b32_e32 v89, v81
	v_mov_b32_e32 v90, v82
	v_mov_b32_e32 v91, v83
	s_nop 0
	v_permlane16_swap_b32_e32 v80, v88
	v_permlane16_swap_b32_e32 v81, v89
	v_permlane16_swap_b32_e32 v82, v90
	v_permlane16_swap_b32_e32 v83, v91
	v_fmac_f32_e32 v81, v124, v80
	v_fmac_f32_e32 v82, v128, v80
	v_fmac_f32_e32 v83, v132, v80
	v_fmac_f32_e32 v88, v136, v80
	v_fmac_f32_e32 v89, v144, v80
	v_fmac_f32_e32 v90, v152, v80
	v_fmac_f32_e32 v91, v160, v80
	v_fmac_f32_e32 v82, v129, v81
	v_fmac_f32_e32 v83, v133, v81
	v_fmac_f32_e32 v88, v137, v81
	v_fmac_f32_e32 v89, v145, v81
	v_fmac_f32_e32 v90, v153, v81
	v_fmac_f32_e32 v91, v161, v81
	v_fmac_f32_e32 v83, v134, v82
	v_fmac_f32_e32 v88, v138, v82
	v_fmac_f32_e32 v89, v146, v82
	v_fmac_f32_e32 v90, v154, v82
	v_fmac_f32_e32 v91, v162, v82
	v_fmac_f32_e32 v88, v139, v83
	v_fmac_f32_e32 v89, v147, v83
	v_fmac_f32_e32 v90, v155, v83
	v_fmac_f32_e32 v91, v163, v83
	v_fmac_f32_e32 v89, v148, v88
	v_fmac_f32_e32 v90, v156, v88
	v_fmac_f32_e32 v91, v164, v88
	v_fmac_f32_e32 v90, v157, v89
	v_fmac_f32_e32 v91, v165, v89
	v_fmac_f32_e32 v91, v166, v90
	ds_read_b128 v[124:127], v170 offset:5152
	ds_read_b128 v[128:131], v170 offset:5184
	ds_read_b128 v[132:135], v170 offset:5216
	ds_read_b128 v[136:139], v170 offset:5248
	ds_read_b128 v[144:147], v170 offset:5280
	ds_read_b128 v[148:151], v170 offset:5296
	ds_read_b128 v[152:155], v170 offset:5312
	ds_read_b128 v[156:159], v170 offset:5328
	ds_read_b128 v[160:163], v170 offset:5344
	ds_read_b128 v[164:167], v170 offset:5360
	v_cndmask_b32_e32 v220, v80, v81, vcc
	v_cndmask_b32_e64 v220, v220, v82, s[4:5]
	v_cndmask_b32_e64 v220, v220, v83, s[6:7]
	v_cndmask_b32_e32 v221, v88, v89, vcc
	v_cndmask_b32_e64 v221, v221, v90, s[4:5]
	v_cndmask_b32_e64 v221, v221, v91, s[6:7]
	s_nop 1
	v_mfma_f32_16x16x4_f32 v[84:87], v218, v220, v[36:39]
	v_mfma_f32_16x16x4_f32 v[84:87], v219, v221, v[84:87]
	ds_read_b32 v218, v172 offset:5120
	ds_read_b32 v219, v172 offset:5136
	v_mfma_f32_16x16x4_f32 v[224:227], v182, v220, v[224:227]
	v_mfma_f32_16x16x4_f32 v[224:227], v186, v221, v[224:227]
	v_mfma_f32_16x16x4_f32 v[228:231], v183, v220, v[228:231]
	v_mfma_f32_16x16x4_f32 v[228:231], v187, v221, v[228:231]
	v_mfma_f32_16x16x4_f32 v[232:235], v184, v220, v[232:235]
	v_mfma_f32_16x16x4_f32 v[232:235], v188, v221, v[232:235]
	v_mfma_f32_16x16x4_f32 v[236:239], v185, v220, v[236:239]
	v_mfma_f32_16x16x4_f32 v[236:239], v189, v221, v[236:239]
	v_add_u32_e32 v173, 0x880, v173
	v_add_u32_e32 v2, 0x880, v2
	v_add_u32_e32 v3, 0x880, v3
	v_add_u32_e32 v5, 0x880, v5
	ds_read2_b32 v[182:183], v173 offset0:0 offset1:16
	ds_read2_b32 v[184:185], v173 offset0:32 offset1:48
	ds_read2_b32 v[186:187], v2 offset0:0 offset1:16
	ds_read2_b32 v[188:189], v2 offset0:32 offset1:48
	ds_read2_b32 v[190:191], v3 offset0:0 offset1:16
	ds_read2_b32 v[192:193], v3 offset0:32 offset1:48
	ds_read2_b32 v[194:195], v5 offset0:0 offset1:16
	ds_read2_b32 v[196:197], v5 offset0:32 offset1:48
	s_mov_b64 exec, s[8:9]
	ds_write_b32 v175, v84 offset:8192
	ds_write_b32 v175, v85 offset:8448
	ds_write_b32 v175, v86 offset:8704
	ds_write_b32 v175, v87 offset:8960
	s_mov_b64 exec, s[14:15]
	ds_add_u32 v179, v241 offset:16
	s_mov_b64 exec, -1
	s_waitcnt lgkmcnt(4)
	v_pk_mul_f32 v[224:225], v[224:225], v[198:199]
	v_pk_mul_f32 v[226:227], v[226:227], v[200:201]
	v_pk_mul_f32 v[228:229], v[228:229], v[202:203]
	v_pk_mul_f32 v[230:231], v[230:231], v[204:205]
	v_mfma_f32_16x16x4_f32 v[36:39], v44, v224, 0
	v_mfma_f32_16x16x4_f32 v[40:43], v45, v225, 0
	v_mfma_f32_16x16x4_f32 v[36:39], v46, v226, v[36:39]
	v_mfma_f32_16x16x4_f32 v[40:43], v47, v227, v[40:43]
	v_pk_mul_f32 v[232:233], v[232:233], v[206:207]
	v_pk_mul_f32 v[234:235], v[234:235], v[208:209]
	v_mfma_f32_16x16x4_f32 v[36:39], v48, v228, v[36:39]
	v_mfma_f32_16x16x4_f32 v[40:43], v49, v229, v[40:43]
	v_mfma_f32_16x16x4_f32 v[36:39], v50, v230, v[36:39]
	v_mfma_f32_16x16x4_f32 v[40:43], v51, v231, v[40:43]
	v_pk_mul_f32 v[236:237], v[236:237], v[210:211]
	v_pk_mul_f32 v[238:239], v[238:239], v[212:213]
	v_mfma_f32_16x16x4_f32 v[36:39], v68, v232, v[36:39]
	v_mfma_f32_16x16x4_f32 v[40:43], v69, v233, v[40:43]
	v_mfma_f32_16x16x4_f32 v[36:39], v70, v234, v[36:39]
	v_mfma_f32_16x16x4_f32 v[40:43], v71, v235, v[40:43]
	v_mfma_f32_16x16x4_f32 v[36:39], v96, v236, v[36:39]
	v_mfma_f32_16x16x4_f32 v[40:43], v97, v237, v[40:43]
	v_mfma_f32_16x16x4_f32 v[36:39], v98, v238, v[36:39]
	v_mfma_f32_16x16x4_f32 v[40:43], v99, v239, v[40:43]
	v_mfma_f32_16x16x4_f32 v[36:39], v216, v214, v[36:39]
	v_mfma_f32_16x16x4_f32 v[40:43], v217, v215, v[40:43]
	ds_read_b128 v[44:47], v168 offset:13056
	ds_read_b128 v[48:51], v168 offset:13120
	ds_read_b128 v[68:71], v168 offset:13184
	ds_read_b128 v[96:99], v168 offset:13248
	ds_read_b32 v216, v171 offset:6144
	ds_read_b32 v217, v171 offset:6160
	ds_read_b128 v[198:201], v174 offset:1280
	ds_read_b128 v[202:205], v174 offset:1344
	ds_read_b128 v[206:209], v174 offset:1408
	ds_read_b128 v[210:213], v174 offset:1472
	v_mfma_f32_16x16x4_f32 v[224:227], v190, v214, v[224:227]
	v_mfma_f32_16x16x4_f32 v[224:227], v194, v215, v[224:227]
	v_mfma_f32_16x16x4_f32 v[228:231], v191, v214, v[228:231]
	v_mfma_f32_16x16x4_f32 v[228:231], v195, v215, v[228:231]
	v_mfma_f32_16x16x4_f32 v[232:235], v192, v214, v[232:235]
	v_mfma_f32_16x16x4_f32 v[232:235], v196, v215, v[232:235]
	v_mfma_f32_16x16x4_f32 v[236:239], v193, v214, v[236:239]
	v_mfma_f32_16x16x4_f32 v[236:239], v197, v215, v[236:239]
	ds_read_b32 v214, v169 offset:12288
	ds_read_b32 v215, v169 offset:13312
	v_pk_add_f32 v[80:81], v[36:37], v[40:41]
	v_pk_add_f32 v[82:83], v[38:39], v[42:43]
	v_pk_add_f32 v[84:85], v[36:37], v[40:41]
	v_pk_add_f32 v[86:87], v[38:39], v[42:43]
	v_pk_add_f32 v[36:37], v[36:37], v[40:41]
	v_pk_add_f32 v[38:39], v[38:39], v[42:43]
	v_permlane32_swap_b32_e32 v80, v84
	v_permlane32_swap_b32_e32 v81, v85
	v_permlane32_swap_b32_e32 v82, v86
	v_permlane32_swap_b32_e32 v83, v87
	v_mov_b32_e32 v88, v80
	v_mov_b32_e32 v89, v81
	v_mov_b32_e32 v90, v82
	v_mov_b32_e32 v91, v83
	s_nop 0
	v_permlane16_swap_b32_e32 v80, v88
	v_permlane16_swap_b32_e32 v81, v89
	v_permlane16_swap_b32_e32 v82, v90
	v_permlane16_swap_b32_e32 v83, v91
	v_fmac_f32_e32 v81, v124, v80
	v_fmac_f32_e32 v82, v128, v80
	v_fmac_f32_e32 v83, v132, v80
	v_fmac_f32_e32 v88, v136, v80
	v_fmac_f32_e32 v89, v144, v80
	v_fmac_f32_e32 v90, v152, v80
	v_fmac_f32_e32 v91, v160, v80
	v_fmac_f32_e32 v82, v129, v81
	v_fmac_f32_e32 v83, v133, v81
	v_fmac_f32_e32 v88, v137, v81
	v_fmac_f32_e32 v89, v145, v81
	v_fmac_f32_e32 v90, v153, v81
	v_fmac_f32_e32 v91, v161, v81
	v_fmac_f32_e32 v83, v134, v82
	v_fmac_f32_e32 v88, v138, v82
	v_fmac_f32_e32 v89, v146, v82
	v_fmac_f32_e32 v90, v154, v82
	v_fmac_f32_e32 v91, v162, v82
	v_fmac_f32_e32 v88, v139, v83
	v_fmac_f32_e32 v89, v147, v83
	v_fmac_f32_e32 v90, v155, v83
	v_fmac_f32_e32 v91, v163, v83
	v_fmac_f32_e32 v89, v148, v88
	v_fmac_f32_e32 v90, v156, v88
	v_fmac_f32_e32 v91, v164, v88
	v_fmac_f32_e32 v90, v157, v89
	v_fmac_f32_e32 v91, v165, v89
	v_fmac_f32_e32 v91, v166, v90
	ds_read_b128 v[124:127], v170 offset:6176
	ds_read_b128 v[128:131], v170 offset:6208
	ds_read_b128 v[132:135], v170 offset:6240
	ds_read_b128 v[136:139], v170 offset:6272
	ds_read_b128 v[144:147], v170 offset:6304
	ds_read_b128 v[148:151], v170 offset:6320
	ds_read_b128 v[152:155], v170 offset:6336
	ds_read_b128 v[156:159], v170 offset:6352
	ds_read_b128 v[160:163], v170 offset:6368
	ds_read_b128 v[164:167], v170 offset:6384
	v_cndmask_b32_e32 v220, v80, v81, vcc
	v_cndmask_b32_e64 v220, v220, v82, s[4:5]
	v_cndmask_b32_e64 v220, v220, v83, s[6:7]
	v_cndmask_b32_e32 v221, v88, v89, vcc
	v_cndmask_b32_e64 v221, v221, v90, s[4:5]
	v_cndmask_b32_e64 v221, v221, v91, s[6:7]
	s_nop 1
	v_mfma_f32_16x16x4_f32 v[84:87], v218, v220, v[36:39]
	v_mfma_f32_16x16x4_f32 v[84:87], v219, v221, v[84:87]
	ds_read_b32 v218, v172 offset:6144
	ds_read_b32 v219, v172 offset:6160
	v_mfma_f32_16x16x4_f32 v[224:227], v182, v220, v[224:227]
	v_mfma_f32_16x16x4_f32 v[224:227], v186, v221, v[224:227]
	v_mfma_f32_16x16x4_f32 v[228:231], v183, v220, v[228:231]
	v_mfma_f32_16x16x4_f32 v[228:231], v187, v221, v[228:231]
	v_mfma_f32_16x16x4_f32 v[232:235], v184, v220, v[232:235]
	v_mfma_f32_16x16x4_f32 v[232:235], v188, v221, v[232:235]
	v_mfma_f32_16x16x4_f32 v[236:239], v185, v220, v[236:239]
	v_mfma_f32_16x16x4_f32 v[236:239], v189, v221, v[236:239]
	v_add_u32_e32 v173, 0x880, v173
	v_add_u32_e32 v2, 0x880, v2
	v_add_u32_e32 v3, 0x880, v3
	v_add_u32_e32 v5, 0x880, v5
	ds_read2_b32 v[182:183], v173 offset0:0 offset1:16
	ds_read2_b32 v[184:185], v173 offset0:32 offset1:48
	ds_read2_b32 v[186:187], v2 offset0:0 offset1:16
	ds_read2_b32 v[188:189], v2 offset0:32 offset1:48
	ds_read2_b32 v[190:191], v3 offset0:0 offset1:16
	ds_read2_b32 v[192:193], v3 offset0:32 offset1:48
	ds_read2_b32 v[194:195], v5 offset0:0 offset1:16
	ds_read2_b32 v[196:197], v5 offset0:32 offset1:48
	s_mov_b64 exec, s[8:9]
	ds_write_b32 v175, v84 offset:10240
	ds_write_b32 v175, v85 offset:10496
	ds_write_b32 v175, v86 offset:10752
	ds_write_b32 v175, v87 offset:11008
	s_mov_b64 exec, s[14:15]
	ds_add_u32 v179, v241 offset:20
	s_mov_b64 exec, -1
	s_waitcnt lgkmcnt(4)
	v_pk_mul_f32 v[224:225], v[224:225], v[198:199]
	v_pk_mul_f32 v[226:227], v[226:227], v[200:201]
	v_pk_mul_f32 v[228:229], v[228:229], v[202:203]
	v_pk_mul_f32 v[230:231], v[230:231], v[204:205]
	v_mfma_f32_16x16x4_f32 v[36:39], v44, v224, 0
	v_mfma_f32_16x16x4_f32 v[40:43], v45, v225, 0
	v_mfma_f32_16x16x4_f32 v[36:39], v46, v226, v[36:39]
	v_mfma_f32_16x16x4_f32 v[40:43], v47, v227, v[40:43]
	v_pk_mul_f32 v[232:233], v[232:233], v[206:207]
	v_pk_mul_f32 v[234:235], v[234:235], v[208:209]
	v_mfma_f32_16x16x4_f32 v[36:39], v48, v228, v[36:39]
	v_mfma_f32_16x16x4_f32 v[40:43], v49, v229, v[40:43]
	v_mfma_f32_16x16x4_f32 v[36:39], v50, v230, v[36:39]
	v_mfma_f32_16x16x4_f32 v[40:43], v51, v231, v[40:43]
	v_pk_mul_f32 v[236:237], v[236:237], v[210:211]
	v_pk_mul_f32 v[238:239], v[238:239], v[212:213]
	v_mfma_f32_16x16x4_f32 v[36:39], v68, v232, v[36:39]
	v_mfma_f32_16x16x4_f32 v[40:43], v69, v233, v[40:43]
	v_mfma_f32_16x16x4_f32 v[36:39], v70, v234, v[36:39]
	v_mfma_f32_16x16x4_f32 v[40:43], v71, v235, v[40:43]
	v_mfma_f32_16x16x4_f32 v[36:39], v96, v236, v[36:39]
	v_mfma_f32_16x16x4_f32 v[40:43], v97, v237, v[40:43]
	v_mfma_f32_16x16x4_f32 v[36:39], v98, v238, v[36:39]
	v_mfma_f32_16x16x4_f32 v[40:43], v99, v239, v[40:43]
	v_mfma_f32_16x16x4_f32 v[36:39], v216, v214, v[36:39]
	v_mfma_f32_16x16x4_f32 v[40:43], v217, v215, v[40:43]
	ds_read_b128 v[44:47], v168 offset:15232
	ds_read_b128 v[48:51], v168 offset:15296
	ds_read_b128 v[68:71], v168 offset:15360
	ds_read_b128 v[96:99], v168 offset:15424
	ds_read_b32 v216, v171 offset:7168
	ds_read_b32 v217, v171 offset:7184
	ds_read_b128 v[198:201], v174 offset:1536
	ds_read_b128 v[202:205], v174 offset:1600
	ds_read_b128 v[206:209], v174 offset:1664
	ds_read_b128 v[210:213], v174 offset:1728
	v_mfma_f32_16x16x4_f32 v[224:227], v190, v214, v[224:227]
	v_mfma_f32_16x16x4_f32 v[224:227], v194, v215, v[224:227]
	v_mfma_f32_16x16x4_f32 v[228:231], v191, v214, v[228:231]
	v_mfma_f32_16x16x4_f32 v[228:231], v195, v215, v[228:231]
	v_mfma_f32_16x16x4_f32 v[232:235], v192, v214, v[232:235]
	v_mfma_f32_16x16x4_f32 v[232:235], v196, v215, v[232:235]
	v_mfma_f32_16x16x4_f32 v[236:239], v193, v214, v[236:239]
	v_mfma_f32_16x16x4_f32 v[236:239], v197, v215, v[236:239]
	ds_read_b32 v214, v169 offset:14336
	ds_read_b32 v215, v169 offset:15360
	v_pk_add_f32 v[80:81], v[36:37], v[40:41]
	v_pk_add_f32 v[82:83], v[38:39], v[42:43]
	v_pk_add_f32 v[84:85], v[36:37], v[40:41]
	v_pk_add_f32 v[86:87], v[38:39], v[42:43]
	v_pk_add_f32 v[36:37], v[36:37], v[40:41]
	v_pk_add_f32 v[38:39], v[38:39], v[42:43]
	v_permlane32_swap_b32_e32 v80, v84
	v_permlane32_swap_b32_e32 v81, v85
	v_permlane32_swap_b32_e32 v82, v86
	v_permlane32_swap_b32_e32 v83, v87
	v_mov_b32_e32 v88, v80
	v_mov_b32_e32 v89, v81
	v_mov_b32_e32 v90, v82
	v_mov_b32_e32 v91, v83
	s_nop 0
	v_permlane16_swap_b32_e32 v80, v88
	v_permlane16_swap_b32_e32 v81, v89
	v_permlane16_swap_b32_e32 v82, v90
	v_permlane16_swap_b32_e32 v83, v91
	v_fmac_f32_e32 v81, v124, v80
	v_fmac_f32_e32 v82, v128, v80
	v_fmac_f32_e32 v83, v132, v80
	v_fmac_f32_e32 v88, v136, v80
	v_fmac_f32_e32 v89, v144, v80
	v_fmac_f32_e32 v90, v152, v80
	v_fmac_f32_e32 v91, v160, v80
	v_fmac_f32_e32 v82, v129, v81
	v_fmac_f32_e32 v83, v133, v81
	v_fmac_f32_e32 v88, v137, v81
	v_fmac_f32_e32 v89, v145, v81
	v_fmac_f32_e32 v90, v153, v81
	v_fmac_f32_e32 v91, v161, v81
	v_fmac_f32_e32 v83, v134, v82
	v_fmac_f32_e32 v88, v138, v82
	v_fmac_f32_e32 v89, v146, v82
	v_fmac_f32_e32 v90, v154, v82
	v_fmac_f32_e32 v91, v162, v82
	v_fmac_f32_e32 v88, v139, v83
	v_fmac_f32_e32 v89, v147, v83
	v_fmac_f32_e32 v90, v155, v83
	v_fmac_f32_e32 v91, v163, v83
	v_fmac_f32_e32 v89, v148, v88
	v_fmac_f32_e32 v90, v156, v88
	v_fmac_f32_e32 v91, v164, v88
	v_fmac_f32_e32 v90, v157, v89
	v_fmac_f32_e32 v91, v165, v89
	v_fmac_f32_e32 v91, v166, v90
	ds_read_b128 v[124:127], v170 offset:7200
	ds_read_b128 v[128:131], v170 offset:7232
	ds_read_b128 v[132:135], v170 offset:7264
	ds_read_b128 v[136:139], v170 offset:7296
	ds_read_b128 v[144:147], v170 offset:7328
	ds_read_b128 v[148:151], v170 offset:7344
	ds_read_b128 v[152:155], v170 offset:7360
	ds_read_b128 v[156:159], v170 offset:7376
	ds_read_b128 v[160:163], v170 offset:7392
	ds_read_b128 v[164:167], v170 offset:7408
	v_cndmask_b32_e32 v220, v80, v81, vcc
	v_cndmask_b32_e64 v220, v220, v82, s[4:5]
	v_cndmask_b32_e64 v220, v220, v83, s[6:7]
	v_cndmask_b32_e32 v221, v88, v89, vcc
	v_cndmask_b32_e64 v221, v221, v90, s[4:5]
	v_cndmask_b32_e64 v221, v221, v91, s[6:7]
	s_nop 1
	v_mfma_f32_16x16x4_f32 v[84:87], v218, v220, v[36:39]
	v_mfma_f32_16x16x4_f32 v[84:87], v219, v221, v[84:87]
	ds_read_b32 v218, v172 offset:7168
	ds_read_b32 v219, v172 offset:7184
	v_mfma_f32_16x16x4_f32 v[224:227], v182, v220, v[224:227]
	v_mfma_f32_16x16x4_f32 v[224:227], v186, v221, v[224:227]
	v_mfma_f32_16x16x4_f32 v[228:231], v183, v220, v[228:231]
	v_mfma_f32_16x16x4_f32 v[228:231], v187, v221, v[228:231]
	v_mfma_f32_16x16x4_f32 v[232:235], v184, v220, v[232:235]
	v_mfma_f32_16x16x4_f32 v[232:235], v188, v221, v[232:235]
	v_mfma_f32_16x16x4_f32 v[236:239], v185, v220, v[236:239]
	v_mfma_f32_16x16x4_f32 v[236:239], v189, v221, v[236:239]
	v_add_u32_e32 v173, 0x880, v173
	v_add_u32_e32 v2, 0x880, v2
	v_add_u32_e32 v3, 0x880, v3
	v_add_u32_e32 v5, 0x880, v5
	ds_read2_b32 v[182:183], v173 offset0:0 offset1:16
	ds_read2_b32 v[184:185], v173 offset0:32 offset1:48
	ds_read2_b32 v[186:187], v2 offset0:0 offset1:16
	ds_read2_b32 v[188:189], v2 offset0:32 offset1:48
	ds_read2_b32 v[190:191], v3 offset0:0 offset1:16
	ds_read2_b32 v[192:193], v3 offset0:32 offset1:48
	ds_read2_b32 v[194:195], v5 offset0:0 offset1:16
	ds_read2_b32 v[196:197], v5 offset0:32 offset1:48
	s_mov_b64 exec, s[8:9]
	ds_write_b32 v175, v84 offset:12288
	ds_write_b32 v175, v85 offset:12544
	ds_write_b32 v175, v86 offset:12800
	ds_write_b32 v175, v87 offset:13056
	s_mov_b64 exec, s[14:15]
	ds_add_u32 v179, v241 offset:24
	s_mov_b64 exec, -1
	s_waitcnt lgkmcnt(4)
	v_pk_mul_f32 v[224:225], v[224:225], v[198:199]
	v_pk_mul_f32 v[226:227], v[226:227], v[200:201]
	v_pk_mul_f32 v[228:229], v[228:229], v[202:203]
	v_pk_mul_f32 v[230:231], v[230:231], v[204:205]
	v_mfma_f32_16x16x4_f32 v[36:39], v44, v224, 0
	v_mfma_f32_16x16x4_f32 v[40:43], v45, v225, 0
	v_mfma_f32_16x16x4_f32 v[36:39], v46, v226, v[36:39]
	v_mfma_f32_16x16x4_f32 v[40:43], v47, v227, v[40:43]
	v_pk_mul_f32 v[232:233], v[232:233], v[206:207]
	v_pk_mul_f32 v[234:235], v[234:235], v[208:209]
	v_mfma_f32_16x16x4_f32 v[36:39], v48, v228, v[36:39]
	v_mfma_f32_16x16x4_f32 v[40:43], v49, v229, v[40:43]
	v_mfma_f32_16x16x4_f32 v[36:39], v50, v230, v[36:39]
	v_mfma_f32_16x16x4_f32 v[40:43], v51, v231, v[40:43]
	v_pk_mul_f32 v[236:237], v[236:237], v[210:211]
	v_pk_mul_f32 v[238:239], v[238:239], v[212:213]
	v_mfma_f32_16x16x4_f32 v[36:39], v68, v232, v[36:39]
	v_mfma_f32_16x16x4_f32 v[40:43], v69, v233, v[40:43]
	v_mfma_f32_16x16x4_f32 v[36:39], v70, v234, v[36:39]
	v_mfma_f32_16x16x4_f32 v[40:43], v71, v235, v[40:43]
	v_mfma_f32_16x16x4_f32 v[36:39], v96, v236, v[36:39]
	v_mfma_f32_16x16x4_f32 v[40:43], v97, v237, v[40:43]
	v_mfma_f32_16x16x4_f32 v[36:39], v98, v238, v[36:39]
	v_mfma_f32_16x16x4_f32 v[40:43], v99, v239, v[40:43]
	v_mfma_f32_16x16x4_f32 v[36:39], v216, v214, v[36:39]
	v_mfma_f32_16x16x4_f32 v[40:43], v217, v215, v[40:43]
	ds_read_b128 v[44:47], v168 offset:17408
	ds_read_b128 v[48:51], v168 offset:17472
	ds_read_b128 v[68:71], v168 offset:17536
	ds_read_b128 v[96:99], v168 offset:17600
	ds_read_b32 v216, v171 offset:8192
	ds_read_b32 v217, v171 offset:8208
	ds_read_b128 v[198:201], v174 offset:1792
	ds_read_b128 v[202:205], v174 offset:1856
	ds_read_b128 v[206:209], v174 offset:1920
	ds_read_b128 v[210:213], v174 offset:1984
	v_mfma_f32_16x16x4_f32 v[224:227], v190, v214, v[224:227]
	v_mfma_f32_16x16x4_f32 v[224:227], v194, v215, v[224:227]
	v_mfma_f32_16x16x4_f32 v[228:231], v191, v214, v[228:231]
	v_mfma_f32_16x16x4_f32 v[228:231], v195, v215, v[228:231]
	v_mfma_f32_16x16x4_f32 v[232:235], v192, v214, v[232:235]
	v_mfma_f32_16x16x4_f32 v[232:235], v196, v215, v[232:235]
	v_mfma_f32_16x16x4_f32 v[236:239], v193, v214, v[236:239]
	v_mfma_f32_16x16x4_f32 v[236:239], v197, v215, v[236:239]
	ds_read_b32 v214, v169 offset:16384
	ds_read_b32 v215, v169 offset:17408
	v_pk_add_f32 v[80:81], v[36:37], v[40:41]
	v_pk_add_f32 v[82:83], v[38:39], v[42:43]
	v_pk_add_f32 v[84:85], v[36:37], v[40:41]
	v_pk_add_f32 v[86:87], v[38:39], v[42:43]
	v_pk_add_f32 v[36:37], v[36:37], v[40:41]
	v_pk_add_f32 v[38:39], v[38:39], v[42:43]
	v_permlane32_swap_b32_e32 v80, v84
	v_permlane32_swap_b32_e32 v81, v85
	v_permlane32_swap_b32_e32 v82, v86
	v_permlane32_swap_b32_e32 v83, v87
	v_mov_b32_e32 v88, v80
	v_mov_b32_e32 v89, v81
	v_mov_b32_e32 v90, v82
	v_mov_b32_e32 v91, v83
	s_nop 0
	v_permlane16_swap_b32_e32 v80, v88
	v_permlane16_swap_b32_e32 v81, v89
	v_permlane16_swap_b32_e32 v82, v90
	v_permlane16_swap_b32_e32 v83, v91
	v_fmac_f32_e32 v81, v124, v80
	v_fmac_f32_e32 v82, v128, v80
	v_fmac_f32_e32 v83, v132, v80
	v_fmac_f32_e32 v88, v136, v80
	v_fmac_f32_e32 v89, v144, v80
	v_fmac_f32_e32 v90, v152, v80
	v_fmac_f32_e32 v91, v160, v80
	v_fmac_f32_e32 v82, v129, v81
	v_fmac_f32_e32 v83, v133, v81
	v_fmac_f32_e32 v88, v137, v81
	v_fmac_f32_e32 v89, v145, v81
	v_fmac_f32_e32 v90, v153, v81
	v_fmac_f32_e32 v91, v161, v81
	v_fmac_f32_e32 v83, v134, v82
	v_fmac_f32_e32 v88, v138, v82
	v_fmac_f32_e32 v89, v146, v82
	v_fmac_f32_e32 v90, v154, v82
	v_fmac_f32_e32 v91, v162, v82
	v_fmac_f32_e32 v88, v139, v83
	v_fmac_f32_e32 v89, v147, v83
	v_fmac_f32_e32 v90, v155, v83
	v_fmac_f32_e32 v91, v163, v83
	v_fmac_f32_e32 v89, v148, v88
	v_fmac_f32_e32 v90, v156, v88
	v_fmac_f32_e32 v91, v164, v88
	v_fmac_f32_e32 v90, v157, v89
	v_fmac_f32_e32 v91, v165, v89
	v_fmac_f32_e32 v91, v166, v90
	ds_read_b128 v[124:127], v170 offset:8224
	ds_read_b128 v[128:131], v170 offset:8256
	ds_read_b128 v[132:135], v170 offset:8288
	ds_read_b128 v[136:139], v170 offset:8320
	ds_read_b128 v[144:147], v170 offset:8352
	ds_read_b128 v[148:151], v170 offset:8368
	ds_read_b128 v[152:155], v170 offset:8384
	ds_read_b128 v[156:159], v170 offset:8400
	ds_read_b128 v[160:163], v170 offset:8416
	ds_read_b128 v[164:167], v170 offset:8432
	v_cndmask_b32_e32 v220, v80, v81, vcc
	v_cndmask_b32_e64 v220, v220, v82, s[4:5]
	v_cndmask_b32_e64 v220, v220, v83, s[6:7]
	v_cndmask_b32_e32 v221, v88, v89, vcc
	v_cndmask_b32_e64 v221, v221, v90, s[4:5]
	v_cndmask_b32_e64 v221, v221, v91, s[6:7]
	s_nop 1
	v_mfma_f32_16x16x4_f32 v[84:87], v218, v220, v[36:39]
	v_mfma_f32_16x16x4_f32 v[84:87], v219, v221, v[84:87]
	ds_read_b32 v218, v172 offset:8192
	ds_read_b32 v219, v172 offset:8208
	v_mfma_f32_16x16x4_f32 v[224:227], v182, v220, v[224:227]
	v_mfma_f32_16x16x4_f32 v[224:227], v186, v221, v[224:227]
	v_mfma_f32_16x16x4_f32 v[228:231], v183, v220, v[228:231]
	v_mfma_f32_16x16x4_f32 v[228:231], v187, v221, v[228:231]
	v_mfma_f32_16x16x4_f32 v[232:235], v184, v220, v[232:235]
	v_mfma_f32_16x16x4_f32 v[232:235], v188, v221, v[232:235]
	v_mfma_f32_16x16x4_f32 v[236:239], v185, v220, v[236:239]
	v_mfma_f32_16x16x4_f32 v[236:239], v189, v221, v[236:239]
	v_add_u32_e32 v173, 0x880, v173
	v_add_u32_e32 v2, 0x880, v2
	v_add_u32_e32 v3, 0x880, v3
	v_add_u32_e32 v5, 0x880, v5
	ds_read2_b32 v[182:183], v173 offset0:0 offset1:16
	ds_read2_b32 v[184:185], v173 offset0:32 offset1:48
	ds_read2_b32 v[186:187], v2 offset0:0 offset1:16
	ds_read2_b32 v[188:189], v2 offset0:32 offset1:48
	ds_read2_b32 v[190:191], v3 offset0:0 offset1:16
	ds_read2_b32 v[192:193], v3 offset0:32 offset1:48
	ds_read2_b32 v[194:195], v5 offset0:0 offset1:16
	ds_read2_b32 v[196:197], v5 offset0:32 offset1:48
	s_mov_b64 exec, s[8:9]
	ds_write_b32 v175, v84 offset:14336
	ds_write_b32 v175, v85 offset:14592
	ds_write_b32 v175, v86 offset:14848
	ds_write_b32 v175, v87 offset:15104
	s_mov_b64 exec, s[14:15]
	ds_add_u32 v179, v241 offset:28
	s_mov_b64 exec, -1
	s_waitcnt lgkmcnt(0)
	s_nop 7
	v_pk_mul_f32 v[224:225], v[224:225], v[198:199]
	v_pk_mul_f32 v[226:227], v[226:227], v[200:201]
	v_pk_mul_f32 v[228:229], v[228:229], v[202:203]
	v_pk_mul_f32 v[230:231], v[230:231], v[204:205]
	v_pk_mul_f32 v[232:233], v[232:233], v[206:207]
	v_pk_mul_f32 v[234:235], v[234:235], v[208:209]
	v_pk_mul_f32 v[236:237], v[236:237], v[210:211]
	v_pk_mul_f32 v[238:239], v[238:239], v[212:213]
	s_branch .Lrw_done
.Lrw_epi:
	v_and_b32_e32 v166, 63, v180
	v_lshrrev_b32_e32 v167, 6, v180
	v_subrev_u32_e32 v167, 4, v167
	v_add_u32_e32 v124, s72, v166
	v_lshlrev_b32_e32 v156, 2, v124
	v_lshlrev_b32_e32 v124, 1, v124
	v_lshl_add_u32 v124, v167, 10, v124
	s_add_u32 s0, s80, s17
	s_lshl_b32 s0, s0, 10
	s_add_u32 s10, s50, s0
	s_addc_u32 s11, s51, 0
	s_add_u32 s12, s24, s0
	s_addc_u32 s13, s25, 0
	global_load_ushort v128, v124, s[10:11]
	s_add_u32 s10, s10, 0x1000
	s_addc_u32 s11, s11, 0
	global_load_ushort v129, v124, s[10:11]
	s_add_u32 s10, s10, 0x1000
	s_addc_u32 s11, s11, 0
	global_load_ushort v130, v124, s[10:11]
	s_add_u32 s10, s10, 0x1000
	s_addc_u32 s11, s11, 0
	global_load_ushort v131, v124, s[10:11]
	s_add_u32 s10, s10, 0x1000
	s_addc_u32 s11, s11, 0
	global_load_ushort v132, v124, s[10:11]
	s_add_u32 s10, s10, 0x1000
	s_addc_u32 s11, s11, 0
	global_load_ushort v133, v124, s[10:11]
	s_add_u32 s10, s10, 0x1000
	s_addc_u32 s11, s11, 0
	global_load_ushort v134, v124, s[10:11]
	s_add_u32 s10, s10, 0x1000
	s_addc_u32 s11, s11, 0
	global_load_ushort v135, v124, s[10:11]
	s_add_u32 s10, s10, 0x1000
	s_addc_u32 s11, s11, 0
	global_load_ushort v136, v124, s[10:11]
	s_add_u32 s10, s10, 0x1000
	s_addc_u32 s11, s11, 0
	global_load_ushort v137, v124, s[10:11]
	s_add_u32 s10, s10, 0x1000
	s_addc_u32 s11, s11, 0
	global_load_ushort v138, v124, s[10:11]
	s_add_u32 s10, s10, 0x1000
	s_addc_u32 s11, s11, 0
	global_load_ushort v139, v124, s[10:11]
	s_add_u32 s10, s10, 0x1000
	s_addc_u32 s11, s11, 0
	global_load_ushort v140, v124, s[10:11]
	s_add_u32 s10, s10, 0x1000
	s_addc_u32 s11, s11, 0
	global_load_ushort v141, v124, s[10:11]
	s_add_u32 s10, s10, 0x1000
	s_addc_u32 s11, s11, 0
	global_load_ushort v142, v124, s[10:11]
	s_add_u32 s10, s10, 0x1000
	s_addc_u32 s11, s11, 0
	global_load_ushort v143, v124, s[10:11]
	s_add_u32 s10, s10, 0x1000
	s_addc_u32 s11, s11, 0
	global_load_dword v144, v156, s[58:59]
	global_load_dword v145, v156, s[60:61]
	v_lshl_add_u32 v146, v167, 6, v166
	v_lshlrev_b32_e32 v146, 2, v146
	v_add_u32_e32 v147, s41, v146
	v_add_u32_e32 v146, 0x1f800, v146
	v_lshlrev_b32_e32 v148, 2, v167
	v_add_u32_e32 v148, s16, v148
	v_mov_b32_e32 v125, 0xbc800000
	v_mov_b32_e32 v126, 0x3c800000
	v_mov_b32_e32 v127, 0x3a27c5ac
	v_mov_b32_e32 v149, 0x27f00
	s_lshl_b32 s15, s40, 2
	s_add_u32 s15, s15, 4
.Lrw_poll_0:
	ds_read_b32 v156, v149 offset:0
	s_waitcnt lgkmcnt(0)
	v_readfirstlane_b32 s14, v156
	s_cmp_ge_u32 s14, s15
	s_cbranch_scc1 .Lrw_go_0
	s_sleep 2
	s_branch .Lrw_poll_0
.Lrw_go_0:
	s_waitcnt vmcnt(0)
	ds_read_b32 v150, v146 offset:0
	ds_read_b32 v152, v147 offset:0
	ds_read_b32 v154, v148 offset:0
	ds_read_b32 v151, v146 offset:1024
	ds_read_b32 v153, v147 offset:1024
	ds_read_b32 v155, v148 offset:16
	v_lshlrev_b32_e32 v128, 16, v128
	v_lshlrev_b32_e32 v129, 16, v129
	s_waitcnt lgkmcnt(0)
	v_mov_b32_e32 v156, v150
	v_mov_b32_e32 v157, v151
	s_nop 0
	v_add_f32_dpp v156, v156, v156 quad_perm:[1,0,3,2] row_mask:0xf bank_mask:0xf bound_ctrl:1
	v_add_f32_dpp v157, v157, v157 quad_perm:[1,0,3,2] row_mask:0xf bank_mask:0xf bound_ctrl:1
	s_nop 0
	v_add_f32_dpp v156, v156, v156 quad_perm:[2,3,0,1] row_mask:0xf bank_mask:0xf bound_ctrl:1
	v_add_f32_dpp v157, v157, v157 quad_perm:[2,3,0,1] row_mask:0xf bank_mask:0xf bound_ctrl:1
	s_nop 0
	v_add_f32_dpp v156, v156, v156 row_half_mirror row_mask:0xf bank_mask:0xf bound_ctrl:1
	v_add_f32_dpp v157, v157, v157 row_half_mirror row_mask:0xf bank_mask:0xf bound_ctrl:1
	s_nop 0
	v_add_f32_dpp v156, v156, v156 row_mirror row_mask:0xf bank_mask:0xf bound_ctrl:1
	v_add_f32_dpp v157, v157, v157 row_mirror row_mask:0xf bank_mask:0xf bound_ctrl:1
	s_nop 0
	v_add_f32_dpp v156, v156, v156 row_bcast:15 row_mask:0xa bank_mask:0xf
	v_add_f32_dpp v157, v157, v157 row_bcast:15 row_mask:0xa bank_mask:0xf
	s_nop 0
	v_add_f32_dpp v156, v156, v156 row_bcast:31 row_mask:0xc bank_mask:0xf
	v_add_f32_dpp v157, v157, v157 row_bcast:31 row_mask:0xc bank_mask:0xf
	s_nop 0
	v_readlane_b32 s4, v156, 63
	v_readlane_b32 s5, v157, 63
	s_nop 1
	v_fmac_f32_e32 v150, s4, v125
	v_fmac_f32_e32 v151, s5, v125
	v_mul_f32_e32 v158, v150, v150
	v_mul_f32_e32 v159, v151, v151
	v_mul_f32_e32 v162, 0xbfb8aa3b, v128
	v_exp_f32_e32 v162, v162
	v_mul_f32_e32 v163, 0xbfb8aa3b, v129
	v_exp_f32_e32 v163, v163
	v_add_f32_dpp v158, v158, v158 quad_perm:[1,0,3,2] row_mask:0xf bank_mask:0xf bound_ctrl:1
	v_add_f32_dpp v159, v159, v159 quad_perm:[1,0,3,2] row_mask:0xf bank_mask:0xf bound_ctrl:1
	s_nop 0
	v_add_f32_dpp v158, v158, v158 quad_perm:[2,3,0,1] row_mask:0xf bank_mask:0xf bound_ctrl:1
	v_add_f32_dpp v159, v159, v159 quad_perm:[2,3,0,1] row_mask:0xf bank_mask:0xf bound_ctrl:1
	s_nop 0
	v_add_f32_dpp v158, v158, v158 row_half_mirror row_mask:0xf bank_mask:0xf bound_ctrl:1
	v_add_f32_dpp v159, v159, v159 row_half_mirror row_mask:0xf bank_mask:0xf bound_ctrl:1
	s_nop 0
	v_add_f32_dpp v158, v158, v158 row_mirror row_mask:0xf bank_mask:0xf bound_ctrl:1
	v_add_f32_dpp v159, v159, v159 row_mirror row_mask:0xf bank_mask:0xf bound_ctrl:1
	s_nop 0
	v_add_f32_dpp v158, v158, v158 row_bcast:15 row_mask:0xa bank_mask:0xf
	v_add_f32_dpp v159, v159, v159 row_bcast:15 row_mask:0xa bank_mask:0xf
	s_nop 0
	v_add_f32_dpp v158, v158, v158 row_bcast:31 row_mask:0xc bank_mask:0xf
	v_add_f32_dpp v159, v159, v159 row_bcast:31 row_mask:0xc bank_mask:0xf
	s_nop 0
	v_readlane_b32 s6, v158, 63
	v_readlane_b32 s7, v159, 63
	v_add_f32_e32 v162, 1.0, v162
	v_rcp_f32_e32 v162, v162
	v_add_f32_e32 v163, 1.0, v163
	v_rcp_f32_e32 v163, v163
	v_fma_f32 v160, s6, v126, v127
	v_fma_f32 v161, s7, v126, v127
	v_rsq_f32_e32 v160, v160
	v_rsq_f32_e32 v161, v161
	s_nop 0
	v_mul_f32_e32 v164, v150, v160
	v_fma_f32 v164, v144, v164, v145
	v_fmac_f32_e32 v164, v154, v152
	v_mul_f32_e32 v164, v164, v128
	v_mul_f32_e32 v164, v162, v164
	v_mul_f32_e32 v165, v151, v161
	v_fma_f32 v165, v144, v165, v145
	v_fmac_f32_e32 v165, v155, v153
	v_mul_f32_e32 v165, v165, v129
	v_mul_f32_e32 v165, v163, v165
	v_bfe_u32 v156, v164, 16, 1
	v_add3_u32 v164, v164, v156, s97
	v_bfe_u32 v157, v165, 16, 1
	v_add3_u32 v165, v165, v157, s97
	global_store_short_d16_hi v124, v164, s[12:13]
	s_add_u32 s12, s12, 0x1000
	s_addc_u32 s13, s13, 0
	global_store_short_d16_hi v124, v165, s[12:13]
	s_add_u32 s12, s12, 0x1000
	s_addc_u32 s13, s13, 0
.Lrw_poll_1:
	ds_read_b32 v156, v149 offset:4
	s_waitcnt lgkmcnt(0)
	v_readfirstlane_b32 s14, v156
	s_cmp_ge_u32 s14, s15
	s_cbranch_scc1 .Lrw_go_1
	s_sleep 2
	s_branch .Lrw_poll_1
.Lrw_go_1:
	ds_read_b32 v150, v146 offset:2048
	ds_read_b32 v152, v147 offset:2048
	ds_read_b32 v154, v148 offset:32
	ds_read_b32 v151, v146 offset:3072
	ds_read_b32 v153, v147 offset:3072
	ds_read_b32 v155, v148 offset:48
	v_lshlrev_b32_e32 v130, 16, v130
	v_lshlrev_b32_e32 v131, 16, v131
	s_waitcnt lgkmcnt(0)
	v_mov_b32_e32 v156, v150
	v_mov_b32_e32 v157, v151
	s_nop 0
	v_add_f32_dpp v156, v156, v156 quad_perm:[1,0,3,2] row_mask:0xf bank_mask:0xf bound_ctrl:1
	v_add_f32_dpp v157, v157, v157 quad_perm:[1,0,3,2] row_mask:0xf bank_mask:0xf bound_ctrl:1
	s_nop 0
	v_add_f32_dpp v156, v156, v156 quad_perm:[2,3,0,1] row_mask:0xf bank_mask:0xf bound_ctrl:1
	v_add_f32_dpp v157, v157, v157 quad_perm:[2,3,0,1] row_mask:0xf bank_mask:0xf bound_ctrl:1
	s_nop 0
	v_add_f32_dpp v156, v156, v156 row_half_mirror row_mask:0xf bank_mask:0xf bound_ctrl:1
	v_add_f32_dpp v157, v157, v157 row_half_mirror row_mask:0xf bank_mask:0xf bound_ctrl:1
	s_nop 0
	v_add_f32_dpp v156, v156, v156 row_mirror row_mask:0xf bank_mask:0xf bound_ctrl:1
	v_add_f32_dpp v157, v157, v157 row_mirror row_mask:0xf bank_mask:0xf bound_ctrl:1
	s_nop 0
	v_add_f32_dpp v156, v156, v156 row_bcast:15 row_mask:0xa bank_mask:0xf
	v_add_f32_dpp v157, v157, v157 row_bcast:15 row_mask:0xa bank_mask:0xf
	s_nop 0
	v_add_f32_dpp v156, v156, v156 row_bcast:31 row_mask:0xc bank_mask:0xf
	v_add_f32_dpp v157, v157, v157 row_bcast:31 row_mask:0xc bank_mask:0xf
	s_nop 0
	v_readlane_b32 s4, v156, 63
	v_readlane_b32 s5, v157, 63
	s_nop 1
	v_fmac_f32_e32 v150, s4, v125
	v_fmac_f32_e32 v151, s5, v125
	v_mul_f32_e32 v158, v150, v150
	v_mul_f32_e32 v159, v151, v151
	v_mul_f32_e32 v162, 0xbfb8aa3b, v130
	v_exp_f32_e32 v162, v162
	v_mul_f32_e32 v163, 0xbfb8aa3b, v131
	v_exp_f32_e32 v163, v163
	v_add_f32_dpp v158, v158, v158 quad_perm:[1,0,3,2] row_mask:0xf bank_mask:0xf bound_ctrl:1
	v_add_f32_dpp v159, v159, v159 quad_perm:[1,0,3,2] row_mask:0xf bank_mask:0xf bound_ctrl:1
	s_nop 0
	v_add_f32_dpp v158, v158, v158 quad_perm:[2,3,0,1] row_mask:0xf bank_mask:0xf bound_ctrl:1
	v_add_f32_dpp v159, v159, v159 quad_perm:[2,3,0,1] row_mask:0xf bank_mask:0xf bound_ctrl:1
	s_nop 0
	v_add_f32_dpp v158, v158, v158 row_half_mirror row_mask:0xf bank_mask:0xf bound_ctrl:1
	v_add_f32_dpp v159, v159, v159 row_half_mirror row_mask:0xf bank_mask:0xf bound_ctrl:1
	s_nop 0
	v_add_f32_dpp v158, v158, v158 row_mirror row_mask:0xf bank_mask:0xf bound_ctrl:1
	v_add_f32_dpp v159, v159, v159 row_mirror row_mask:0xf bank_mask:0xf bound_ctrl:1
	s_nop 0
	v_add_f32_dpp v158, v158, v158 row_bcast:15 row_mask:0xa bank_mask:0xf
	v_add_f32_dpp v159, v159, v159 row_bcast:15 row_mask:0xa bank_mask:0xf
	s_nop 0
	v_add_f32_dpp v158, v158, v158 row_bcast:31 row_mask:0xc bank_mask:0xf
	v_add_f32_dpp v159, v159, v159 row_bcast:31 row_mask:0xc bank_mask:0xf
	s_nop 0
	v_readlane_b32 s6, v158, 63
	v_readlane_b32 s7, v159, 63
	v_add_f32_e32 v162, 1.0, v162
	v_rcp_f32_e32 v162, v162
	v_add_f32_e32 v163, 1.0, v163
	v_rcp_f32_e32 v163, v163
	v_fma_f32 v160, s6, v126, v127
	v_fma_f32 v161, s7, v126, v127
	v_rsq_f32_e32 v160, v160
	v_rsq_f32_e32 v161, v161
	s_nop 0
	v_mul_f32_e32 v164, v150, v160
	v_fma_f32 v164, v144, v164, v145
	v_fmac_f32_e32 v164, v154, v152
	v_mul_f32_e32 v164, v164, v130
	v_mul_f32_e32 v164, v162, v164
	v_mul_f32_e32 v165, v151, v161
	v_fma_f32 v165, v144, v165, v145
	v_fmac_f32_e32 v165, v155, v153
	v_mul_f32_e32 v165, v165, v131
	v_mul_f32_e32 v165, v163, v165
	v_bfe_u32 v156, v164, 16, 1
	v_add3_u32 v164, v164, v156, s97
	v_bfe_u32 v157, v165, 16, 1
	v_add3_u32 v165, v165, v157, s97
	global_store_short_d16_hi v124, v164, s[12:13]
	s_add_u32 s12, s12, 0x1000
	s_addc_u32 s13, s13, 0
	global_store_short_d16_hi v124, v165, s[12:13]
	s_add_u32 s12, s12, 0x1000
	s_addc_u32 s13, s13, 0
.Lrw_poll_2:
	ds_read_b32 v156, v149 offset:8
	s_waitcnt lgkmcnt(0)
	v_readfirstlane_b32 s14, v156
	s_cmp_ge_u32 s14, s15
	s_cbranch_scc1 .Lrw_go_2
	s_sleep 2
	s_branch .Lrw_poll_2
.Lrw_go_2:
	ds_read_b32 v150, v146 offset:4096
	ds_read_b32 v152, v147 offset:4096
	ds_read_b32 v154, v148 offset:64
	ds_read_b32 v151, v146 offset:5120
	ds_read_b32 v153, v147 offset:5120
	ds_read_b32 v155, v148 offset:80
	v_lshlrev_b32_e32 v132, 16, v132
	v_lshlrev_b32_e32 v133, 16, v133
	s_waitcnt lgkmcnt(0)
	v_mov_b32_e32 v156, v150
	v_mov_b32_e32 v157, v151
	s_nop 0
	v_add_f32_dpp v156, v156, v156 quad_perm:[1,0,3,2] row_mask:0xf bank_mask:0xf bound_ctrl:1
	v_add_f32_dpp v157, v157, v157 quad_perm:[1,0,3,2] row_mask:0xf bank_mask:0xf bound_ctrl:1
	s_nop 0
	v_add_f32_dpp v156, v156, v156 quad_perm:[2,3,0,1] row_mask:0xf bank_mask:0xf bound_ctrl:1
	v_add_f32_dpp v157, v157, v157 quad_perm:[2,3,0,1] row_mask:0xf bank_mask:0xf bound_ctrl:1
	s_nop 0
	v_add_f32_dpp v156, v156, v156 row_half_mirror row_mask:0xf bank_mask:0xf bound_ctrl:1
	v_add_f32_dpp v157, v157, v157 row_half_mirror row_mask:0xf bank_mask:0xf bound_ctrl:1
	s_nop 0
	v_add_f32_dpp v156, v156, v156 row_mirror row_mask:0xf bank_mask:0xf bound_ctrl:1
	v_add_f32_dpp v157, v157, v157 row_mirror row_mask:0xf bank_mask:0xf bound_ctrl:1
	s_nop 0
	v_add_f32_dpp v156, v156, v156 row_bcast:15 row_mask:0xa bank_mask:0xf
	v_add_f32_dpp v157, v157, v157 row_bcast:15 row_mask:0xa bank_mask:0xf
	s_nop 0
	v_add_f32_dpp v156, v156, v156 row_bcast:31 row_mask:0xc bank_mask:0xf
	v_add_f32_dpp v157, v157, v157 row_bcast:31 row_mask:0xc bank_mask:0xf
	s_nop 0
	v_readlane_b32 s4, v156, 63
	v_readlane_b32 s5, v157, 63
	s_nop 1
	v_fmac_f32_e32 v150, s4, v125
	v_fmac_f32_e32 v151, s5, v125
	v_mul_f32_e32 v158, v150, v150
	v_mul_f32_e32 v159, v151, v151
	v_mul_f32_e32 v162, 0xbfb8aa3b, v132
	v_exp_f32_e32 v162, v162
	v_mul_f32_e32 v163, 0xbfb8aa3b, v133
	v_exp_f32_e32 v163, v163
	v_add_f32_dpp v158, v158, v158 quad_perm:[1,0,3,2] row_mask:0xf bank_mask:0xf bound_ctrl:1
	v_add_f32_dpp v159, v159, v159 quad_perm:[1,0,3,2] row_mask:0xf bank_mask:0xf bound_ctrl:1
	s_nop 0
	v_add_f32_dpp v158, v158, v158 quad_perm:[2,3,0,1] row_mask:0xf bank_mask:0xf bound_ctrl:1
	v_add_f32_dpp v159, v159, v159 quad_perm:[2,3,0,1] row_mask:0xf bank_mask:0xf bound_ctrl:1
	s_nop 0
	v_add_f32_dpp v158, v158, v158 row_half_mirror row_mask:0xf bank_mask:0xf bound_ctrl:1
	v_add_f32_dpp v159, v159, v159 row_half_mirror row_mask:0xf bank_mask:0xf bound_ctrl:1
	s_nop 0
	v_add_f32_dpp v158, v158, v158 row_mirror row_mask:0xf bank_mask:0xf bound_ctrl:1
	v_add_f32_dpp v159, v159, v159 row_mirror row_mask:0xf bank_mask:0xf bound_ctrl:1
	s_nop 0
	v_add_f32_dpp v158, v158, v158 row_bcast:15 row_mask:0xa bank_mask:0xf
	v_add_f32_dpp v159, v159, v159 row_bcast:15 row_mask:0xa bank_mask:0xf
	s_nop 0
	v_add_f32_dpp v158, v158, v158 row_bcast:31 row_mask:0xc bank_mask:0xf
	v_add_f32_dpp v159, v159, v159 row_bcast:31 row_mask:0xc bank_mask:0xf
	s_nop 0
	v_readlane_b32 s6, v158, 63
	v_readlane_b32 s7, v159, 63
	v_add_f32_e32 v162, 1.0, v162
	v_rcp_f32_e32 v162, v162
	v_add_f32_e32 v163, 1.0, v163
	v_rcp_f32_e32 v163, v163
	v_fma_f32 v160, s6, v126, v127
	v_fma_f32 v161, s7, v126, v127
	v_rsq_f32_e32 v160, v160
	v_rsq_f32_e32 v161, v161
	s_nop 0
	v_mul_f32_e32 v164, v150, v160
	v_fma_f32 v164, v144, v164, v145
	v_fmac_f32_e32 v164, v154, v152
	v_mul_f32_e32 v164, v164, v132
	v_mul_f32_e32 v164, v162, v164
	v_mul_f32_e32 v165, v151, v161
	v_fma_f32 v165, v144, v165, v145
	v_fmac_f32_e32 v165, v155, v153
	v_mul_f32_e32 v165, v165, v133
	v_mul_f32_e32 v165, v163, v165
	v_bfe_u32 v156, v164, 16, 1
	v_add3_u32 v164, v164, v156, s97
	v_bfe_u32 v157, v165, 16, 1
	v_add3_u32 v165, v165, v157, s97
	global_store_short_d16_hi v124, v164, s[12:13]
	s_add_u32 s12, s12, 0x1000
	s_addc_u32 s13, s13, 0
	global_store_short_d16_hi v124, v165, s[12:13]
	s_add_u32 s12, s12, 0x1000
	s_addc_u32 s13, s13, 0
.Lrw_poll_3:
	ds_read_b32 v156, v149 offset:12
	s_waitcnt lgkmcnt(0)
	v_readfirstlane_b32 s14, v156
	s_cmp_ge_u32 s14, s15
	s_cbranch_scc1 .Lrw_go_3
	s_sleep 2
	s_branch .Lrw_poll_3
.Lrw_go_3:
	ds_read_b32 v150, v146 offset:6144
	ds_read_b32 v152, v147 offset:6144
	ds_read_b32 v154, v148 offset:96
	ds_read_b32 v151, v146 offset:7168
	ds_read_b32 v153, v147 offset:7168
	ds_read_b32 v155, v148 offset:112
	v_lshlrev_b32_e32 v134, 16, v134
	v_lshlrev_b32_e32 v135, 16, v135
	s_waitcnt lgkmcnt(0)
	v_mov_b32_e32 v156, v150
	v_mov_b32_e32 v157, v151
	s_nop 0
	v_add_f32_dpp v156, v156, v156 quad_perm:[1,0,3,2] row_mask:0xf bank_mask:0xf bound_ctrl:1
	v_add_f32_dpp v157, v157, v157 quad_perm:[1,0,3,2] row_mask:0xf bank_mask:0xf bound_ctrl:1
	s_nop 0
	v_add_f32_dpp v156, v156, v156 quad_perm:[2,3,0,1] row_mask:0xf bank_mask:0xf bound_ctrl:1
	v_add_f32_dpp v157, v157, v157 quad_perm:[2,3,0,1] row_mask:0xf bank_mask:0xf bound_ctrl:1
	s_nop 0
	v_add_f32_dpp v156, v156, v156 row_half_mirror row_mask:0xf bank_mask:0xf bound_ctrl:1
	v_add_f32_dpp v157, v157, v157 row_half_mirror row_mask:0xf bank_mask:0xf bound_ctrl:1
	s_nop 0
	v_add_f32_dpp v156, v156, v156 row_mirror row_mask:0xf bank_mask:0xf bound_ctrl:1
	v_add_f32_dpp v157, v157, v157 row_mirror row_mask:0xf bank_mask:0xf bound_ctrl:1
	s_nop 0
	v_add_f32_dpp v156, v156, v156 row_bcast:15 row_mask:0xa bank_mask:0xf
	v_add_f32_dpp v157, v157, v157 row_bcast:15 row_mask:0xa bank_mask:0xf
	s_nop 0
	v_add_f32_dpp v156, v156, v156 row_bcast:31 row_mask:0xc bank_mask:0xf
	v_add_f32_dpp v157, v157, v157 row_bcast:31 row_mask:0xc bank_mask:0xf
	s_nop 0
	v_readlane_b32 s4, v156, 63
	v_readlane_b32 s5, v157, 63
	s_nop 1
	v_fmac_f32_e32 v150, s4, v125
	v_fmac_f32_e32 v151, s5, v125
	v_mul_f32_e32 v158, v150, v150
	v_mul_f32_e32 v159, v151, v151
	v_mul_f32_e32 v162, 0xbfb8aa3b, v134
	v_exp_f32_e32 v162, v162
	v_mul_f32_e32 v163, 0xbfb8aa3b, v135
	v_exp_f32_e32 v163, v163
	v_add_f32_dpp v158, v158, v158 quad_perm:[1,0,3,2] row_mask:0xf bank_mask:0xf bound_ctrl:1
	v_add_f32_dpp v159, v159, v159 quad_perm:[1,0,3,2] row_mask:0xf bank_mask:0xf bound_ctrl:1
	s_nop 0
	v_add_f32_dpp v158, v158, v158 quad_perm:[2,3,0,1] row_mask:0xf bank_mask:0xf bound_ctrl:1
	v_add_f32_dpp v159, v159, v159 quad_perm:[2,3,0,1] row_mask:0xf bank_mask:0xf bound_ctrl:1
	s_nop 0
	v_add_f32_dpp v158, v158, v158 row_half_mirror row_mask:0xf bank_mask:0xf bound_ctrl:1
	v_add_f32_dpp v159, v159, v159 row_half_mirror row_mask:0xf bank_mask:0xf bound_ctrl:1
	s_nop 0
	v_add_f32_dpp v158, v158, v158 row_mirror row_mask:0xf bank_mask:0xf bound_ctrl:1
	v_add_f32_dpp v159, v159, v159 row_mirror row_mask:0xf bank_mask:0xf bound_ctrl:1
	s_nop 0
	v_add_f32_dpp v158, v158, v158 row_bcast:15 row_mask:0xa bank_mask:0xf
	v_add_f32_dpp v159, v159, v159 row_bcast:15 row_mask:0xa bank_mask:0xf
	s_nop 0
	v_add_f32_dpp v158, v158, v158 row_bcast:31 row_mask:0xc bank_mask:0xf
	v_add_f32_dpp v159, v159, v159 row_bcast:31 row_mask:0xc bank_mask:0xf
	s_nop 0
	v_readlane_b32 s6, v158, 63
	v_readlane_b32 s7, v159, 63
	v_add_f32_e32 v162, 1.0, v162
	v_rcp_f32_e32 v162, v162
	v_add_f32_e32 v163, 1.0, v163
	v_rcp_f32_e32 v163, v163
	v_fma_f32 v160, s6, v126, v127
	v_fma_f32 v161, s7, v126, v127
	v_rsq_f32_e32 v160, v160
	v_rsq_f32_e32 v161, v161
	s_nop 0
	v_mul_f32_e32 v164, v150, v160
	v_fma_f32 v164, v144, v164, v145
	v_fmac_f32_e32 v164, v154, v152
	v_mul_f32_e32 v164, v164, v134
	v_mul_f32_e32 v164, v162, v164
	v_mul_f32_e32 v165, v151, v161
	v_fma_f32 v165, v144, v165, v145
	v_fmac_f32_e32 v165, v155, v153
	v_mul_f32_e32 v165, v165, v135
	v_mul_f32_e32 v165, v163, v165
	v_bfe_u32 v156, v164, 16, 1
	v_add3_u32 v164, v164, v156, s97
	v_bfe_u32 v157, v165, 16, 1
	v_add3_u32 v165, v165, v157, s97
	global_store_short_d16_hi v124, v164, s[12:13]
	s_add_u32 s12, s12, 0x1000
	s_addc_u32 s13, s13, 0
	global_store_short_d16_hi v124, v165, s[12:13]
	s_add_u32 s12, s12, 0x1000
	s_addc_u32 s13, s13, 0
.Lrw_poll_4:
	ds_read_b32 v156, v149 offset:16
	s_waitcnt lgkmcnt(0)
	v_readfirstlane_b32 s14, v156
	s_cmp_ge_u32 s14, s15
	s_cbranch_scc1 .Lrw_go_4
	s_sleep 2
	s_branch .Lrw_poll_4
.Lrw_go_4:
	ds_read_b32 v150, v146 offset:8192
	ds_read_b32 v152, v147 offset:8192
	ds_read_b32 v154, v148 offset:128
	ds_read_b32 v151, v146 offset:9216
	ds_read_b32 v153, v147 offset:9216
	ds_read_b32 v155, v148 offset:144
	v_lshlrev_b32_e32 v136, 16, v136
	v_lshlrev_b32_e32 v137, 16, v137
	s_waitcnt lgkmcnt(0)
	v_mov_b32_e32 v156, v150
	v_mov_b32_e32 v157, v151
	s_nop 0
	v_add_f32_dpp v156, v156, v156 quad_perm:[1,0,3,2] row_mask:0xf bank_mask:0xf bound_ctrl:1
	v_add_f32_dpp v157, v157, v157 quad_perm:[1,0,3,2] row_mask:0xf bank_mask:0xf bound_ctrl:1
	s_nop 0
	v_add_f32_dpp v156, v156, v156 quad_perm:[2,3,0,1] row_mask:0xf bank_mask:0xf bound_ctrl:1
	v_add_f32_dpp v157, v157, v157 quad_perm:[2,3,0,1] row_mask:0xf bank_mask:0xf bound_ctrl:1
	s_nop 0
	v_add_f32_dpp v156, v156, v156 row_half_mirror row_mask:0xf bank_mask:0xf bound_ctrl:1
	v_add_f32_dpp v157, v157, v157 row_half_mirror row_mask:0xf bank_mask:0xf bound_ctrl:1
	s_nop 0
	v_add_f32_dpp v156, v156, v156 row_mirror row_mask:0xf bank_mask:0xf bound_ctrl:1
	v_add_f32_dpp v157, v157, v157 row_mirror row_mask:0xf bank_mask:0xf bound_ctrl:1
	s_nop 0
	v_add_f32_dpp v156, v156, v156 row_bcast:15 row_mask:0xa bank_mask:0xf
	v_add_f32_dpp v157, v157, v157 row_bcast:15 row_mask:0xa bank_mask:0xf
	s_nop 0
	v_add_f32_dpp v156, v156, v156 row_bcast:31 row_mask:0xc bank_mask:0xf
	v_add_f32_dpp v157, v157, v157 row_bcast:31 row_mask:0xc bank_mask:0xf
	s_nop 0
	v_readlane_b32 s4, v156, 63
	v_readlane_b32 s5, v157, 63
	s_nop 1
	v_fmac_f32_e32 v150, s4, v125
	v_fmac_f32_e32 v151, s5, v125
	v_mul_f32_e32 v158, v150, v150
	v_mul_f32_e32 v159, v151, v151
	v_mul_f32_e32 v162, 0xbfb8aa3b, v136
	v_exp_f32_e32 v162, v162
	v_mul_f32_e32 v163, 0xbfb8aa3b, v137
	v_exp_f32_e32 v163, v163
	v_add_f32_dpp v158, v158, v158 quad_perm:[1,0,3,2] row_mask:0xf bank_mask:0xf bound_ctrl:1
	v_add_f32_dpp v159, v159, v159 quad_perm:[1,0,3,2] row_mask:0xf bank_mask:0xf bound_ctrl:1
	s_nop 0
	v_add_f32_dpp v158, v158, v158 quad_perm:[2,3,0,1] row_mask:0xf bank_mask:0xf bound_ctrl:1
	v_add_f32_dpp v159, v159, v159 quad_perm:[2,3,0,1] row_mask:0xf bank_mask:0xf bound_ctrl:1
	s_nop 0
	v_add_f32_dpp v158, v158, v158 row_half_mirror row_mask:0xf bank_mask:0xf bound_ctrl:1
	v_add_f32_dpp v159, v159, v159 row_half_mirror row_mask:0xf bank_mask:0xf bound_ctrl:1
	s_nop 0
	v_add_f32_dpp v158, v158, v158 row_mirror row_mask:0xf bank_mask:0xf bound_ctrl:1
	v_add_f32_dpp v159, v159, v159 row_mirror row_mask:0xf bank_mask:0xf bound_ctrl:1
	s_nop 0
	v_add_f32_dpp v158, v158, v158 row_bcast:15 row_mask:0xa bank_mask:0xf
	v_add_f32_dpp v159, v159, v159 row_bcast:15 row_mask:0xa bank_mask:0xf
	s_nop 0
	v_add_f32_dpp v158, v158, v158 row_bcast:31 row_mask:0xc bank_mask:0xf
	v_add_f32_dpp v159, v159, v159 row_bcast:31 row_mask:0xc bank_mask:0xf
	s_nop 0
	v_readlane_b32 s6, v158, 63
	v_readlane_b32 s7, v159, 63
	v_add_f32_e32 v162, 1.0, v162
	v_rcp_f32_e32 v162, v162
	v_add_f32_e32 v163, 1.0, v163
	v_rcp_f32_e32 v163, v163
	v_fma_f32 v160, s6, v126, v127
	v_fma_f32 v161, s7, v126, v127
	v_rsq_f32_e32 v160, v160
	v_rsq_f32_e32 v161, v161
	s_nop 0
	v_mul_f32_e32 v164, v150, v160
	v_fma_f32 v164, v144, v164, v145
	v_fmac_f32_e32 v164, v154, v152
	v_mul_f32_e32 v164, v164, v136
	v_mul_f32_e32 v164, v162, v164
	v_mul_f32_e32 v165, v151, v161
	v_fma_f32 v165, v144, v165, v145
	v_fmac_f32_e32 v165, v155, v153
	v_mul_f32_e32 v165, v165, v137
	v_mul_f32_e32 v165, v163, v165
	v_bfe_u32 v156, v164, 16, 1
	v_add3_u32 v164, v164, v156, s97
	v_bfe_u32 v157, v165, 16, 1
	v_add3_u32 v165, v165, v157, s97
	global_store_short_d16_hi v124, v164, s[12:13]
	s_add_u32 s12, s12, 0x1000
	s_addc_u32 s13, s13, 0
	global_store_short_d16_hi v124, v165, s[12:13]
	s_add_u32 s12, s12, 0x1000
	s_addc_u32 s13, s13, 0
.Lrw_poll_5:
	ds_read_b32 v156, v149 offset:20
	s_waitcnt lgkmcnt(0)
	v_readfirstlane_b32 s14, v156
	s_cmp_ge_u32 s14, s15
	s_cbranch_scc1 .Lrw_go_5
	s_sleep 2
	s_branch .Lrw_poll_5
.Lrw_go_5:
	ds_read_b32 v150, v146 offset:10240
	ds_read_b32 v152, v147 offset:10240
	ds_read_b32 v154, v148 offset:160
	ds_read_b32 v151, v146 offset:11264
	ds_read_b32 v153, v147 offset:11264
	ds_read_b32 v155, v148 offset:176
	v_lshlrev_b32_e32 v138, 16, v138
	v_lshlrev_b32_e32 v139, 16, v139
	s_waitcnt lgkmcnt(0)
	v_mov_b32_e32 v156, v150
	v_mov_b32_e32 v157, v151
	s_nop 0
	v_add_f32_dpp v156, v156, v156 quad_perm:[1,0,3,2] row_mask:0xf bank_mask:0xf bound_ctrl:1
	v_add_f32_dpp v157, v157, v157 quad_perm:[1,0,3,2] row_mask:0xf bank_mask:0xf bound_ctrl:1
	s_nop 0
	v_add_f32_dpp v156, v156, v156 quad_perm:[2,3,0,1] row_mask:0xf bank_mask:0xf bound_ctrl:1
	v_add_f32_dpp v157, v157, v157 quad_perm:[2,3,0,1] row_mask:0xf bank_mask:0xf bound_ctrl:1
	s_nop 0
	v_add_f32_dpp v156, v156, v156 row_half_mirror row_mask:0xf bank_mask:0xf bound_ctrl:1
	v_add_f32_dpp v157, v157, v157 row_half_mirror row_mask:0xf bank_mask:0xf bound_ctrl:1
	s_nop 0
	v_add_f32_dpp v156, v156, v156 row_mirror row_mask:0xf bank_mask:0xf bound_ctrl:1
	v_add_f32_dpp v157, v157, v157 row_mirror row_mask:0xf bank_mask:0xf bound_ctrl:1
	s_nop 0
	v_add_f32_dpp v156, v156, v156 row_bcast:15 row_mask:0xa bank_mask:0xf
	v_add_f32_dpp v157, v157, v157 row_bcast:15 row_mask:0xa bank_mask:0xf
	s_nop 0
	v_add_f32_dpp v156, v156, v156 row_bcast:31 row_mask:0xc bank_mask:0xf
	v_add_f32_dpp v157, v157, v157 row_bcast:31 row_mask:0xc bank_mask:0xf
	s_nop 0
	v_readlane_b32 s4, v156, 63
	v_readlane_b32 s5, v157, 63
	s_nop 1
	v_fmac_f32_e32 v150, s4, v125
	v_fmac_f32_e32 v151, s5, v125
	v_mul_f32_e32 v158, v150, v150
	v_mul_f32_e32 v159, v151, v151
	v_mul_f32_e32 v162, 0xbfb8aa3b, v138
	v_exp_f32_e32 v162, v162
	v_mul_f32_e32 v163, 0xbfb8aa3b, v139
	v_exp_f32_e32 v163, v163
	v_add_f32_dpp v158, v158, v158 quad_perm:[1,0,3,2] row_mask:0xf bank_mask:0xf bound_ctrl:1
	v_add_f32_dpp v159, v159, v159 quad_perm:[1,0,3,2] row_mask:0xf bank_mask:0xf bound_ctrl:1
	s_nop 0
	v_add_f32_dpp v158, v158, v158 quad_perm:[2,3,0,1] row_mask:0xf bank_mask:0xf bound_ctrl:1
	v_add_f32_dpp v159, v159, v159 quad_perm:[2,3,0,1] row_mask:0xf bank_mask:0xf bound_ctrl:1
	s_nop 0
	v_add_f32_dpp v158, v158, v158 row_half_mirror row_mask:0xf bank_mask:0xf bound_ctrl:1
	v_add_f32_dpp v159, v159, v159 row_half_mirror row_mask:0xf bank_mask:0xf bound_ctrl:1
	s_nop 0
	v_add_f32_dpp v158, v158, v158 row_mirror row_mask:0xf bank_mask:0xf bound_ctrl:1
	v_add_f32_dpp v159, v159, v159 row_mirror row_mask:0xf bank_mask:0xf bound_ctrl:1
	s_nop 0
	v_add_f32_dpp v158, v158, v158 row_bcast:15 row_mask:0xa bank_mask:0xf
	v_add_f32_dpp v159, v159, v159 row_bcast:15 row_mask:0xa bank_mask:0xf
	s_nop 0
	v_add_f32_dpp v158, v158, v158 row_bcast:31 row_mask:0xc bank_mask:0xf
	v_add_f32_dpp v159, v159, v159 row_bcast:31 row_mask:0xc bank_mask:0xf
	s_nop 0
	v_readlane_b32 s6, v158, 63
	v_readlane_b32 s7, v159, 63
	v_add_f32_e32 v162, 1.0, v162
	v_rcp_f32_e32 v162, v162
	v_add_f32_e32 v163, 1.0, v163
	v_rcp_f32_e32 v163, v163
	v_fma_f32 v160, s6, v126, v127
	v_fma_f32 v161, s7, v126, v127
	v_rsq_f32_e32 v160, v160
	v_rsq_f32_e32 v161, v161
	s_nop 0
	v_mul_f32_e32 v164, v150, v160
	v_fma_f32 v164, v144, v164, v145
	v_fmac_f32_e32 v164, v154, v152
	v_mul_f32_e32 v164, v164, v138
	v_mul_f32_e32 v164, v162, v164
	v_mul_f32_e32 v165, v151, v161
	v_fma_f32 v165, v144, v165, v145
	v_fmac_f32_e32 v165, v155, v153
	v_mul_f32_e32 v165, v165, v139
	v_mul_f32_e32 v165, v163, v165
	v_bfe_u32 v156, v164, 16, 1
	v_add3_u32 v164, v164, v156, s97
	v_bfe_u32 v157, v165, 16, 1
	v_add3_u32 v165, v165, v157, s97
	global_store_short_d16_hi v124, v164, s[12:13]
	s_add_u32 s12, s12, 0x1000
	s_addc_u32 s13, s13, 0
	global_store_short_d16_hi v124, v165, s[12:13]
	s_add_u32 s12, s12, 0x1000
	s_addc_u32 s13, s13, 0
.Lrw_poll_6:
	ds_read_b32 v156, v149 offset:24
	s_waitcnt lgkmcnt(0)
	v_readfirstlane_b32 s14, v156
	s_cmp_ge_u32 s14, s15
	s_cbranch_scc1 .Lrw_go_6
	s_sleep 2
	s_branch .Lrw_poll_6
.Lrw_go_6:
	ds_read_b32 v150, v146 offset:12288
	ds_read_b32 v152, v147 offset:12288
	ds_read_b32 v154, v148 offset:192
	ds_read_b32 v151, v146 offset:13312
	ds_read_b32 v153, v147 offset:13312
	ds_read_b32 v155, v148 offset:208
	v_lshlrev_b32_e32 v140, 16, v140
	v_lshlrev_b32_e32 v141, 16, v141
	s_waitcnt lgkmcnt(0)
	v_mov_b32_e32 v156, v150
	v_mov_b32_e32 v157, v151
	s_nop 0
	v_add_f32_dpp v156, v156, v156 quad_perm:[1,0,3,2] row_mask:0xf bank_mask:0xf bound_ctrl:1
	v_add_f32_dpp v157, v157, v157 quad_perm:[1,0,3,2] row_mask:0xf bank_mask:0xf bound_ctrl:1
	s_nop 0
	v_add_f32_dpp v156, v156, v156 quad_perm:[2,3,0,1] row_mask:0xf bank_mask:0xf bound_ctrl:1
	v_add_f32_dpp v157, v157, v157 quad_perm:[2,3,0,1] row_mask:0xf bank_mask:0xf bound_ctrl:1
	s_nop 0
	v_add_f32_dpp v156, v156, v156 row_half_mirror row_mask:0xf bank_mask:0xf bound_ctrl:1
	v_add_f32_dpp v157, v157, v157 row_half_mirror row_mask:0xf bank_mask:0xf bound_ctrl:1
	s_nop 0
	v_add_f32_dpp v156, v156, v156 row_mirror row_mask:0xf bank_mask:0xf bound_ctrl:1
	v_add_f32_dpp v157, v157, v157 row_mirror row_mask:0xf bank_mask:0xf bound_ctrl:1
	s_nop 0
	v_add_f32_dpp v156, v156, v156 row_bcast:15 row_mask:0xa bank_mask:0xf
	v_add_f32_dpp v157, v157, v157 row_bcast:15 row_mask:0xa bank_mask:0xf
	s_nop 0
	v_add_f32_dpp v156, v156, v156 row_bcast:31 row_mask:0xc bank_mask:0xf
	v_add_f32_dpp v157, v157, v157 row_bcast:31 row_mask:0xc bank_mask:0xf
	s_nop 0
	v_readlane_b32 s4, v156, 63
	v_readlane_b32 s5, v157, 63
	s_nop 1
	v_fmac_f32_e32 v150, s4, v125
	v_fmac_f32_e32 v151, s5, v125
	v_mul_f32_e32 v158, v150, v150
	v_mul_f32_e32 v159, v151, v151
	v_mul_f32_e32 v162, 0xbfb8aa3b, v140
	v_exp_f32_e32 v162, v162
	v_mul_f32_e32 v163, 0xbfb8aa3b, v141
	v_exp_f32_e32 v163, v163
	v_add_f32_dpp v158, v158, v158 quad_perm:[1,0,3,2] row_mask:0xf bank_mask:0xf bound_ctrl:1
	v_add_f32_dpp v159, v159, v159 quad_perm:[1,0,3,2] row_mask:0xf bank_mask:0xf bound_ctrl:1
	s_nop 0
	v_add_f32_dpp v158, v158, v158 quad_perm:[2,3,0,1] row_mask:0xf bank_mask:0xf bound_ctrl:1
	v_add_f32_dpp v159, v159, v159 quad_perm:[2,3,0,1] row_mask:0xf bank_mask:0xf bound_ctrl:1
	s_nop 0
	v_add_f32_dpp v158, v158, v158 row_half_mirror row_mask:0xf bank_mask:0xf bound_ctrl:1
	v_add_f32_dpp v159, v159, v159 row_half_mirror row_mask:0xf bank_mask:0xf bound_ctrl:1
	s_nop 0
	v_add_f32_dpp v158, v158, v158 row_mirror row_mask:0xf bank_mask:0xf bound_ctrl:1
	v_add_f32_dpp v159, v159, v159 row_mirror row_mask:0xf bank_mask:0xf bound_ctrl:1
	s_nop 0
	v_add_f32_dpp v158, v158, v158 row_bcast:15 row_mask:0xa bank_mask:0xf
	v_add_f32_dpp v159, v159, v159 row_bcast:15 row_mask:0xa bank_mask:0xf
	s_nop 0
	v_add_f32_dpp v158, v158, v158 row_bcast:31 row_mask:0xc bank_mask:0xf
	v_add_f32_dpp v159, v159, v159 row_bcast:31 row_mask:0xc bank_mask:0xf
	s_nop 0
	v_readlane_b32 s6, v158, 63
	v_readlane_b32 s7, v159, 63
	v_add_f32_e32 v162, 1.0, v162
	v_rcp_f32_e32 v162, v162
	v_add_f32_e32 v163, 1.0, v163
	v_rcp_f32_e32 v163, v163
	v_fma_f32 v160, s6, v126, v127
	v_fma_f32 v161, s7, v126, v127
	v_rsq_f32_e32 v160, v160
	v_rsq_f32_e32 v161, v161
	s_nop 0
	v_mul_f32_e32 v164, v150, v160
	v_fma_f32 v164, v144, v164, v145
	v_fmac_f32_e32 v164, v154, v152
	v_mul_f32_e32 v164, v164, v140
	v_mul_f32_e32 v164, v162, v164
	v_mul_f32_e32 v165, v151, v161
	v_fma_f32 v165, v144, v165, v145
	v_fmac_f32_e32 v165, v155, v153
	v_mul_f32_e32 v165, v165, v141
	v_mul_f32_e32 v165, v163, v165
	v_bfe_u32 v156, v164, 16, 1
	v_add3_u32 v164, v164, v156, s97
	v_bfe_u32 v157, v165, 16, 1
	v_add3_u32 v165, v165, v157, s97
	global_store_short_d16_hi v124, v164, s[12:13]
	s_add_u32 s12, s12, 0x1000
	s_addc_u32 s13, s13, 0
	global_store_short_d16_hi v124, v165, s[12:13]
	s_add_u32 s12, s12, 0x1000
	s_addc_u32 s13, s13, 0
.Lrw_poll_7:
	ds_read_b32 v156, v149 offset:28
	s_waitcnt lgkmcnt(0)
	v_readfirstlane_b32 s14, v156
	s_cmp_ge_u32 s14, s15
	s_cbranch_scc1 .Lrw_go_7
	s_sleep 2
	s_branch .Lrw_poll_7
.Lrw_go_7:
	ds_read_b32 v150, v146 offset:14336
	ds_read_b32 v152, v147 offset:14336
	ds_read_b32 v154, v148 offset:224
	ds_read_b32 v151, v146 offset:15360
	ds_read_b32 v153, v147 offset:15360
	ds_read_b32 v155, v148 offset:240
	v_lshlrev_b32_e32 v142, 16, v142
	v_lshlrev_b32_e32 v143, 16, v143
	s_waitcnt lgkmcnt(0)
	v_mov_b32_e32 v156, v150
	v_mov_b32_e32 v157, v151
	s_nop 0
	v_add_f32_dpp v156, v156, v156 quad_perm:[1,0,3,2] row_mask:0xf bank_mask:0xf bound_ctrl:1
	v_add_f32_dpp v157, v157, v157 quad_perm:[1,0,3,2] row_mask:0xf bank_mask:0xf bound_ctrl:1
	s_nop 0
	v_add_f32_dpp v156, v156, v156 quad_perm:[2,3,0,1] row_mask:0xf bank_mask:0xf bound_ctrl:1
	v_add_f32_dpp v157, v157, v157 quad_perm:[2,3,0,1] row_mask:0xf bank_mask:0xf bound_ctrl:1
	s_nop 0
	v_add_f32_dpp v156, v156, v156 row_half_mirror row_mask:0xf bank_mask:0xf bound_ctrl:1
	v_add_f32_dpp v157, v157, v157 row_half_mirror row_mask:0xf bank_mask:0xf bound_ctrl:1
	s_nop 0
	v_add_f32_dpp v156, v156, v156 row_mirror row_mask:0xf bank_mask:0xf bound_ctrl:1
	v_add_f32_dpp v157, v157, v157 row_mirror row_mask:0xf bank_mask:0xf bound_ctrl:1
	s_nop 0
	v_add_f32_dpp v156, v156, v156 row_bcast:15 row_mask:0xa bank_mask:0xf
	v_add_f32_dpp v157, v157, v157 row_bcast:15 row_mask:0xa bank_mask:0xf
	s_nop 0
	v_add_f32_dpp v156, v156, v156 row_bcast:31 row_mask:0xc bank_mask:0xf
	v_add_f32_dpp v157, v157, v157 row_bcast:31 row_mask:0xc bank_mask:0xf
	s_nop 0
	v_readlane_b32 s4, v156, 63
	v_readlane_b32 s5, v157, 63
	s_nop 1
	v_fmac_f32_e32 v150, s4, v125
	v_fmac_f32_e32 v151, s5, v125
	v_mul_f32_e32 v158, v150, v150
	v_mul_f32_e32 v159, v151, v151
	v_mul_f32_e32 v162, 0xbfb8aa3b, v142
	v_exp_f32_e32 v162, v162
	v_mul_f32_e32 v163, 0xbfb8aa3b, v143
	v_exp_f32_e32 v163, v163
	v_add_f32_dpp v158, v158, v158 quad_perm:[1,0,3,2] row_mask:0xf bank_mask:0xf bound_ctrl:1
	v_add_f32_dpp v159, v159, v159 quad_perm:[1,0,3,2] row_mask:0xf bank_mask:0xf bound_ctrl:1
	s_nop 0
	v_add_f32_dpp v158, v158, v158 quad_perm:[2,3,0,1] row_mask:0xf bank_mask:0xf bound_ctrl:1
	v_add_f32_dpp v159, v159, v159 quad_perm:[2,3,0,1] row_mask:0xf bank_mask:0xf bound_ctrl:1
	s_nop 0
	v_add_f32_dpp v158, v158, v158 row_half_mirror row_mask:0xf bank_mask:0xf bound_ctrl:1
	v_add_f32_dpp v159, v159, v159 row_half_mirror row_mask:0xf bank_mask:0xf bound_ctrl:1
	s_nop 0
	v_add_f32_dpp v158, v158, v158 row_mirror row_mask:0xf bank_mask:0xf bound_ctrl:1
	v_add_f32_dpp v159, v159, v159 row_mirror row_mask:0xf bank_mask:0xf bound_ctrl:1
	s_nop 0
	v_add_f32_dpp v158, v158, v158 row_bcast:15 row_mask:0xa bank_mask:0xf
	v_add_f32_dpp v159, v159, v159 row_bcast:15 row_mask:0xa bank_mask:0xf
	s_nop 0
	v_add_f32_dpp v158, v158, v158 row_bcast:31 row_mask:0xc bank_mask:0xf
	v_add_f32_dpp v159, v159, v159 row_bcast:31 row_mask:0xc bank_mask:0xf
	s_nop 0
	v_readlane_b32 s6, v158, 63
	v_readlane_b32 s7, v159, 63
	v_add_f32_e32 v162, 1.0, v162
	v_rcp_f32_e32 v162, v162
	v_add_f32_e32 v163, 1.0, v163
	v_rcp_f32_e32 v163, v163
	v_fma_f32 v160, s6, v126, v127
	v_fma_f32 v161, s7, v126, v127
	v_rsq_f32_e32 v160, v160
	v_rsq_f32_e32 v161, v161
	s_nop 0
	v_mul_f32_e32 v164, v150, v160
	v_fma_f32 v164, v144, v164, v145
	v_fmac_f32_e32 v164, v154, v152
	v_mul_f32_e32 v164, v164, v142
	v_mul_f32_e32 v164, v162, v164
	v_mul_f32_e32 v165, v151, v161
	v_fma_f32 v165, v144, v165, v145
	v_fmac_f32_e32 v165, v155, v153
	v_mul_f32_e32 v165, v165, v143
	v_mul_f32_e32 v165, v163, v165
	v_bfe_u32 v156, v164, 16, 1
	v_add3_u32 v164, v164, v156, s97
	v_bfe_u32 v157, v165, 16, 1
	v_add3_u32 v165, v165, v157, s97
	global_store_short_d16_hi v124, v164, s[12:13]
	s_add_u32 s12, s12, 0x1000
	s_addc_u32 s13, s13, 0
	global_store_short_d16_hi v124, v165, s[12:13]
	s_add_u32 s12, s12, 0x1000
	s_addc_u32 s13, s13, 0
	s_waitcnt vmcnt(0)
